# v16 + open barrier before the first MFMA in the bf16 K-loops as well (no MFMA issued ahead of the barrier anywhere)
# speedup vs baseline: 1.0018x; 1.0018x over previous
.LBB0_642:
	ds_read_b128 v[148:151], v139
	ds_read_b128 v[152:155], v139 offset:1024
	ds_read_b128 v[156:159], v139 offset:2048
	ds_read_b128 v[160:163], v139 offset:3072
	ds_read_b128 v[164:167], v140
	ds_read_b128 v[168:171], v140 offset:1024
	ds_read_b128 v[172:175], v140 offset:2048
	ds_read_b128 v[176:179], v140 offset:3072
	s_add_i32 s18, s71, 0xffe80080
	s_cmp_eq_u32 s58, s73
	s_cselect_b32 s74, s69, s18
	s_cselect_b32 s76, s70, s72
	s_or_b32 s75, s74, 0x80
	s_add_i32 s18, s71, 0xfff80000
	s_mov_b32 m0, s59
	ds_read_b128 v[180:183], v141
	ds_read_b128 v[184:187], v141 offset:1024
	ds_read_b128 v[188:191], v141 offset:2048
	ds_read_b128 v[192:195], v141 offset:3072
	ds_read_b128 v[196:199], v141 offset:4096
	ds_read_b128 v[200:203], v141 offset:5120
	ds_read_b128 v[204:207], v141 offset:6144
	ds_read_b128 v[208:211], v141 offset:7168
	buffer_load_dwordx4 v137, s[12:15], s18 offen lds
	s_mov_b32 m0, s60
	s_nop 0
	buffer_load_dwordx4 v137, s[12:15], s71 offen lds
	s_waitcnt vmcnt(8) lgkmcnt(0)
	s_setprio 1
	s_barrier
	v_mfma_f32_16x16x32_bf16 v[118:121], v[148:151], v[180:183], v[118:121]
	v_mfma_f32_16x16x32_bf16 v[118:121], v[152:155], v[184:187], v[118:121]
	v_mfma_f32_16x16x32_bf16 v[114:117], v[156:159], v[180:183], v[114:117]
	v_mfma_f32_16x16x32_bf16 v[114:117], v[160:163], v[184:187], v[114:117]
	v_mfma_f32_16x16x32_bf16 v[126:129], v[164:167], v[180:183], v[126:129]
	v_mfma_f32_16x16x32_bf16 v[126:129], v[168:171], v[184:187], v[126:129]
	v_mfma_f32_16x16x32_bf16 v[122:125], v[172:175], v[180:183], v[122:125]
	v_mfma_f32_16x16x32_bf16 v[122:125], v[176:179], v[184:187], v[122:125]
	v_mfma_f32_16x16x32_bf16 v[98:101], v[172:175], v[188:191], v[98:101]
	v_mfma_f32_16x16x32_bf16 v[98:101], v[176:179], v[192:195], v[98:101]
	v_mfma_f32_16x16x32_bf16 v[106:109], v[164:167], v[188:191], v[106:109]
	v_mfma_f32_16x16x32_bf16 v[106:109], v[168:171], v[192:195], v[106:109]
	v_mfma_f32_16x16x32_bf16 v[102:105], v[156:159], v[188:191], v[102:105]
	v_mfma_f32_16x16x32_bf16 v[102:105], v[160:163], v[192:195], v[102:105]
	v_mfma_f32_16x16x32_bf16 v[110:113], v[148:151], v[188:191], v[110:113]
	v_mfma_f32_16x16x32_bf16 v[110:113], v[152:155], v[192:195], v[110:113]
	v_mfma_f32_16x16x32_bf16 v[94:97], v[148:151], v[196:199], v[94:97]
	v_mfma_f32_16x16x32_bf16 v[94:97], v[152:155], v[200:203], v[94:97]
	v_mfma_f32_16x16x32_bf16 v[86:89], v[156:159], v[196:199], v[86:89]
	v_mfma_f32_16x16x32_bf16 v[86:89], v[160:163], v[200:203], v[86:89]
	v_mfma_f32_16x16x32_bf16 v[90:93], v[164:167], v[196:199], v[90:93]
	v_mfma_f32_16x16x32_bf16 v[90:93], v[168:171], v[200:203], v[90:93]
	v_mfma_f32_16x16x32_bf16 v[82:85], v[172:175], v[196:199], v[82:85]
	v_mfma_f32_16x16x32_bf16 v[82:85], v[176:179], v[200:203], v[82:85]
	v_mfma_f32_16x16x32_bf16 v[70:73], v[172:175], v[204:207], v[70:73]
	v_mfma_f32_16x16x32_bf16 v[70:73], v[176:179], v[208:211], v[70:73]
	v_mfma_f32_16x16x32_bf16 v[74:77], v[164:167], v[204:207], v[74:77]
	v_mfma_f32_16x16x32_bf16 v[74:77], v[168:171], v[208:211], v[74:77]
	v_mfma_f32_16x16x32_bf16 v[66:69], v[156:159], v[204:207], v[66:69]
	v_mfma_f32_16x16x32_bf16 v[66:69], v[160:163], v[208:211], v[66:69]
	v_mfma_f32_16x16x32_bf16 v[78:81], v[148:151], v[204:207], v[78:81]
	v_mfma_f32_16x16x32_bf16 v[78:81], v[152:155], v[208:211], v[78:81]
	s_setprio 0
	s_barrier
	s_mov_b32 m0, s30
	s_mov_b32 s18, s14
	s_mov_b32 s19, s15
	ds_read_b128 v[180:183], v141 offset:16384
	ds_read_b128 v[184:187], v141 offset:17408
	ds_read_b128 v[188:191], v141 offset:18432
	ds_read_b128 v[192:195], v141 offset:19456
	ds_read_b128 v[196:199], v141 offset:20480
	ds_read_b128 v[200:203], v141 offset:21504
	ds_read_b128 v[204:207], v141 offset:22528
	ds_read_b128 v[208:211], v141 offset:23552
	buffer_load_dwordx4 v138, s[16:19], s76 offen lds
	s_mov_b32 m0, s31
	s_add_i32 s77, s76, 0x80000
	buffer_load_dwordx4 v138, s[16:19], s77 offen lds
	s_mov_b32 m0, s44
	s_add_i32 s77, s76, 0x100000
	buffer_load_dwordx4 v138, s[16:19], s77 offen lds
	s_mov_b32 m0, s45
	s_add_i32 s77, s76, 0x180000
	buffer_load_dwordx4 v138, s[16:19], s77 offen lds
	s_mov_b32 m0, s27
	s_add_i32 s77, s74, 0x80000
	buffer_load_dwordx4 v137, s[12:15], s74 offen lds
	s_mov_b32 m0, s46
	s_nop 0
	buffer_load_dwordx4 v137, s[12:15], s77 offen lds
	s_waitcnt vmcnt(8) lgkmcnt(0)
	s_setprio 1
	s_barrier
	v_mfma_f32_16x16x32_bf16 v[62:65], v[148:151], v[180:183], v[62:65]
	v_mfma_f32_16x16x32_bf16 v[62:65], v[152:155], v[184:187], v[62:65]
	v_mfma_f32_16x16x32_bf16 v[54:57], v[156:159], v[180:183], v[54:57]
	v_mfma_f32_16x16x32_bf16 v[54:57], v[160:163], v[184:187], v[54:57]
	v_mfma_f32_16x16x32_bf16 v[58:61], v[164:167], v[180:183], v[58:61]
	v_mfma_f32_16x16x32_bf16 v[58:61], v[168:171], v[184:187], v[58:61]
	v_mfma_f32_16x16x32_bf16 v[50:53], v[172:175], v[180:183], v[50:53]
	v_mfma_f32_16x16x32_bf16 v[50:53], v[176:179], v[184:187], v[50:53]
	v_mfma_f32_16x16x32_bf16 v[34:37], v[172:175], v[188:191], v[34:37]
	v_mfma_f32_16x16x32_bf16 v[34:37], v[176:179], v[192:195], v[34:37]
	v_mfma_f32_16x16x32_bf16 v[42:45], v[164:167], v[188:191], v[42:45]
	v_mfma_f32_16x16x32_bf16 v[42:45], v[168:171], v[192:195], v[42:45]
	v_mfma_f32_16x16x32_bf16 v[38:41], v[156:159], v[188:191], v[38:41]
	v_mfma_f32_16x16x32_bf16 v[38:41], v[160:163], v[192:195], v[38:41]
	v_mfma_f32_16x16x32_bf16 v[46:49], v[148:151], v[188:191], v[46:49]
	v_mfma_f32_16x16x32_bf16 v[46:49], v[152:155], v[192:195], v[46:49]
	v_mfma_f32_16x16x32_bf16 v[30:33], v[148:151], v[196:199], v[30:33]
	v_mfma_f32_16x16x32_bf16 v[30:33], v[152:155], v[200:203], v[30:33]
	v_mfma_f32_16x16x32_bf16 v[22:25], v[156:159], v[196:199], v[22:25]
	v_mfma_f32_16x16x32_bf16 v[22:25], v[160:163], v[200:203], v[22:25]
	v_mfma_f32_16x16x32_bf16 v[26:29], v[164:167], v[196:199], v[26:29]
	v_mfma_f32_16x16x32_bf16 v[26:29], v[168:171], v[200:203], v[26:29]
	v_mfma_f32_16x16x32_bf16 v[18:21], v[172:175], v[196:199], v[18:21]
	v_mfma_f32_16x16x32_bf16 v[18:21], v[176:179], v[200:203], v[18:21]
	v_mfma_f32_16x16x32_bf16 v[2:5], v[172:175], v[204:207], v[2:5]
	v_mfma_f32_16x16x32_bf16 v[2:5], v[176:179], v[208:211], v[2:5]
	v_mfma_f32_16x16x32_bf16 v[10:13], v[164:167], v[204:207], v[10:13]
	v_mfma_f32_16x16x32_bf16 v[10:13], v[168:171], v[208:211], v[10:13]
	v_mfma_f32_16x16x32_bf16 v[6:9], v[156:159], v[204:207], v[6:9]
	v_mfma_f32_16x16x32_bf16 v[6:9], v[160:163], v[208:211], v[6:9]
	v_mfma_f32_16x16x32_bf16 v[14:17], v[148:151], v[204:207], v[14:17]
	v_mfma_f32_16x16x32_bf16 v[14:17], v[152:155], v[208:211], v[14:17]
	s_setprio 0
	s_barrier
	ds_read_b128 v[148:151], v142
	ds_read_b128 v[152:155], v142 offset:1024
	ds_read_b128 v[156:159], v142 offset:2048
	ds_read_b128 v[160:163], v142 offset:3072
	ds_read_b128 v[164:167], v143
	ds_read_b128 v[168:171], v143 offset:1024
	ds_read_b128 v[172:175], v143 offset:2048
	ds_read_b128 v[176:179], v143 offset:3072
	s_mov_b32 m0, s47
	s_add_i32 s77, s74, 0x100000
	ds_read_b128 v[180:183], v141 offset:32768
	ds_read_b128 v[184:187], v141 offset:33792
	ds_read_b128 v[188:191], v141 offset:34816
	ds_read_b128 v[192:195], v141 offset:35840
	ds_read_b128 v[196:199], v141 offset:36864
	ds_read_b128 v[200:203], v141 offset:37888
	ds_read_b128 v[204:207], v141 offset:38912
	ds_read_b128 v[208:211], v141 offset:39936
	buffer_load_dwordx4 v137, s[12:15], s77 offen lds
	s_mov_b32 m0, s48
	s_add_i32 s77, s74, 0x180000
	buffer_load_dwordx4 v137, s[12:15], s77 offen lds
	s_waitcnt vmcnt(8) lgkmcnt(0)
	s_setprio 1
	s_barrier
	v_mfma_f32_16x16x32_bf16 v[118:121], v[148:151], v[180:183], v[118:121]
	v_mfma_f32_16x16x32_bf16 v[118:121], v[152:155], v[184:187], v[118:121]
	v_mfma_f32_16x16x32_bf16 v[114:117], v[156:159], v[180:183], v[114:117]
	v_mfma_f32_16x16x32_bf16 v[114:117], v[160:163], v[184:187], v[114:117]
	v_mfma_f32_16x16x32_bf16 v[126:129], v[164:167], v[180:183], v[126:129]
	v_mfma_f32_16x16x32_bf16 v[126:129], v[168:171], v[184:187], v[126:129]
	v_mfma_f32_16x16x32_bf16 v[122:125], v[172:175], v[180:183], v[122:125]
	v_mfma_f32_16x16x32_bf16 v[122:125], v[176:179], v[184:187], v[122:125]
	v_mfma_f32_16x16x32_bf16 v[98:101], v[172:175], v[188:191], v[98:101]
	v_mfma_f32_16x16x32_bf16 v[98:101], v[176:179], v[192:195], v[98:101]
	v_mfma_f32_16x16x32_bf16 v[106:109], v[164:167], v[188:191], v[106:109]
	v_mfma_f32_16x16x32_bf16 v[106:109], v[168:171], v[192:195], v[106:109]
	v_mfma_f32_16x16x32_bf16 v[102:105], v[156:159], v[188:191], v[102:105]
	v_mfma_f32_16x16x32_bf16 v[102:105], v[160:163], v[192:195], v[102:105]
	v_mfma_f32_16x16x32_bf16 v[110:113], v[148:151], v[188:191], v[110:113]
	v_mfma_f32_16x16x32_bf16 v[110:113], v[152:155], v[192:195], v[110:113]
	v_mfma_f32_16x16x32_bf16 v[94:97], v[148:151], v[196:199], v[94:97]
	v_mfma_f32_16x16x32_bf16 v[94:97], v[152:155], v[200:203], v[94:97]
	v_mfma_f32_16x16x32_bf16 v[86:89], v[156:159], v[196:199], v[86:89]
	v_mfma_f32_16x16x32_bf16 v[86:89], v[160:163], v[200:203], v[86:89]
	v_mfma_f32_16x16x32_bf16 v[90:93], v[164:167], v[196:199], v[90:93]
	v_mfma_f32_16x16x32_bf16 v[90:93], v[168:171], v[200:203], v[90:93]
	v_mfma_f32_16x16x32_bf16 v[82:85], v[172:175], v[196:199], v[82:85]
	v_mfma_f32_16x16x32_bf16 v[82:85], v[176:179], v[200:203], v[82:85]
	v_mfma_f32_16x16x32_bf16 v[70:73], v[172:175], v[204:207], v[70:73]
	v_mfma_f32_16x16x32_bf16 v[70:73], v[176:179], v[208:211], v[70:73]
	v_mfma_f32_16x16x32_bf16 v[74:77], v[164:167], v[204:207], v[74:77]
	v_mfma_f32_16x16x32_bf16 v[74:77], v[168:171], v[208:211], v[74:77]
	v_mfma_f32_16x16x32_bf16 v[66:69], v[156:159], v[204:207], v[66:69]
	v_mfma_f32_16x16x32_bf16 v[66:69], v[160:163], v[208:211], v[66:69]
	v_mfma_f32_16x16x32_bf16 v[78:81], v[148:151], v[204:207], v[78:81]
	v_mfma_f32_16x16x32_bf16 v[78:81], v[152:155], v[208:211], v[78:81]
	s_setprio 0
	s_barrier
	s_mov_b32 m0, s50
	s_or_b32 s77, s76, 0x80
	ds_read_b128 v[180:183], v141 offset:49152
	ds_read_b128 v[184:187], v141 offset:50176
	ds_read_b128 v[188:191], v141 offset:51200
	ds_read_b128 v[192:195], v141 offset:52224
	ds_read_b128 v[196:199], v141 offset:53248
	ds_read_b128 v[200:203], v141 offset:54272
	ds_read_b128 v[204:207], v141 offset:55296
	ds_read_b128 v[208:211], v141 offset:56320
	buffer_load_dwordx4 v138, s[16:19], s77 offen lds
	s_add_i32 s77, s76, 0x80080
	s_mov_b32 m0, s51
	s_add_i32 s74, s74, 0x80080
	buffer_load_dwordx4 v138, s[16:19], s77 offen lds
	s_add_i32 s77, s76, 0x100080
	s_mov_b32 m0, s54
	s_add_i32 s76, s76, 0x180080
	buffer_load_dwordx4 v138, s[16:19], s77 offen lds
	s_mov_b32 m0, s55
	s_nop 0
	buffer_load_dwordx4 v138, s[16:19], s76 offen lds
	s_mov_b32 m0, s52
	s_nop 0
	buffer_load_dwordx4 v137, s[12:15], s75 offen lds
	s_mov_b32 m0, s53
	s_nop 0
	buffer_load_dwordx4 v137, s[12:15], s74 offen lds
	s_waitcnt vmcnt(8) lgkmcnt(0)
	s_setprio 1
	s_barrier
	v_mfma_f32_16x16x32_bf16 v[62:65], v[148:151], v[180:183], v[62:65]
	v_mfma_f32_16x16x32_bf16 v[62:65], v[152:155], v[184:187], v[62:65]
	v_mfma_f32_16x16x32_bf16 v[54:57], v[156:159], v[180:183], v[54:57]
	v_mfma_f32_16x16x32_bf16 v[54:57], v[160:163], v[184:187], v[54:57]
	v_mfma_f32_16x16x32_bf16 v[58:61], v[164:167], v[180:183], v[58:61]
	v_mfma_f32_16x16x32_bf16 v[58:61], v[168:171], v[184:187], v[58:61]
	v_mfma_f32_16x16x32_bf16 v[50:53], v[172:175], v[180:183], v[50:53]
	v_mfma_f32_16x16x32_bf16 v[50:53], v[176:179], v[184:187], v[50:53]
	v_mfma_f32_16x16x32_bf16 v[34:37], v[172:175], v[188:191], v[34:37]
	v_mfma_f32_16x16x32_bf16 v[34:37], v[176:179], v[192:195], v[34:37]
	v_mfma_f32_16x16x32_bf16 v[42:45], v[164:167], v[188:191], v[42:45]
	v_mfma_f32_16x16x32_bf16 v[42:45], v[168:171], v[192:195], v[42:45]
	v_mfma_f32_16x16x32_bf16 v[38:41], v[156:159], v[188:191], v[38:41]
	v_mfma_f32_16x16x32_bf16 v[38:41], v[160:163], v[192:195], v[38:41]
	v_mfma_f32_16x16x32_bf16 v[46:49], v[148:151], v[188:191], v[46:49]
	v_mfma_f32_16x16x32_bf16 v[46:49], v[152:155], v[192:195], v[46:49]
	v_mfma_f32_16x16x32_bf16 v[30:33], v[148:151], v[196:199], v[30:33]
	v_mfma_f32_16x16x32_bf16 v[30:33], v[152:155], v[200:203], v[30:33]
	v_mfma_f32_16x16x32_bf16 v[22:25], v[156:159], v[196:199], v[22:25]
	v_mfma_f32_16x16x32_bf16 v[22:25], v[160:163], v[200:203], v[22:25]
	v_mfma_f32_16x16x32_bf16 v[26:29], v[164:167], v[196:199], v[26:29]
	v_mfma_f32_16x16x32_bf16 v[26:29], v[168:171], v[200:203], v[26:29]
	v_mfma_f32_16x16x32_bf16 v[18:21], v[172:175], v[196:199], v[18:21]
	v_mfma_f32_16x16x32_bf16 v[18:21], v[176:179], v[200:203], v[18:21]
	v_mfma_f32_16x16x32_bf16 v[2:5], v[172:175], v[204:207], v[2:5]
	v_mfma_f32_16x16x32_bf16 v[2:5], v[176:179], v[208:211], v[2:5]
	v_mfma_f32_16x16x32_bf16 v[10:13], v[164:167], v[204:207], v[10:13]
	v_mfma_f32_16x16x32_bf16 v[10:13], v[168:171], v[208:211], v[10:13]
	v_mfma_f32_16x16x32_bf16 v[6:9], v[156:159], v[204:207], v[6:9]
	v_mfma_f32_16x16x32_bf16 v[6:9], v[160:163], v[208:211], v[6:9]
	v_mfma_f32_16x16x32_bf16 v[14:17], v[148:151], v[204:207], v[14:17]
	v_mfma_f32_16x16x32_bf16 v[14:17], v[152:155], v[208:211], v[14:17]
	s_setprio 0
	s_barrier
	s_add_i32 s73, s73, 2
	s_addk_i32 s71, 0x100
	s_addk_i32 s72, 0x100
	s_cmp_ge_i32 s73, s3
	s_cbranch_scc0 .LBB0_642
	s_and_b64 vcc, exec, s[42:43]
	s_cbranch_vccz .LBB0_645

.LBB0_799:
	ds_read_b128 v[134:137], v210
	ds_read_b128 v[138:141], v210 offset:1024
	ds_read_b128 v[142:145], v210 offset:2048
	ds_read_b128 v[148:151], v210 offset:3072
	ds_read_b128 v[152:155], v211
	ds_read_b128 v[156:159], v211 offset:1024
	ds_read_b128 v[160:163], v211 offset:2048
	ds_read_b128 v[164:167], v211 offset:3072
	s_add_i32 s18, s77, 0xffbf8080
	s_cmp_eq_u32 s62, s79
	s_cselect_b32 s80, s6, s18
	s_cselect_b32 s82, s7, s78
	s_or_b32 s81, s80, 0x80
	s_add_i32 s18, s77, 0xffea8000
	s_mov_b32 m0, s63
	ds_read_b128 v[168:171], v212
	ds_read_b128 v[172:175], v212 offset:1024
	ds_read_b128 v[176:179], v212 offset:2048
	ds_read_b128 v[180:183], v212 offset:3072
	ds_read_b128 v[184:187], v212 offset:4096
	ds_read_b128 v[188:191], v212 offset:5120
	ds_read_b128 v[192:195], v212 offset:6144
	ds_read_b128 v[196:199], v212 offset:7168
	buffer_load_dwordx4 v208, s[12:15], s18 offen lds
	s_mov_b32 m0, s66
	s_nop 0
	buffer_load_dwordx4 v208, s[12:15], s77 offen lds
	s_waitcnt vmcnt(8) lgkmcnt(0)
	s_setprio 1
	s_barrier
	v_mfma_f32_16x16x32_bf16 v[126:129], v[134:137], v[168:171], v[126:129]
	v_mfma_f32_16x16x32_bf16 v[126:129], v[138:141], v[172:175], v[126:129]
	v_mfma_f32_16x16x32_bf16 v[122:125], v[142:145], v[168:171], v[122:125]
	v_mfma_f32_16x16x32_bf16 v[122:125], v[148:151], v[172:175], v[122:125]
	v_mfma_f32_16x16x32_bf16 v[110:113], v[152:155], v[168:171], v[110:113]
	v_mfma_f32_16x16x32_bf16 v[110:113], v[156:159], v[172:175], v[110:113]
	v_mfma_f32_16x16x32_bf16 v[102:105], v[160:163], v[168:171], v[102:105]
	v_mfma_f32_16x16x32_bf16 v[102:105], v[164:167], v[172:175], v[102:105]
	v_mfma_f32_16x16x32_bf16 v[86:89], v[160:163], v[176:179], v[86:89]
	v_mfma_f32_16x16x32_bf16 v[86:89], v[164:167], v[180:183], v[86:89]
	v_mfma_f32_16x16x32_bf16 v[94:97], v[152:155], v[176:179], v[94:97]
	v_mfma_f32_16x16x32_bf16 v[94:97], v[156:159], v[180:183], v[94:97]
	v_mfma_f32_16x16x32_bf16 v[114:117], v[142:145], v[176:179], v[114:117]
	v_mfma_f32_16x16x32_bf16 v[114:117], v[148:151], v[180:183], v[114:117]
	v_mfma_f32_16x16x32_bf16 v[118:121], v[134:137], v[176:179], v[118:121]
	v_mfma_f32_16x16x32_bf16 v[118:121], v[138:141], v[180:183], v[118:121]
	v_mfma_f32_16x16x32_bf16 v[106:109], v[134:137], v[184:187], v[106:109]
	v_mfma_f32_16x16x32_bf16 v[106:109], v[138:141], v[188:191], v[106:109]
	v_mfma_f32_16x16x32_bf16 v[98:101], v[142:145], v[184:187], v[98:101]
	v_mfma_f32_16x16x32_bf16 v[98:101], v[148:151], v[188:191], v[98:101]
	v_mfma_f32_16x16x32_bf16 v[78:81], v[152:155], v[184:187], v[78:81]
	v_mfma_f32_16x16x32_bf16 v[78:81], v[156:159], v[188:191], v[78:81]
	v_mfma_f32_16x16x32_bf16 v[74:77], v[160:163], v[184:187], v[74:77]
	v_mfma_f32_16x16x32_bf16 v[74:77], v[164:167], v[188:191], v[74:77]
	v_mfma_f32_16x16x32_bf16 v[66:69], v[160:163], v[192:195], v[66:69]
	v_mfma_f32_16x16x32_bf16 v[66:69], v[164:167], v[196:199], v[66:69]
	v_mfma_f32_16x16x32_bf16 v[70:73], v[152:155], v[192:195], v[70:73]
	v_mfma_f32_16x16x32_bf16 v[70:73], v[156:159], v[196:199], v[70:73]
	v_mfma_f32_16x16x32_bf16 v[82:85], v[142:145], v[192:195], v[82:85]
	v_mfma_f32_16x16x32_bf16 v[82:85], v[148:151], v[196:199], v[82:85]
	v_mfma_f32_16x16x32_bf16 v[90:93], v[134:137], v[192:195], v[90:93]
	v_mfma_f32_16x16x32_bf16 v[90:93], v[138:141], v[196:199], v[90:93]
	s_setprio 0
	s_barrier
	s_mov_b32 m0, s25
	s_mov_b32 s18, s14
	s_mov_b32 s19, s15
	ds_read_b128 v[168:171], v212 offset:16384
	ds_read_b128 v[172:175], v212 offset:17408
	ds_read_b128 v[176:179], v212 offset:18432
	ds_read_b128 v[180:183], v212 offset:19456
	ds_read_b128 v[184:187], v212 offset:20480
	ds_read_b128 v[188:191], v212 offset:21504
	ds_read_b128 v[192:195], v212 offset:22528
	ds_read_b128 v[196:199], v212 offset:23552
	buffer_load_dwordx4 v209, s[16:19], s82 offen lds
	s_mov_b32 m0, s27
	s_add_i32 s83, s82, 0x158000
	buffer_load_dwordx4 v209, s[16:19], s83 offen lds
	s_mov_b32 m0, s30
	s_add_i32 s83, s82, 0x2b0000
	buffer_load_dwordx4 v209, s[16:19], s83 offen lds
	s_mov_b32 m0, s31
	s_add_i32 s83, s82, 0x408000
	buffer_load_dwordx4 v209, s[16:19], s83 offen lds
	s_mov_b32 m0, s21
	s_add_i32 s83, s80, 0x158000
	buffer_load_dwordx4 v208, s[12:15], s80 offen lds
	s_mov_b32 m0, s48
	s_nop 0
	buffer_load_dwordx4 v208, s[12:15], s83 offen lds
	s_waitcnt vmcnt(8) lgkmcnt(0)
	s_setprio 1
	s_barrier
	v_mfma_f32_16x16x32_bf16 v[62:65], v[134:137], v[168:171], v[62:65]
	v_mfma_f32_16x16x32_bf16 v[62:65], v[138:141], v[172:175], v[62:65]
	v_mfma_f32_16x16x32_bf16 v[58:61], v[142:145], v[168:171], v[58:61]
	v_mfma_f32_16x16x32_bf16 v[58:61], v[148:151], v[172:175], v[58:61]
	v_mfma_f32_16x16x32_bf16 v[46:49], v[152:155], v[168:171], v[46:49]
	v_mfma_f32_16x16x32_bf16 v[46:49], v[156:159], v[172:175], v[46:49]
	v_mfma_f32_16x16x32_bf16 v[38:41], v[160:163], v[168:171], v[38:41]
	v_mfma_f32_16x16x32_bf16 v[38:41], v[164:167], v[172:175], v[38:41]
	v_mfma_f32_16x16x32_bf16 v[22:25], v[160:163], v[176:179], v[22:25]
	v_mfma_f32_16x16x32_bf16 v[22:25], v[164:167], v[180:183], v[22:25]
	v_mfma_f32_16x16x32_bf16 v[30:33], v[152:155], v[176:179], v[30:33]
	v_mfma_f32_16x16x32_bf16 v[30:33], v[156:159], v[180:183], v[30:33]
	v_mfma_f32_16x16x32_bf16 v[50:53], v[142:145], v[176:179], v[50:53]
	v_mfma_f32_16x16x32_bf16 v[50:53], v[148:151], v[180:183], v[50:53]
	v_mfma_f32_16x16x32_bf16 v[54:57], v[134:137], v[176:179], v[54:57]
	v_mfma_f32_16x16x32_bf16 v[54:57], v[138:141], v[180:183], v[54:57]
	v_mfma_f32_16x16x32_bf16 v[42:45], v[134:137], v[184:187], v[42:45]
	v_mfma_f32_16x16x32_bf16 v[42:45], v[138:141], v[188:191], v[42:45]
	v_mfma_f32_16x16x32_bf16 v[34:37], v[142:145], v[184:187], v[34:37]
	v_mfma_f32_16x16x32_bf16 v[34:37], v[148:151], v[188:191], v[34:37]
	v_mfma_f32_16x16x32_bf16 v[14:17], v[152:155], v[184:187], v[14:17]
	v_mfma_f32_16x16x32_bf16 v[14:17], v[156:159], v[188:191], v[14:17]
	v_mfma_f32_16x16x32_bf16 v[10:13], v[160:163], v[184:187], v[10:13]
	v_mfma_f32_16x16x32_bf16 v[10:13], v[164:167], v[188:191], v[10:13]
	v_mfma_f32_16x16x32_bf16 v[2:5], v[160:163], v[192:195], v[2:5]
	v_mfma_f32_16x16x32_bf16 v[2:5], v[164:167], v[196:199], v[2:5]
	v_mfma_f32_16x16x32_bf16 v[6:9], v[152:155], v[192:195], v[6:9]
	v_mfma_f32_16x16x32_bf16 v[6:9], v[156:159], v[196:199], v[6:9]
	v_mfma_f32_16x16x32_bf16 v[18:21], v[142:145], v[192:195], v[18:21]
	v_mfma_f32_16x16x32_bf16 v[18:21], v[148:151], v[196:199], v[18:21]
	v_mfma_f32_16x16x32_bf16 v[26:29], v[134:137], v[192:195], v[26:29]
	v_mfma_f32_16x16x32_bf16 v[26:29], v[138:141], v[196:199], v[26:29]
	s_setprio 0
	s_barrier
	ds_read_b128 v[134:137], v213
	ds_read_b128 v[138:141], v213 offset:1024
	ds_read_b128 v[142:145], v213 offset:2048
	ds_read_b128 v[148:151], v213 offset:3072
	ds_read_b128 v[152:155], v214
	ds_read_b128 v[156:159], v214 offset:1024
	ds_read_b128 v[160:163], v214 offset:2048
	ds_read_b128 v[164:167], v214 offset:3072
	s_mov_b32 m0, s49
	s_add_i32 s83, s80, 0x2b0000
	ds_read_b128 v[168:171], v212 offset:32768
	ds_read_b128 v[172:175], v212 offset:33792
	ds_read_b128 v[176:179], v212 offset:34816
	ds_read_b128 v[180:183], v212 offset:35840
	ds_read_b128 v[184:187], v212 offset:36864
	ds_read_b128 v[188:191], v212 offset:37888
	ds_read_b128 v[192:195], v212 offset:38912
	ds_read_b128 v[196:199], v212 offset:39936
	buffer_load_dwordx4 v208, s[12:15], s83 offen lds
	s_mov_b32 m0, s50
	s_add_i32 s83, s80, 0x408000
	buffer_load_dwordx4 v208, s[12:15], s83 offen lds
	s_waitcnt vmcnt(8) lgkmcnt(0)
	s_setprio 1
	s_barrier
	v_mfma_f32_16x16x32_bf16 v[126:129], v[134:137], v[168:171], v[126:129]
	v_mfma_f32_16x16x32_bf16 v[126:129], v[138:141], v[172:175], v[126:129]
	v_mfma_f32_16x16x32_bf16 v[122:125], v[142:145], v[168:171], v[122:125]
	v_mfma_f32_16x16x32_bf16 v[122:125], v[148:151], v[172:175], v[122:125]
	v_mfma_f32_16x16x32_bf16 v[110:113], v[152:155], v[168:171], v[110:113]
	v_mfma_f32_16x16x32_bf16 v[110:113], v[156:159], v[172:175], v[110:113]
	v_mfma_f32_16x16x32_bf16 v[102:105], v[160:163], v[168:171], v[102:105]
	v_mfma_f32_16x16x32_bf16 v[102:105], v[164:167], v[172:175], v[102:105]
	v_mfma_f32_16x16x32_bf16 v[86:89], v[160:163], v[176:179], v[86:89]
	v_mfma_f32_16x16x32_bf16 v[86:89], v[164:167], v[180:183], v[86:89]
	v_mfma_f32_16x16x32_bf16 v[94:97], v[152:155], v[176:179], v[94:97]
	v_mfma_f32_16x16x32_bf16 v[94:97], v[156:159], v[180:183], v[94:97]
	v_mfma_f32_16x16x32_bf16 v[114:117], v[142:145], v[176:179], v[114:117]
	v_mfma_f32_16x16x32_bf16 v[114:117], v[148:151], v[180:183], v[114:117]
	v_mfma_f32_16x16x32_bf16 v[118:121], v[134:137], v[176:179], v[118:121]
	v_mfma_f32_16x16x32_bf16 v[118:121], v[138:141], v[180:183], v[118:121]
	v_mfma_f32_16x16x32_bf16 v[106:109], v[134:137], v[184:187], v[106:109]
	v_mfma_f32_16x16x32_bf16 v[106:109], v[138:141], v[188:191], v[106:109]
	v_mfma_f32_16x16x32_bf16 v[98:101], v[142:145], v[184:187], v[98:101]
	v_mfma_f32_16x16x32_bf16 v[98:101], v[148:151], v[188:191], v[98:101]
	v_mfma_f32_16x16x32_bf16 v[78:81], v[152:155], v[184:187], v[78:81]
	v_mfma_f32_16x16x32_bf16 v[78:81], v[156:159], v[188:191], v[78:81]
	v_mfma_f32_16x16x32_bf16 v[74:77], v[160:163], v[184:187], v[74:77]
	v_mfma_f32_16x16x32_bf16 v[74:77], v[164:167], v[188:191], v[74:77]
	v_mfma_f32_16x16x32_bf16 v[66:69], v[160:163], v[192:195], v[66:69]
	v_mfma_f32_16x16x32_bf16 v[66:69], v[164:167], v[196:199], v[66:69]
	v_mfma_f32_16x16x32_bf16 v[70:73], v[152:155], v[192:195], v[70:73]
	v_mfma_f32_16x16x32_bf16 v[70:73], v[156:159], v[196:199], v[70:73]
	v_mfma_f32_16x16x32_bf16 v[82:85], v[142:145], v[192:195], v[82:85]
	v_mfma_f32_16x16x32_bf16 v[82:85], v[148:151], v[196:199], v[82:85]
	v_mfma_f32_16x16x32_bf16 v[90:93], v[134:137], v[192:195], v[90:93]
	v_mfma_f32_16x16x32_bf16 v[90:93], v[138:141], v[196:199], v[90:93]
	s_setprio 0
	s_barrier
	s_mov_b32 m0, s54
	s_or_b32 s83, s82, 0x80
	ds_read_b128 v[168:171], v212 offset:49152
	ds_read_b128 v[172:175], v212 offset:50176
	ds_read_b128 v[176:179], v212 offset:51200
	ds_read_b128 v[180:183], v212 offset:52224
	ds_read_b128 v[184:187], v212 offset:53248
	ds_read_b128 v[188:191], v212 offset:54272
	ds_read_b128 v[192:195], v212 offset:55296
	ds_read_b128 v[196:199], v212 offset:56320
	buffer_load_dwordx4 v209, s[16:19], s83 offen lds
	s_add_i32 s83, s82, 0x158080
	s_mov_b32 m0, s55
	s_add_i32 s80, s80, 0x158080
	buffer_load_dwordx4 v209, s[16:19], s83 offen lds
	s_add_i32 s83, s82, 0x2b0080
	s_mov_b32 m0, s58
	s_add_i32 s82, s82, 0x408080
	buffer_load_dwordx4 v209, s[16:19], s83 offen lds
	s_mov_b32 m0, s59
	s_nop 0
	buffer_load_dwordx4 v209, s[16:19], s82 offen lds
	s_mov_b32 m0, s56
	s_nop 0
	buffer_load_dwordx4 v208, s[12:15], s81 offen lds
	s_mov_b32 m0, s57
	s_nop 0
	buffer_load_dwordx4 v208, s[12:15], s80 offen lds
	s_waitcnt vmcnt(8) lgkmcnt(0)
	s_setprio 1
	s_barrier
	v_mfma_f32_16x16x32_bf16 v[62:65], v[134:137], v[168:171], v[62:65]
	v_mfma_f32_16x16x32_bf16 v[62:65], v[138:141], v[172:175], v[62:65]
	v_mfma_f32_16x16x32_bf16 v[58:61], v[142:145], v[168:171], v[58:61]
	v_mfma_f32_16x16x32_bf16 v[58:61], v[148:151], v[172:175], v[58:61]
	v_mfma_f32_16x16x32_bf16 v[46:49], v[152:155], v[168:171], v[46:49]
	v_mfma_f32_16x16x32_bf16 v[46:49], v[156:159], v[172:175], v[46:49]
	v_mfma_f32_16x16x32_bf16 v[38:41], v[160:163], v[168:171], v[38:41]
	v_mfma_f32_16x16x32_bf16 v[38:41], v[164:167], v[172:175], v[38:41]
	v_mfma_f32_16x16x32_bf16 v[22:25], v[160:163], v[176:179], v[22:25]
	v_mfma_f32_16x16x32_bf16 v[22:25], v[164:167], v[180:183], v[22:25]
	v_mfma_f32_16x16x32_bf16 v[30:33], v[152:155], v[176:179], v[30:33]
	v_mfma_f32_16x16x32_bf16 v[30:33], v[156:159], v[180:183], v[30:33]
	v_mfma_f32_16x16x32_bf16 v[50:53], v[142:145], v[176:179], v[50:53]
	v_mfma_f32_16x16x32_bf16 v[50:53], v[148:151], v[180:183], v[50:53]
	v_mfma_f32_16x16x32_bf16 v[54:57], v[134:137], v[176:179], v[54:57]
	v_mfma_f32_16x16x32_bf16 v[54:57], v[138:141], v[180:183], v[54:57]
	v_mfma_f32_16x16x32_bf16 v[42:45], v[134:137], v[184:187], v[42:45]
	v_mfma_f32_16x16x32_bf16 v[42:45], v[138:141], v[188:191], v[42:45]
	v_mfma_f32_16x16x32_bf16 v[34:37], v[142:145], v[184:187], v[34:37]
	v_mfma_f32_16x16x32_bf16 v[34:37], v[148:151], v[188:191], v[34:37]
	v_mfma_f32_16x16x32_bf16 v[14:17], v[152:155], v[184:187], v[14:17]
	v_mfma_f32_16x16x32_bf16 v[14:17], v[156:159], v[188:191], v[14:17]
	v_mfma_f32_16x16x32_bf16 v[10:13], v[160:163], v[184:187], v[10:13]
	v_mfma_f32_16x16x32_bf16 v[10:13], v[164:167], v[188:191], v[10:13]
	v_mfma_f32_16x16x32_bf16 v[2:5], v[160:163], v[192:195], v[2:5]
	v_mfma_f32_16x16x32_bf16 v[2:5], v[164:167], v[196:199], v[2:5]
	v_mfma_f32_16x16x32_bf16 v[6:9], v[152:155], v[192:195], v[6:9]
	v_mfma_f32_16x16x32_bf16 v[6:9], v[156:159], v[196:199], v[6:9]
	v_mfma_f32_16x16x32_bf16 v[18:21], v[142:145], v[192:195], v[18:21]
	v_mfma_f32_16x16x32_bf16 v[18:21], v[148:151], v[196:199], v[18:21]
	v_mfma_f32_16x16x32_bf16 v[26:29], v[134:137], v[192:195], v[26:29]
	v_mfma_f32_16x16x32_bf16 v[26:29], v[138:141], v[196:199], v[26:29]
	s_setprio 0
	s_barrier
	s_add_i32 s79, s79, 2
	s_addk_i32 s77, 0x100
	s_addk_i32 s78, 0x100
	s_cmp_ge_i32 s79, s3
	s_cbranch_scc0 .LBB0_799
	v_pk_mul_f32 v[184:185], v[128:129], 0.5 op_sel_hi:[1,0]
	v_pk_mul_f32 v[186:187], v[126:127], 0.5 op_sel_hi:[1,0]
	v_pk_mul_f32 v[188:189], v[124:125], 0.5 op_sel_hi:[1,0]
	v_pk_mul_f32 v[190:191], v[122:123], 0.5 op_sel_hi:[1,0]
	v_pk_mul_f32 v[198:199], v[112:113], 0.5 op_sel_hi:[1,0]
	v_pk_mul_f32 v[196:197], v[110:111], 0.5 op_sel_hi:[1,0]
	v_pk_mul_f32 v[194:195], v[104:105], 0.5 op_sel_hi:[1,0]
	v_pk_mul_f32 v[192:193], v[102:103], 0.5 op_sel_hi:[1,0]
	v_pk_mul_f32 v[182:183], v[120:121], 0.5 op_sel_hi:[1,0]
	v_pk_mul_f32 v[180:181], v[118:119], 0.5 op_sel_hi:[1,0]
	v_pk_mul_f32 v[178:179], v[116:117], 0.5 op_sel_hi:[1,0]
	v_pk_mul_f32 v[176:177], v[114:115], 0.5 op_sel_hi:[1,0]
	v_pk_mul_f32 v[172:173], v[96:97], 0.5 op_sel_hi:[1,0]
	v_pk_mul_f32 v[170:171], v[94:95], 0.5 op_sel_hi:[1,0]
	v_pk_mul_f32 v[168:169], v[88:89], 0.5 op_sel_hi:[1,0]
	v_pk_mul_f32 v[166:167], v[86:87], 0.5 op_sel_hi:[1,0]
	v_pk_mul_f32 v[164:165], v[108:109], 0.5 op_sel_hi:[1,0]
	v_pk_mul_f32 v[162:163], v[106:107], 0.5 op_sel_hi:[1,0]
	v_pk_mul_f32 v[160:161], v[100:101], 0.5 op_sel_hi:[1,0]
	v_pk_mul_f32 v[158:159], v[98:99], 0.5 op_sel_hi:[1,0]
	v_pk_mul_f32 v[156:157], v[80:81], 0.5 op_sel_hi:[1,0]
	v_pk_mul_f32 v[154:155], v[78:79], 0.5 op_sel_hi:[1,0]
	v_pk_mul_f32 v[152:153], v[76:77], 0.5 op_sel_hi:[1,0]
	v_pk_mul_f32 v[150:151], v[74:75], 0.5 op_sel_hi:[1,0]
	v_pk_mul_f32 v[144:145], v[92:93], 0.5 op_sel_hi:[1,0]
	v_pk_mul_f32 v[142:143], v[90:91], 0.5 op_sel_hi:[1,0]
	v_pk_mul_f32 v[140:141], v[84:85], 0.5 op_sel_hi:[1,0]
	v_pk_mul_f32 v[138:139], v[82:83], 0.5 op_sel_hi:[1,0]
	v_pk_mul_f32 v[136:137], v[72:73], 0.5 op_sel_hi:[1,0]
	v_pk_mul_f32 v[134:135], v[70:71], 0.5 op_sel_hi:[1,0]
	v_pk_mul_f32 v[128:129], v[68:69], 0.5 op_sel_hi:[1,0]
	v_pk_mul_f32 v[126:127], v[66:67], 0.5 op_sel_hi:[1,0]
	v_pk_mul_f32 v[122:123], v[64:65], 0.5 op_sel_hi:[1,0]
	v_pk_mul_f32 v[120:121], v[62:63], 0.5 op_sel_hi:[1,0]
	v_pk_mul_f32 v[118:119], v[60:61], 0.5 op_sel_hi:[1,0]
	v_pk_mul_f32 v[116:117], v[58:59], 0.5 op_sel_hi:[1,0]
	v_pk_mul_f32 v[112:113], v[48:49], 0.5 op_sel_hi:[1,0]
	v_pk_mul_f32 v[110:111], v[46:47], 0.5 op_sel_hi:[1,0]
	v_pk_mul_f32 v[108:109], v[40:41], 0.5 op_sel_hi:[1,0]
	v_pk_mul_f32 v[106:107], v[38:39], 0.5 op_sel_hi:[1,0]
	v_pk_mul_f32 v[104:105], v[56:57], 0.5 op_sel_hi:[1,0]
	v_pk_mul_f32 v[102:103], v[54:55], 0.5 op_sel_hi:[1,0]
	v_pk_mul_f32 v[100:101], v[52:53], 0.5 op_sel_hi:[1,0]
	v_pk_mul_f32 v[98:99], v[50:51], 0.5 op_sel_hi:[1,0]
	v_pk_mul_f32 v[96:97], v[32:33], 0.5 op_sel_hi:[1,0]
	v_pk_mul_f32 v[94:95], v[30:31], 0.5 op_sel_hi:[1,0]
	v_pk_mul_f32 v[92:93], v[24:25], 0.5 op_sel_hi:[1,0]
	v_pk_mul_f32 v[90:91], v[22:23], 0.5 op_sel_hi:[1,0]
	v_pk_mul_f32 v[88:89], v[44:45], 0.5 op_sel_hi:[1,0]
	v_pk_mul_f32 v[86:87], v[42:43], 0.5 op_sel_hi:[1,0]
	v_pk_mul_f32 v[84:85], v[36:37], 0.5 op_sel_hi:[1,0]
	v_pk_mul_f32 v[82:83], v[34:35], 0.5 op_sel_hi:[1,0]
	v_pk_mul_f32 v[80:81], v[16:17], 0.5 op_sel_hi:[1,0]
	v_pk_mul_f32 v[78:79], v[14:15], 0.5 op_sel_hi:[1,0]
	v_pk_mul_f32 v[76:77], v[12:13], 0.5 op_sel_hi:[1,0]
	v_pk_mul_f32 v[74:75], v[10:11], 0.5 op_sel_hi:[1,0]
	v_pk_mul_f32 v[72:73], v[28:29], 0.5 op_sel_hi:[1,0]
	v_pk_mul_f32 v[70:71], v[26:27], 0.5 op_sel_hi:[1,0]
	v_pk_mul_f32 v[68:69], v[20:21], 0.5 op_sel_hi:[1,0]
	v_pk_mul_f32 v[66:67], v[18:19], 0.5 op_sel_hi:[1,0]
	v_pk_mul_f32 v[64:65], v[8:9], 0.5 op_sel_hi:[1,0]
	v_pk_mul_f32 v[62:63], v[6:7], 0.5 op_sel_hi:[1,0]
	v_pk_mul_f32 v[60:61], v[4:5], 0.5 op_sel_hi:[1,0]
	v_pk_mul_f32 v[58:59], v[2:3], 0.5 op_sel_hi:[1,0]
	s_and_b64 vcc, exec, s[38:39]
	s_cbranch_vccz .LBB0_802

.LBB0_892:
	ds_read_b128 v[130:133], v172
	ds_read_b128 v[134:137], v172 offset:1024
	ds_read_b128 v[148:151], v172 offset:2048
	ds_read_b128 v[152:155], v172 offset:3072
	ds_read_b128 v[156:159], v173
	ds_read_b128 v[160:163], v173 offset:1024
	ds_read_b128 v[164:167], v173 offset:2048
	ds_read_b128 v[180:183], v173 offset:3072
	s_add_i32 s18, s8, 0xffe80080
	s_cmp_eq_u32 s77, s52
	s_cselect_b32 s53, s6, s18
	s_cselect_b32 s58, s7, s9
	s_or_b32 s57, s53, 0x80
	s_add_i32 s18, s8, 0xfff80000
	s_mov_b32 m0, s78
	ds_read_b128 v[184:187], v174
	ds_read_b128 v[188:191], v174 offset:1024
	ds_read_b128 v[192:195], v174 offset:2048
	ds_read_b128 v[196:199], v174 offset:3072
	ds_read_b128 v[200:203], v174 offset:4096
	ds_read_b128 v[204:207], v174 offset:5120
	ds_read_b128 v[208:211], v174 offset:6144
	ds_read_b128 v[212:215], v174 offset:7168
	buffer_load_dwordx4 v170, s[12:15], s18 offen lds
	s_mov_b32 m0, s79
	s_nop 0
	buffer_load_dwordx4 v170, s[12:15], s8 offen lds
	s_waitcnt vmcnt(8) lgkmcnt(0)
	s_setprio 1
	s_barrier
	v_mfma_f32_16x16x32_bf16 v[126:129], v[130:133], v[184:187], v[126:129]
	v_mfma_f32_16x16x32_bf16 v[126:129], v[134:137], v[188:191], v[126:129]
	v_mfma_f32_16x16x32_bf16 v[118:121], v[148:151], v[184:187], v[118:121]
	v_mfma_f32_16x16x32_bf16 v[118:121], v[152:155], v[188:191], v[118:121]
	v_mfma_f32_16x16x32_bf16 v[122:125], v[156:159], v[184:187], v[122:125]
	v_mfma_f32_16x16x32_bf16 v[122:125], v[160:163], v[188:191], v[122:125]
	v_mfma_f32_16x16x32_bf16 v[114:117], v[164:167], v[184:187], v[114:117]
	v_mfma_f32_16x16x32_bf16 v[114:117], v[180:183], v[188:191], v[114:117]
	v_mfma_f32_16x16x32_bf16 v[98:101], v[164:167], v[192:195], v[98:101]
	v_mfma_f32_16x16x32_bf16 v[98:101], v[180:183], v[196:199], v[98:101]
	v_mfma_f32_16x16x32_bf16 v[106:109], v[156:159], v[192:195], v[106:109]
	v_mfma_f32_16x16x32_bf16 v[106:109], v[160:163], v[196:199], v[106:109]
	v_mfma_f32_16x16x32_bf16 v[102:105], v[148:151], v[192:195], v[102:105]
	v_mfma_f32_16x16x32_bf16 v[102:105], v[152:155], v[196:199], v[102:105]
	v_mfma_f32_16x16x32_bf16 v[110:113], v[130:133], v[192:195], v[110:113]
	v_mfma_f32_16x16x32_bf16 v[110:113], v[134:137], v[196:199], v[110:113]
	v_mfma_f32_16x16x32_bf16 v[94:97], v[130:133], v[200:203], v[94:97]
	v_mfma_f32_16x16x32_bf16 v[94:97], v[134:137], v[204:207], v[94:97]
	v_mfma_f32_16x16x32_bf16 v[90:93], v[148:151], v[200:203], v[90:93]
	v_mfma_f32_16x16x32_bf16 v[90:93], v[152:155], v[204:207], v[90:93]
	v_mfma_f32_16x16x32_bf16 v[86:89], v[156:159], v[200:203], v[86:89]
	v_mfma_f32_16x16x32_bf16 v[86:89], v[160:163], v[204:207], v[86:89]
	v_mfma_f32_16x16x32_bf16 v[82:85], v[164:167], v[200:203], v[82:85]
	v_mfma_f32_16x16x32_bf16 v[82:85], v[180:183], v[204:207], v[82:85]
	v_mfma_f32_16x16x32_bf16 v[66:69], v[164:167], v[208:211], v[66:69]
	v_mfma_f32_16x16x32_bf16 v[66:69], v[180:183], v[212:215], v[66:69]
	v_mfma_f32_16x16x32_bf16 v[74:77], v[156:159], v[208:211], v[74:77]
	v_mfma_f32_16x16x32_bf16 v[74:77], v[160:163], v[212:215], v[74:77]
	v_mfma_f32_16x16x32_bf16 v[70:73], v[148:151], v[208:211], v[70:73]
	v_mfma_f32_16x16x32_bf16 v[70:73], v[152:155], v[212:215], v[70:73]
	v_mfma_f32_16x16x32_bf16 v[78:81], v[130:133], v[208:211], v[78:81]
	v_mfma_f32_16x16x32_bf16 v[78:81], v[134:137], v[212:215], v[78:81]
	s_setprio 0
	s_barrier
	s_mov_b32 m0, s27
	s_mov_b32 s18, s14
	s_mov_b32 s19, s15
	ds_read_b128 v[184:187], v174 offset:16384
	ds_read_b128 v[188:191], v174 offset:17408
	ds_read_b128 v[192:195], v174 offset:18432
	ds_read_b128 v[196:199], v174 offset:19456
	ds_read_b128 v[200:203], v174 offset:20480
	ds_read_b128 v[204:207], v174 offset:21504
	ds_read_b128 v[208:211], v174 offset:22528
	ds_read_b128 v[212:215], v174 offset:23552
	buffer_load_dwordx4 v171, s[16:19], s58 offen lds
	s_mov_b32 m0, s60
	s_add_i32 s59, s58, 0x80000
	buffer_load_dwordx4 v171, s[16:19], s59 offen lds
	s_mov_b32 m0, s61
	s_add_i32 s59, s58, 0x100000
	buffer_load_dwordx4 v171, s[16:19], s59 offen lds
	s_mov_b32 m0, s62
	s_add_i32 s59, s58, 0x180000
	buffer_load_dwordx4 v171, s[16:19], s59 offen lds
	s_mov_b32 m0, s25
	s_add_i32 s59, s53, 0x80000
	buffer_load_dwordx4 v170, s[12:15], s53 offen lds
	s_mov_b32 m0, s63
	s_nop 0
	buffer_load_dwordx4 v170, s[12:15], s59 offen lds
	s_waitcnt vmcnt(8) lgkmcnt(0)
	s_setprio 1
	s_barrier
	v_mfma_f32_16x16x32_bf16 v[62:65], v[130:133], v[184:187], v[62:65]
	v_mfma_f32_16x16x32_bf16 v[62:65], v[134:137], v[188:191], v[62:65]
	v_mfma_f32_16x16x32_bf16 v[54:57], v[148:151], v[184:187], v[54:57]
	v_mfma_f32_16x16x32_bf16 v[54:57], v[152:155], v[188:191], v[54:57]
	v_mfma_f32_16x16x32_bf16 v[58:61], v[156:159], v[184:187], v[58:61]
	v_mfma_f32_16x16x32_bf16 v[58:61], v[160:163], v[188:191], v[58:61]
	v_mfma_f32_16x16x32_bf16 v[50:53], v[164:167], v[184:187], v[50:53]
	v_mfma_f32_16x16x32_bf16 v[50:53], v[180:183], v[188:191], v[50:53]
	v_mfma_f32_16x16x32_bf16 v[34:37], v[164:167], v[192:195], v[34:37]
	v_mfma_f32_16x16x32_bf16 v[34:37], v[180:183], v[196:199], v[34:37]
	v_mfma_f32_16x16x32_bf16 v[42:45], v[156:159], v[192:195], v[42:45]
	v_mfma_f32_16x16x32_bf16 v[42:45], v[160:163], v[196:199], v[42:45]
	v_mfma_f32_16x16x32_bf16 v[38:41], v[148:151], v[192:195], v[38:41]
	v_mfma_f32_16x16x32_bf16 v[38:41], v[152:155], v[196:199], v[38:41]
	v_mfma_f32_16x16x32_bf16 v[46:49], v[130:133], v[192:195], v[46:49]
	v_mfma_f32_16x16x32_bf16 v[46:49], v[134:137], v[196:199], v[46:49]
	v_mfma_f32_16x16x32_bf16 v[30:33], v[130:133], v[200:203], v[30:33]
	v_mfma_f32_16x16x32_bf16 v[30:33], v[134:137], v[204:207], v[30:33]
	v_mfma_f32_16x16x32_bf16 v[22:25], v[148:151], v[200:203], v[22:25]
	v_mfma_f32_16x16x32_bf16 v[22:25], v[152:155], v[204:207], v[22:25]
	v_mfma_f32_16x16x32_bf16 v[26:29], v[156:159], v[200:203], v[26:29]
	v_mfma_f32_16x16x32_bf16 v[26:29], v[160:163], v[204:207], v[26:29]
	v_mfma_f32_16x16x32_bf16 v[18:21], v[164:167], v[200:203], v[18:21]
	v_mfma_f32_16x16x32_bf16 v[18:21], v[180:183], v[204:207], v[18:21]
	v_mfma_f32_16x16x32_bf16 v[2:5], v[164:167], v[208:211], v[2:5]
	v_mfma_f32_16x16x32_bf16 v[2:5], v[180:183], v[212:215], v[2:5]
	v_mfma_f32_16x16x32_bf16 v[10:13], v[156:159], v[208:211], v[10:13]
	v_mfma_f32_16x16x32_bf16 v[10:13], v[160:163], v[212:215], v[10:13]
	v_mfma_f32_16x16x32_bf16 v[6:9], v[148:151], v[208:211], v[6:9]
	v_mfma_f32_16x16x32_bf16 v[6:9], v[152:155], v[212:215], v[6:9]
	v_mfma_f32_16x16x32_bf16 v[14:17], v[130:133], v[208:211], v[14:17]
	v_mfma_f32_16x16x32_bf16 v[14:17], v[134:137], v[212:215], v[14:17]
	s_setprio 0
	s_barrier
	ds_read_b128 v[130:133], v175
	ds_read_b128 v[134:137], v175 offset:1024
	ds_read_b128 v[148:151], v175 offset:2048
	ds_read_b128 v[152:155], v175 offset:3072
	ds_read_b128 v[156:159], v176
	ds_read_b128 v[160:163], v176 offset:1024
	ds_read_b128 v[164:167], v176 offset:2048
	ds_read_b128 v[180:183], v176 offset:3072
	s_mov_b32 m0, s64
	s_add_i32 s59, s53, 0x100000
	ds_read_b128 v[184:187], v174 offset:32768
	ds_read_b128 v[188:191], v174 offset:33792
	ds_read_b128 v[192:195], v174 offset:34816
	ds_read_b128 v[196:199], v174 offset:35840
	ds_read_b128 v[200:203], v174 offset:36864
	ds_read_b128 v[204:207], v174 offset:37888
	ds_read_b128 v[208:211], v174 offset:38912
	ds_read_b128 v[212:215], v174 offset:39936
	buffer_load_dwordx4 v170, s[12:15], s59 offen lds
	s_mov_b32 m0, s65
	s_add_i32 s59, s53, 0x180000
	buffer_load_dwordx4 v170, s[12:15], s59 offen lds
	s_waitcnt vmcnt(8) lgkmcnt(0)
	s_setprio 1
	s_barrier
	v_mfma_f32_16x16x32_bf16 v[126:129], v[130:133], v[184:187], v[126:129]
	v_mfma_f32_16x16x32_bf16 v[126:129], v[134:137], v[188:191], v[126:129]
	v_mfma_f32_16x16x32_bf16 v[118:121], v[148:151], v[184:187], v[118:121]
	v_mfma_f32_16x16x32_bf16 v[118:121], v[152:155], v[188:191], v[118:121]
	v_mfma_f32_16x16x32_bf16 v[122:125], v[156:159], v[184:187], v[122:125]
	v_mfma_f32_16x16x32_bf16 v[122:125], v[160:163], v[188:191], v[122:125]
	v_mfma_f32_16x16x32_bf16 v[114:117], v[164:167], v[184:187], v[114:117]
	v_mfma_f32_16x16x32_bf16 v[114:117], v[180:183], v[188:191], v[114:117]
	v_mfma_f32_16x16x32_bf16 v[98:101], v[164:167], v[192:195], v[98:101]
	v_mfma_f32_16x16x32_bf16 v[98:101], v[180:183], v[196:199], v[98:101]
	v_mfma_f32_16x16x32_bf16 v[106:109], v[156:159], v[192:195], v[106:109]
	v_mfma_f32_16x16x32_bf16 v[106:109], v[160:163], v[196:199], v[106:109]
	v_mfma_f32_16x16x32_bf16 v[102:105], v[148:151], v[192:195], v[102:105]
	v_mfma_f32_16x16x32_bf16 v[102:105], v[152:155], v[196:199], v[102:105]
	v_mfma_f32_16x16x32_bf16 v[110:113], v[130:133], v[192:195], v[110:113]
	v_mfma_f32_16x16x32_bf16 v[110:113], v[134:137], v[196:199], v[110:113]
	v_mfma_f32_16x16x32_bf16 v[94:97], v[130:133], v[200:203], v[94:97]
	v_mfma_f32_16x16x32_bf16 v[94:97], v[134:137], v[204:207], v[94:97]
	v_mfma_f32_16x16x32_bf16 v[90:93], v[148:151], v[200:203], v[90:93]
	v_mfma_f32_16x16x32_bf16 v[90:93], v[152:155], v[204:207], v[90:93]
	v_mfma_f32_16x16x32_bf16 v[86:89], v[156:159], v[200:203], v[86:89]
	v_mfma_f32_16x16x32_bf16 v[86:89], v[160:163], v[204:207], v[86:89]
	v_mfma_f32_16x16x32_bf16 v[82:85], v[164:167], v[200:203], v[82:85]
	v_mfma_f32_16x16x32_bf16 v[82:85], v[180:183], v[204:207], v[82:85]
	v_mfma_f32_16x16x32_bf16 v[66:69], v[164:167], v[208:211], v[66:69]
	v_mfma_f32_16x16x32_bf16 v[66:69], v[180:183], v[212:215], v[66:69]
	v_mfma_f32_16x16x32_bf16 v[74:77], v[156:159], v[208:211], v[74:77]
	v_mfma_f32_16x16x32_bf16 v[74:77], v[160:163], v[212:215], v[74:77]
	v_mfma_f32_16x16x32_bf16 v[70:73], v[148:151], v[208:211], v[70:73]
	v_mfma_f32_16x16x32_bf16 v[70:73], v[152:155], v[212:215], v[70:73]
	v_mfma_f32_16x16x32_bf16 v[78:81], v[130:133], v[208:211], v[78:81]
	v_mfma_f32_16x16x32_bf16 v[78:81], v[134:137], v[212:215], v[78:81]
	s_setprio 0
	s_barrier
	s_mov_b32 m0, s70
	s_or_b32 s59, s58, 0x80
	ds_read_b128 v[184:187], v174 offset:49152
	ds_read_b128 v[188:191], v174 offset:50176
	ds_read_b128 v[192:195], v174 offset:51200
	ds_read_b128 v[196:199], v174 offset:52224
	ds_read_b128 v[200:203], v174 offset:53248
	ds_read_b128 v[204:207], v174 offset:54272
	ds_read_b128 v[208:211], v174 offset:55296
	ds_read_b128 v[212:215], v174 offset:56320
	buffer_load_dwordx4 v171, s[16:19], s59 offen lds
	s_add_i32 s59, s58, 0x80080
	s_mov_b32 m0, s71
	s_add_i32 s53, s53, 0x80080
	buffer_load_dwordx4 v171, s[16:19], s59 offen lds
	s_add_i32 s59, s58, 0x100080
	s_mov_b32 m0, s74
	s_add_i32 s58, s58, 0x180080
	buffer_load_dwordx4 v171, s[16:19], s59 offen lds
	s_mov_b32 m0, s75
	s_nop 0
	buffer_load_dwordx4 v171, s[16:19], s58 offen lds
	s_mov_b32 m0, s72
	s_nop 0
	buffer_load_dwordx4 v170, s[12:15], s57 offen lds
	s_mov_b32 m0, s73
	s_nop 0
	buffer_load_dwordx4 v170, s[12:15], s53 offen lds
	s_waitcnt vmcnt(8) lgkmcnt(0)
	s_setprio 1
	s_barrier
	v_mfma_f32_16x16x32_bf16 v[62:65], v[130:133], v[184:187], v[62:65]
	v_mfma_f32_16x16x32_bf16 v[62:65], v[134:137], v[188:191], v[62:65]
	v_mfma_f32_16x16x32_bf16 v[54:57], v[148:151], v[184:187], v[54:57]
	v_mfma_f32_16x16x32_bf16 v[54:57], v[152:155], v[188:191], v[54:57]
	v_mfma_f32_16x16x32_bf16 v[58:61], v[156:159], v[184:187], v[58:61]
	v_mfma_f32_16x16x32_bf16 v[58:61], v[160:163], v[188:191], v[58:61]
	v_mfma_f32_16x16x32_bf16 v[50:53], v[164:167], v[184:187], v[50:53]
	v_mfma_f32_16x16x32_bf16 v[50:53], v[180:183], v[188:191], v[50:53]
	v_mfma_f32_16x16x32_bf16 v[34:37], v[164:167], v[192:195], v[34:37]
	v_mfma_f32_16x16x32_bf16 v[34:37], v[180:183], v[196:199], v[34:37]
	v_mfma_f32_16x16x32_bf16 v[42:45], v[156:159], v[192:195], v[42:45]
	v_mfma_f32_16x16x32_bf16 v[42:45], v[160:163], v[196:199], v[42:45]
	v_mfma_f32_16x16x32_bf16 v[38:41], v[148:151], v[192:195], v[38:41]
	v_mfma_f32_16x16x32_bf16 v[38:41], v[152:155], v[196:199], v[38:41]
	v_mfma_f32_16x16x32_bf16 v[46:49], v[130:133], v[192:195], v[46:49]
	v_mfma_f32_16x16x32_bf16 v[46:49], v[134:137], v[196:199], v[46:49]
	v_mfma_f32_16x16x32_bf16 v[30:33], v[130:133], v[200:203], v[30:33]
	v_mfma_f32_16x16x32_bf16 v[30:33], v[134:137], v[204:207], v[30:33]
	v_mfma_f32_16x16x32_bf16 v[22:25], v[148:151], v[200:203], v[22:25]
	v_mfma_f32_16x16x32_bf16 v[22:25], v[152:155], v[204:207], v[22:25]
	v_mfma_f32_16x16x32_bf16 v[26:29], v[156:159], v[200:203], v[26:29]
	v_mfma_f32_16x16x32_bf16 v[26:29], v[160:163], v[204:207], v[26:29]
	v_mfma_f32_16x16x32_bf16 v[18:21], v[164:167], v[200:203], v[18:21]
	v_mfma_f32_16x16x32_bf16 v[18:21], v[180:183], v[204:207], v[18:21]
	v_mfma_f32_16x16x32_bf16 v[2:5], v[164:167], v[208:211], v[2:5]
	v_mfma_f32_16x16x32_bf16 v[2:5], v[180:183], v[212:215], v[2:5]
	v_mfma_f32_16x16x32_bf16 v[10:13], v[156:159], v[208:211], v[10:13]
	v_mfma_f32_16x16x32_bf16 v[10:13], v[160:163], v[212:215], v[10:13]
	v_mfma_f32_16x16x32_bf16 v[6:9], v[148:151], v[208:211], v[6:9]
	v_mfma_f32_16x16x32_bf16 v[6:9], v[152:155], v[212:215], v[6:9]
	v_mfma_f32_16x16x32_bf16 v[14:17], v[130:133], v[208:211], v[14:17]
	v_mfma_f32_16x16x32_bf16 v[14:17], v[134:137], v[212:215], v[14:17]
	s_setprio 0
	s_barrier
	s_add_i32 s52, s52, 2
	s_addk_i32 s8, 0x100
	s_addk_i32 s9, 0x100
	s_cmp_ge_i32 s52, s21
	s_cbranch_scc0 .LBB0_892
	s_and_b64 vcc, exec, s[48:49]
	s_cbranch_vccz .LBB0_895

.LBB0_1020:
	v_add_u32_e32 v142, 0x10000, v162
	v_add_u32_e32 v150, 0x14000, v162
	ds_read_b128 v[130:133], v142
	ds_read_b128 v[134:137], v142 offset:1024
	ds_read_b128 v[138:141], v142 offset:2048
	ds_read_b128 v[142:145], v142 offset:3072
	ds_read_b128 v[154:157], v150
	ds_read_b128 v[164:167], v150 offset:1024
	ds_read_b128 v[168:171], v150 offset:2048
	ds_read_b128 v[172:175], v150 offset:3072
	s_add_i32 s90, s6, 0x100
	s_add_i32 s7, s88, s6
	s_cmp_eq_u32 s81, s89
	s_cselect_b32 s91, 0, s90
	s_cselect_b32 s93, s87, s7
	s_add_i32 s91, s91, s70
	s_or_b32 s92, s91, 0x80
	s_add_i32 s6, s3, s6
	s_mov_b32 m0, s82
	s_add_i32 s7, s6, 0x20080
	ds_read_b128 v[176:179], v163
	ds_read_b128 v[180:183], v163 offset:1024
	ds_read_b128 v[184:187], v163 offset:2048
	ds_read_b128 v[188:191], v163 offset:3072
	ds_read_b128 v[192:195], v163 offset:4096
	ds_read_b128 v[196:199], v163 offset:5120
	ds_read_b128 v[200:203], v163 offset:6144
	ds_read_b128 v[204:207], v163 offset:7168
	buffer_load_dwordx4 v161, s[12:15], s7 offen lds
	s_mov_b32 m0, s83
	s_add_i32 s6, s6, 0x30080
	buffer_load_dwordx4 v161, s[12:15], s6 offen lds
	s_waitcnt vmcnt(8) lgkmcnt(0)
	s_setprio 1
	s_barrier
	v_mfma_f32_16x16x32_bf16 v[126:129], v[130:133], v[176:179], v[126:129]
	v_mfma_f32_16x16x32_bf16 v[126:129], v[134:137], v[180:183], v[126:129]
	v_mfma_f32_16x16x32_bf16 v[122:125], v[138:141], v[176:179], v[122:125]
	v_mfma_f32_16x16x32_bf16 v[122:125], v[142:145], v[180:183], v[122:125]
	v_mfma_f32_16x16x32_bf16 v[118:121], v[154:157], v[176:179], v[118:121]
	v_mfma_f32_16x16x32_bf16 v[118:121], v[164:167], v[180:183], v[118:121]
	v_mfma_f32_16x16x32_bf16 v[114:117], v[168:171], v[176:179], v[114:117]
	v_mfma_f32_16x16x32_bf16 v[114:117], v[172:175], v[180:183], v[114:117]
	v_mfma_f32_16x16x32_bf16 v[98:101], v[168:171], v[184:187], v[98:101]
	v_mfma_f32_16x16x32_bf16 v[98:101], v[172:175], v[188:191], v[98:101]
	v_mfma_f32_16x16x32_bf16 v[102:105], v[154:157], v[184:187], v[102:105]
	v_mfma_f32_16x16x32_bf16 v[102:105], v[164:167], v[188:191], v[102:105]
	v_mfma_f32_16x16x32_bf16 v[106:109], v[138:141], v[184:187], v[106:109]
	v_mfma_f32_16x16x32_bf16 v[106:109], v[142:145], v[188:191], v[106:109]
	v_mfma_f32_16x16x32_bf16 v[110:113], v[130:133], v[184:187], v[110:113]
	v_mfma_f32_16x16x32_bf16 v[110:113], v[134:137], v[188:191], v[110:113]
	v_mfma_f32_16x16x32_bf16 v[94:97], v[130:133], v[192:195], v[94:97]
	v_mfma_f32_16x16x32_bf16 v[94:97], v[134:137], v[196:199], v[94:97]
	v_mfma_f32_16x16x32_bf16 v[90:93], v[138:141], v[192:195], v[90:93]
	v_mfma_f32_16x16x32_bf16 v[90:93], v[142:145], v[196:199], v[90:93]
	v_mfma_f32_16x16x32_bf16 v[86:89], v[154:157], v[192:195], v[86:89]
	v_mfma_f32_16x16x32_bf16 v[86:89], v[164:167], v[196:199], v[86:89]
	v_mfma_f32_16x16x32_bf16 v[82:85], v[168:171], v[192:195], v[82:85]
	v_mfma_f32_16x16x32_bf16 v[82:85], v[172:175], v[196:199], v[82:85]
	v_mfma_f32_16x16x32_bf16 v[66:69], v[168:171], v[200:203], v[66:69]
	v_mfma_f32_16x16x32_bf16 v[66:69], v[172:175], v[204:207], v[66:69]
	v_mfma_f32_16x16x32_bf16 v[70:73], v[154:157], v[200:203], v[70:73]
	v_mfma_f32_16x16x32_bf16 v[70:73], v[164:167], v[204:207], v[70:73]
	v_mfma_f32_16x16x32_bf16 v[74:77], v[138:141], v[200:203], v[74:77]
	v_mfma_f32_16x16x32_bf16 v[74:77], v[142:145], v[204:207], v[74:77]
	v_mfma_f32_16x16x32_bf16 v[78:81], v[130:133], v[200:203], v[78:81]
	v_mfma_f32_16x16x32_bf16 v[78:81], v[134:137], v[204:207], v[78:81]
	s_setprio 0
	s_barrier
	s_mov_b32 m0, s66
	s_mov_b32 s6, s14
	s_mov_b32 s7, s15
	ds_read_b128 v[176:179], v163 offset:16384
	ds_read_b128 v[180:183], v163 offset:17408
	ds_read_b128 v[184:187], v163 offset:18432
	ds_read_b128 v[188:191], v163 offset:19456
	ds_read_b128 v[192:195], v163 offset:20480
	ds_read_b128 v[196:199], v163 offset:21504
	ds_read_b128 v[200:203], v163 offset:22528
	ds_read_b128 v[204:207], v163 offset:23552
	buffer_load_dwordx4 v160, s[4:7], s93 offen lds
	s_mov_b32 m0, s67
	s_add_i32 s94, s93, 0x10000
	buffer_load_dwordx4 v160, s[4:7], s94 offen lds
	s_mov_b32 m0, s68
	s_add_i32 s94, s93, 0x20000
	buffer_load_dwordx4 v160, s[4:7], s94 offen lds
	s_mov_b32 m0, s69
	s_add_i32 s94, s93, 0x30000
	buffer_load_dwordx4 v160, s[4:7], s94 offen lds
	s_mov_b32 m0, s65
	s_add_i32 s94, s91, 0x10000
	buffer_load_dwordx4 v161, s[12:15], s91 offen lds
	s_mov_b32 m0, s71
	s_nop 0
	buffer_load_dwordx4 v161, s[12:15], s94 offen lds
	s_waitcnt vmcnt(8) lgkmcnt(0)
	s_setprio 1
	s_barrier
	v_mfma_f32_16x16x32_bf16 v[62:65], v[130:133], v[176:179], v[62:65]
	v_mfma_f32_16x16x32_bf16 v[62:65], v[134:137], v[180:183], v[62:65]
	v_mfma_f32_16x16x32_bf16 v[58:61], v[138:141], v[176:179], v[58:61]
	v_mfma_f32_16x16x32_bf16 v[58:61], v[142:145], v[180:183], v[58:61]
	v_mfma_f32_16x16x32_bf16 v[54:57], v[154:157], v[176:179], v[54:57]
	v_mfma_f32_16x16x32_bf16 v[54:57], v[164:167], v[180:183], v[54:57]
	v_mfma_f32_16x16x32_bf16 v[50:53], v[168:171], v[176:179], v[50:53]
	v_mfma_f32_16x16x32_bf16 v[50:53], v[172:175], v[180:183], v[50:53]
	v_mfma_f32_16x16x32_bf16 v[34:37], v[168:171], v[184:187], v[34:37]
	v_mfma_f32_16x16x32_bf16 v[34:37], v[172:175], v[188:191], v[34:37]
	v_mfma_f32_16x16x32_bf16 v[38:41], v[154:157], v[184:187], v[38:41]
	v_mfma_f32_16x16x32_bf16 v[38:41], v[164:167], v[188:191], v[38:41]
	v_mfma_f32_16x16x32_bf16 v[42:45], v[138:141], v[184:187], v[42:45]
	v_mfma_f32_16x16x32_bf16 v[42:45], v[142:145], v[188:191], v[42:45]
	v_mfma_f32_16x16x32_bf16 v[46:49], v[130:133], v[184:187], v[46:49]
	v_mfma_f32_16x16x32_bf16 v[46:49], v[134:137], v[188:191], v[46:49]
	v_mfma_f32_16x16x32_bf16 v[30:33], v[130:133], v[192:195], v[30:33]
	v_mfma_f32_16x16x32_bf16 v[30:33], v[134:137], v[196:199], v[30:33]
	v_mfma_f32_16x16x32_bf16 v[26:29], v[138:141], v[192:195], v[26:29]
	v_mfma_f32_16x16x32_bf16 v[26:29], v[142:145], v[196:199], v[26:29]
	v_mfma_f32_16x16x32_bf16 v[22:25], v[154:157], v[192:195], v[22:25]
	v_mfma_f32_16x16x32_bf16 v[22:25], v[164:167], v[196:199], v[22:25]
	v_mfma_f32_16x16x32_bf16 v[18:21], v[168:171], v[192:195], v[18:21]
	v_mfma_f32_16x16x32_bf16 v[18:21], v[172:175], v[196:199], v[18:21]
	v_mfma_f32_16x16x32_bf16 v[2:5], v[168:171], v[200:203], v[2:5]
	v_mfma_f32_16x16x32_bf16 v[2:5], v[172:175], v[204:207], v[2:5]
	v_mfma_f32_16x16x32_bf16 v[6:9], v[154:157], v[200:203], v[6:9]
	v_mfma_f32_16x16x32_bf16 v[6:9], v[164:167], v[204:207], v[6:9]
	v_mfma_f32_16x16x32_bf16 v[10:13], v[138:141], v[200:203], v[10:13]
	v_mfma_f32_16x16x32_bf16 v[10:13], v[142:145], v[204:207], v[10:13]
	v_mfma_f32_16x16x32_bf16 v[14:17], v[130:133], v[200:203], v[14:17]
	v_mfma_f32_16x16x32_bf16 v[14:17], v[134:137], v[204:207], v[14:17]
	s_setprio 0
	s_barrier
	v_add_u32_e32 v142, 0x18000, v162
	v_add_u32_e32 v150, 0x1c000, v162
	ds_read_b128 v[130:133], v142
	ds_read_b128 v[134:137], v142 offset:1024
	ds_read_b128 v[138:141], v142 offset:2048
	ds_read_b128 v[142:145], v142 offset:3072
	ds_read_b128 v[154:157], v150
	ds_read_b128 v[164:167], v150 offset:1024
	ds_read_b128 v[168:171], v150 offset:2048
	ds_read_b128 v[172:175], v150 offset:3072
	s_mov_b32 m0, s72
	s_add_i32 s94, s91, 0x20000
	ds_read_b128 v[176:179], v163 offset:32768
	ds_read_b128 v[180:183], v163 offset:33792
	ds_read_b128 v[184:187], v163 offset:34816
	ds_read_b128 v[188:191], v163 offset:35840
	ds_read_b128 v[192:195], v163 offset:36864
	ds_read_b128 v[196:199], v163 offset:37888
	ds_read_b128 v[200:203], v163 offset:38912
	ds_read_b128 v[204:207], v163 offset:39936
	buffer_load_dwordx4 v161, s[12:15], s94 offen lds
	s_mov_b32 m0, s73
	s_add_i32 s94, s91, 0x30000
	buffer_load_dwordx4 v161, s[12:15], s94 offen lds
	s_waitcnt vmcnt(8) lgkmcnt(0)
	s_setprio 1
	s_barrier
	v_mfma_f32_16x16x32_bf16 v[126:129], v[130:133], v[176:179], v[126:129]
	v_mfma_f32_16x16x32_bf16 v[126:129], v[134:137], v[180:183], v[126:129]
	v_mfma_f32_16x16x32_bf16 v[122:125], v[138:141], v[176:179], v[122:125]
	v_mfma_f32_16x16x32_bf16 v[122:125], v[142:145], v[180:183], v[122:125]
	v_mfma_f32_16x16x32_bf16 v[118:121], v[154:157], v[176:179], v[118:121]
	v_mfma_f32_16x16x32_bf16 v[118:121], v[164:167], v[180:183], v[118:121]
	v_mfma_f32_16x16x32_bf16 v[114:117], v[168:171], v[176:179], v[114:117]
	v_mfma_f32_16x16x32_bf16 v[114:117], v[172:175], v[180:183], v[114:117]
	v_mfma_f32_16x16x32_bf16 v[98:101], v[168:171], v[184:187], v[98:101]
	v_mfma_f32_16x16x32_bf16 v[98:101], v[172:175], v[188:191], v[98:101]
	v_mfma_f32_16x16x32_bf16 v[102:105], v[154:157], v[184:187], v[102:105]
	v_mfma_f32_16x16x32_bf16 v[102:105], v[164:167], v[188:191], v[102:105]
	v_mfma_f32_16x16x32_bf16 v[106:109], v[138:141], v[184:187], v[106:109]
	v_mfma_f32_16x16x32_bf16 v[106:109], v[142:145], v[188:191], v[106:109]
	v_mfma_f32_16x16x32_bf16 v[110:113], v[130:133], v[184:187], v[110:113]
	v_mfma_f32_16x16x32_bf16 v[110:113], v[134:137], v[188:191], v[110:113]
	v_mfma_f32_16x16x32_bf16 v[94:97], v[130:133], v[192:195], v[94:97]
	v_mfma_f32_16x16x32_bf16 v[94:97], v[134:137], v[196:199], v[94:97]
	v_mfma_f32_16x16x32_bf16 v[90:93], v[138:141], v[192:195], v[90:93]
	v_mfma_f32_16x16x32_bf16 v[90:93], v[142:145], v[196:199], v[90:93]
	v_mfma_f32_16x16x32_bf16 v[86:89], v[154:157], v[192:195], v[86:89]
	v_mfma_f32_16x16x32_bf16 v[86:89], v[164:167], v[196:199], v[86:89]
	v_mfma_f32_16x16x32_bf16 v[82:85], v[168:171], v[192:195], v[82:85]
	v_mfma_f32_16x16x32_bf16 v[82:85], v[172:175], v[196:199], v[82:85]
	v_mfma_f32_16x16x32_bf16 v[66:69], v[168:171], v[200:203], v[66:69]
	v_mfma_f32_16x16x32_bf16 v[66:69], v[172:175], v[204:207], v[66:69]
	v_mfma_f32_16x16x32_bf16 v[70:73], v[154:157], v[200:203], v[70:73]
	v_mfma_f32_16x16x32_bf16 v[70:73], v[164:167], v[204:207], v[70:73]
	v_mfma_f32_16x16x32_bf16 v[74:77], v[138:141], v[200:203], v[74:77]
	v_mfma_f32_16x16x32_bf16 v[74:77], v[142:145], v[204:207], v[74:77]
	v_mfma_f32_16x16x32_bf16 v[78:81], v[130:133], v[200:203], v[78:81]
	v_mfma_f32_16x16x32_bf16 v[78:81], v[134:137], v[204:207], v[78:81]
	s_setprio 0
	s_barrier
	s_mov_b32 m0, s74
	s_or_b32 s94, s93, 0x80
	ds_read_b128 v[176:179], v163 offset:49152
	ds_read_b128 v[180:183], v163 offset:50176
	ds_read_b128 v[184:187], v163 offset:51200
	ds_read_b128 v[188:191], v163 offset:52224
	ds_read_b128 v[192:195], v163 offset:53248
	ds_read_b128 v[196:199], v163 offset:54272
	ds_read_b128 v[200:203], v163 offset:55296
	ds_read_b128 v[204:207], v163 offset:56320
	buffer_load_dwordx4 v160, s[4:7], s94 offen lds
	s_add_i32 s94, s93, 0x10080
	s_mov_b32 m0, s75
	s_add_i32 s91, s91, 0x10080
	buffer_load_dwordx4 v160, s[4:7], s94 offen lds
	s_add_i32 s94, s93, 0x20080
	s_mov_b32 m0, s78
	s_add_i32 s93, s93, 0x30080
	buffer_load_dwordx4 v160, s[4:7], s94 offen lds
	s_mov_b32 m0, s79
	s_nop 0
	buffer_load_dwordx4 v160, s[4:7], s93 offen lds
	s_mov_b32 m0, s76
	s_nop 0
	buffer_load_dwordx4 v161, s[12:15], s92 offen lds
	s_mov_b32 m0, s77
	s_nop 0
	buffer_load_dwordx4 v161, s[12:15], s91 offen lds
	s_waitcnt vmcnt(8) lgkmcnt(0)
	s_setprio 1
	s_barrier
	v_mfma_f32_16x16x32_bf16 v[62:65], v[130:133], v[176:179], v[62:65]
	v_mfma_f32_16x16x32_bf16 v[62:65], v[134:137], v[180:183], v[62:65]
	v_mfma_f32_16x16x32_bf16 v[58:61], v[138:141], v[176:179], v[58:61]
	v_mfma_f32_16x16x32_bf16 v[58:61], v[142:145], v[180:183], v[58:61]
	v_mfma_f32_16x16x32_bf16 v[54:57], v[154:157], v[176:179], v[54:57]
	v_mfma_f32_16x16x32_bf16 v[54:57], v[164:167], v[180:183], v[54:57]
	v_mfma_f32_16x16x32_bf16 v[50:53], v[168:171], v[176:179], v[50:53]
	v_mfma_f32_16x16x32_bf16 v[50:53], v[172:175], v[180:183], v[50:53]
	v_mfma_f32_16x16x32_bf16 v[34:37], v[168:171], v[184:187], v[34:37]
	v_mfma_f32_16x16x32_bf16 v[34:37], v[172:175], v[188:191], v[34:37]
	v_mfma_f32_16x16x32_bf16 v[38:41], v[154:157], v[184:187], v[38:41]
	v_mfma_f32_16x16x32_bf16 v[38:41], v[164:167], v[188:191], v[38:41]
	v_mfma_f32_16x16x32_bf16 v[42:45], v[138:141], v[184:187], v[42:45]
	v_mfma_f32_16x16x32_bf16 v[42:45], v[142:145], v[188:191], v[42:45]
	v_mfma_f32_16x16x32_bf16 v[46:49], v[130:133], v[184:187], v[46:49]
	v_mfma_f32_16x16x32_bf16 v[46:49], v[134:137], v[188:191], v[46:49]
	v_mfma_f32_16x16x32_bf16 v[30:33], v[130:133], v[192:195], v[30:33]
	v_mfma_f32_16x16x32_bf16 v[30:33], v[134:137], v[196:199], v[30:33]
	v_mfma_f32_16x16x32_bf16 v[26:29], v[138:141], v[192:195], v[26:29]
	v_mfma_f32_16x16x32_bf16 v[26:29], v[142:145], v[196:199], v[26:29]
	v_mfma_f32_16x16x32_bf16 v[22:25], v[154:157], v[192:195], v[22:25]
	v_mfma_f32_16x16x32_bf16 v[22:25], v[164:167], v[196:199], v[22:25]
	v_mfma_f32_16x16x32_bf16 v[18:21], v[168:171], v[192:195], v[18:21]
	v_mfma_f32_16x16x32_bf16 v[18:21], v[172:175], v[196:199], v[18:21]
	v_mfma_f32_16x16x32_bf16 v[2:5], v[168:171], v[200:203], v[2:5]
	v_mfma_f32_16x16x32_bf16 v[2:5], v[172:175], v[204:207], v[2:5]
	v_mfma_f32_16x16x32_bf16 v[6:9], v[154:157], v[200:203], v[6:9]
	v_mfma_f32_16x16x32_bf16 v[6:9], v[164:167], v[204:207], v[6:9]
	v_mfma_f32_16x16x32_bf16 v[10:13], v[138:141], v[200:203], v[10:13]
	v_mfma_f32_16x16x32_bf16 v[10:13], v[142:145], v[204:207], v[10:13]
	v_mfma_f32_16x16x32_bf16 v[14:17], v[130:133], v[200:203], v[14:17]
	v_mfma_f32_16x16x32_bf16 v[14:17], v[134:137], v[204:207], v[14:17]
	s_setprio 0
	s_barrier
	s_add_i32 s89, s89, 2
	s_cmp_ge_i32 s89, s63
	s_mov_b32 s6, s90
	s_cbranch_scc0 .LBB0_1020
	s_and_b64 vcc, exec, s[54:55]
	s_cbranch_vccz .LBB0_1023

.LBB0_1035:
	ds_read_b128 v[140:143], v134
	ds_read_b128 v[148:151], v134 offset:1024
	ds_read_b128 v[152:155], v134 offset:2048
	ds_read_b128 v[156:159], v134 offset:3072
	ds_read_b128 v[160:163], v135
	ds_read_b128 v[164:167], v135 offset:1024
	ds_read_b128 v[168:171], v135 offset:2048
	ds_read_b128 v[172:175], v135 offset:3072
	s_add_i32 s73, s70, 0xfffb8080
	s_cmp_eq_u32 s53, s72
	s_cselect_b32 s73, s68, s73
	s_cselect_b32 s75, s69, s71
	s_add_i32 s74, s73, 0x80
	s_add_i32 s76, s70, 0xfffe8000
	s_mov_b32 m0, s54
	ds_read_b128 v[176:179], v136
	ds_read_b128 v[180:183], v136 offset:1024
	ds_read_b128 v[184:187], v136 offset:2048
	ds_read_b128 v[188:191], v136 offset:3072
	ds_read_b128 v[192:195], v136 offset:4096
	ds_read_b128 v[196:199], v136 offset:5120
	ds_read_b128 v[200:203], v136 offset:6144
	ds_read_b128 v[204:207], v136 offset:7168
	buffer_load_dwordx4 v132, s[12:15], s76 offen lds
	s_mov_b32 m0, s55
	s_nop 0
	buffer_load_dwordx4 v132, s[12:15], s70 offen lds
	s_waitcnt vmcnt(8) lgkmcnt(0)
	s_setprio 1
	s_barrier
	v_mfma_f32_16x16x32_bf16 v[126:129], v[140:143], v[176:179], v[126:129]
	v_mfma_f32_16x16x32_bf16 v[126:129], v[148:151], v[180:183], v[126:129]
	v_mfma_f32_16x16x32_bf16 v[122:125], v[152:155], v[176:179], v[122:125]
	v_mfma_f32_16x16x32_bf16 v[122:125], v[156:159], v[180:183], v[122:125]
	v_mfma_f32_16x16x32_bf16 v[118:121], v[160:163], v[176:179], v[118:121]
	v_mfma_f32_16x16x32_bf16 v[118:121], v[164:167], v[180:183], v[118:121]
	v_mfma_f32_16x16x32_bf16 v[114:117], v[168:171], v[176:179], v[114:117]
	v_mfma_f32_16x16x32_bf16 v[114:117], v[172:175], v[180:183], v[114:117]
	v_mfma_f32_16x16x32_bf16 v[98:101], v[168:171], v[184:187], v[98:101]
	v_mfma_f32_16x16x32_bf16 v[98:101], v[172:175], v[188:191], v[98:101]
	v_mfma_f32_16x16x32_bf16 v[102:105], v[160:163], v[184:187], v[102:105]
	v_mfma_f32_16x16x32_bf16 v[102:105], v[164:167], v[188:191], v[102:105]
	v_mfma_f32_16x16x32_bf16 v[106:109], v[152:155], v[184:187], v[106:109]
	v_mfma_f32_16x16x32_bf16 v[106:109], v[156:159], v[188:191], v[106:109]
	v_mfma_f32_16x16x32_bf16 v[110:113], v[140:143], v[184:187], v[110:113]
	v_mfma_f32_16x16x32_bf16 v[110:113], v[148:151], v[188:191], v[110:113]
	v_mfma_f32_16x16x32_bf16 v[94:97], v[140:143], v[192:195], v[94:97]
	v_mfma_f32_16x16x32_bf16 v[94:97], v[148:151], v[196:199], v[94:97]
	v_mfma_f32_16x16x32_bf16 v[90:93], v[152:155], v[192:195], v[90:93]
	v_mfma_f32_16x16x32_bf16 v[90:93], v[156:159], v[196:199], v[90:93]
	v_mfma_f32_16x16x32_bf16 v[86:89], v[160:163], v[192:195], v[86:89]
	v_mfma_f32_16x16x32_bf16 v[86:89], v[164:167], v[196:199], v[86:89]
	v_mfma_f32_16x16x32_bf16 v[82:85], v[168:171], v[192:195], v[82:85]
	v_mfma_f32_16x16x32_bf16 v[82:85], v[172:175], v[196:199], v[82:85]
	v_mfma_f32_16x16x32_bf16 v[66:69], v[168:171], v[200:203], v[66:69]
	v_mfma_f32_16x16x32_bf16 v[66:69], v[172:175], v[204:207], v[66:69]
	v_mfma_f32_16x16x32_bf16 v[70:73], v[160:163], v[200:203], v[70:73]
	v_mfma_f32_16x16x32_bf16 v[70:73], v[164:167], v[204:207], v[70:73]
	v_mfma_f32_16x16x32_bf16 v[74:77], v[152:155], v[200:203], v[74:77]
	v_mfma_f32_16x16x32_bf16 v[74:77], v[156:159], v[204:207], v[74:77]
	v_mfma_f32_16x16x32_bf16 v[78:81], v[140:143], v[200:203], v[78:81]
	v_mfma_f32_16x16x32_bf16 v[78:81], v[148:151], v[204:207], v[78:81]
	s_setprio 0
	s_barrier
	s_mov_b32 m0, s30
	ds_read_b128 v[176:179], v136 offset:16384
	ds_read_b128 v[180:183], v136 offset:17408
	ds_read_b128 v[184:187], v136 offset:18432
	ds_read_b128 v[188:191], v136 offset:19456
	ds_read_b128 v[192:195], v136 offset:20480
	ds_read_b128 v[196:199], v136 offset:21504
	ds_read_b128 v[200:203], v136 offset:22528
	ds_read_b128 v[204:207], v136 offset:23552
	buffer_load_dwordx4 v133, s[16:19], s75 offen lds
	s_mov_b32 m0, s31
	s_add_i32 s76, s75, 0x200000
	buffer_load_dwordx4 v133, s[16:19], s76 offen lds
	s_mov_b32 m0, s35
	s_add_i32 s76, s75, 0x400000
	buffer_load_dwordx4 v133, s[16:19], s76 offen lds
	s_mov_b32 m0, s42
	s_add_i32 s76, s75, 0x600000
	buffer_load_dwordx4 v133, s[16:19], s76 offen lds
	s_mov_b32 m0, s27
	s_add_i32 s76, s73, 0x18000
	buffer_load_dwordx4 v132, s[12:15], s73 offen lds
	s_mov_b32 m0, s43
	s_nop 0
	buffer_load_dwordx4 v132, s[12:15], s76 offen lds
	s_waitcnt vmcnt(8) lgkmcnt(0)
	s_setprio 1
	s_barrier
	v_mfma_f32_16x16x32_bf16 v[62:65], v[140:143], v[176:179], v[62:65]
	v_mfma_f32_16x16x32_bf16 v[62:65], v[148:151], v[180:183], v[62:65]
	v_mfma_f32_16x16x32_bf16 v[58:61], v[152:155], v[176:179], v[58:61]
	v_mfma_f32_16x16x32_bf16 v[58:61], v[156:159], v[180:183], v[58:61]
	v_mfma_f32_16x16x32_bf16 v[54:57], v[160:163], v[176:179], v[54:57]
	v_mfma_f32_16x16x32_bf16 v[54:57], v[164:167], v[180:183], v[54:57]
	v_mfma_f32_16x16x32_bf16 v[50:53], v[168:171], v[176:179], v[50:53]
	v_mfma_f32_16x16x32_bf16 v[50:53], v[172:175], v[180:183], v[50:53]
	v_mfma_f32_16x16x32_bf16 v[34:37], v[168:171], v[184:187], v[34:37]
	v_mfma_f32_16x16x32_bf16 v[34:37], v[172:175], v[188:191], v[34:37]
	v_mfma_f32_16x16x32_bf16 v[38:41], v[160:163], v[184:187], v[38:41]
	v_mfma_f32_16x16x32_bf16 v[38:41], v[164:167], v[188:191], v[38:41]
	v_mfma_f32_16x16x32_bf16 v[42:45], v[152:155], v[184:187], v[42:45]
	v_mfma_f32_16x16x32_bf16 v[42:45], v[156:159], v[188:191], v[42:45]
	v_mfma_f32_16x16x32_bf16 v[46:49], v[140:143], v[184:187], v[46:49]
	v_mfma_f32_16x16x32_bf16 v[46:49], v[148:151], v[188:191], v[46:49]
	v_mfma_f32_16x16x32_bf16 v[30:33], v[140:143], v[192:195], v[30:33]
	v_mfma_f32_16x16x32_bf16 v[30:33], v[148:151], v[196:199], v[30:33]
	v_mfma_f32_16x16x32_bf16 v[26:29], v[152:155], v[192:195], v[26:29]
	v_mfma_f32_16x16x32_bf16 v[26:29], v[156:159], v[196:199], v[26:29]
	v_mfma_f32_16x16x32_bf16 v[22:25], v[160:163], v[192:195], v[22:25]
	v_mfma_f32_16x16x32_bf16 v[22:25], v[164:167], v[196:199], v[22:25]
	v_mfma_f32_16x16x32_bf16 v[18:21], v[168:171], v[192:195], v[18:21]
	v_mfma_f32_16x16x32_bf16 v[18:21], v[172:175], v[196:199], v[18:21]
	v_mfma_f32_16x16x32_bf16 v[2:5], v[168:171], v[200:203], v[2:5]
	v_mfma_f32_16x16x32_bf16 v[2:5], v[172:175], v[204:207], v[2:5]
	v_mfma_f32_16x16x32_bf16 v[6:9], v[160:163], v[200:203], v[6:9]
	v_mfma_f32_16x16x32_bf16 v[6:9], v[164:167], v[204:207], v[6:9]
	v_mfma_f32_16x16x32_bf16 v[10:13], v[152:155], v[200:203], v[10:13]
	v_mfma_f32_16x16x32_bf16 v[10:13], v[156:159], v[204:207], v[10:13]
	v_mfma_f32_16x16x32_bf16 v[14:17], v[140:143], v[200:203], v[14:17]
	v_mfma_f32_16x16x32_bf16 v[14:17], v[148:151], v[204:207], v[14:17]
	s_setprio 0
	s_barrier
	ds_read_b128 v[140:143], v137
	ds_read_b128 v[148:151], v137 offset:1024
	ds_read_b128 v[152:155], v137 offset:2048
	ds_read_b128 v[156:159], v137 offset:3072
	ds_read_b128 v[160:163], v138
	ds_read_b128 v[164:167], v138 offset:1024
	ds_read_b128 v[168:171], v138 offset:2048
	ds_read_b128 v[172:175], v138 offset:3072
	s_mov_b32 m0, s44
	s_add_i32 s76, s73, 0x30000
	ds_read_b128 v[176:179], v136 offset:32768
	ds_read_b128 v[180:183], v136 offset:33792
	ds_read_b128 v[184:187], v136 offset:34816
	ds_read_b128 v[188:191], v136 offset:35840
	ds_read_b128 v[192:195], v136 offset:36864
	ds_read_b128 v[196:199], v136 offset:37888
	ds_read_b128 v[200:203], v136 offset:38912
	ds_read_b128 v[204:207], v136 offset:39936
	buffer_load_dwordx4 v132, s[12:15], s76 offen lds
	s_mov_b32 m0, s45
	s_add_i32 s76, s73, 0x48000
	buffer_load_dwordx4 v132, s[12:15], s76 offen lds
	s_waitcnt vmcnt(8) lgkmcnt(0)
	s_setprio 1
	s_barrier
	v_mfma_f32_16x16x32_bf16 v[126:129], v[140:143], v[176:179], v[126:129]
	v_mfma_f32_16x16x32_bf16 v[126:129], v[148:151], v[180:183], v[126:129]
	v_mfma_f32_16x16x32_bf16 v[122:125], v[152:155], v[176:179], v[122:125]
	v_mfma_f32_16x16x32_bf16 v[122:125], v[156:159], v[180:183], v[122:125]
	v_mfma_f32_16x16x32_bf16 v[118:121], v[160:163], v[176:179], v[118:121]
	v_mfma_f32_16x16x32_bf16 v[118:121], v[164:167], v[180:183], v[118:121]
	v_mfma_f32_16x16x32_bf16 v[114:117], v[168:171], v[176:179], v[114:117]
	v_mfma_f32_16x16x32_bf16 v[114:117], v[172:175], v[180:183], v[114:117]
	v_mfma_f32_16x16x32_bf16 v[98:101], v[168:171], v[184:187], v[98:101]
	v_mfma_f32_16x16x32_bf16 v[98:101], v[172:175], v[188:191], v[98:101]
	v_mfma_f32_16x16x32_bf16 v[102:105], v[160:163], v[184:187], v[102:105]
	v_mfma_f32_16x16x32_bf16 v[102:105], v[164:167], v[188:191], v[102:105]
	v_mfma_f32_16x16x32_bf16 v[106:109], v[152:155], v[184:187], v[106:109]
	v_mfma_f32_16x16x32_bf16 v[106:109], v[156:159], v[188:191], v[106:109]
	v_mfma_f32_16x16x32_bf16 v[110:113], v[140:143], v[184:187], v[110:113]
	v_mfma_f32_16x16x32_bf16 v[110:113], v[148:151], v[188:191], v[110:113]
	v_mfma_f32_16x16x32_bf16 v[94:97], v[140:143], v[192:195], v[94:97]
	v_mfma_f32_16x16x32_bf16 v[94:97], v[148:151], v[196:199], v[94:97]
	v_mfma_f32_16x16x32_bf16 v[90:93], v[152:155], v[192:195], v[90:93]
	v_mfma_f32_16x16x32_bf16 v[90:93], v[156:159], v[196:199], v[90:93]
	v_mfma_f32_16x16x32_bf16 v[86:89], v[160:163], v[192:195], v[86:89]
	v_mfma_f32_16x16x32_bf16 v[86:89], v[164:167], v[196:199], v[86:89]
	v_mfma_f32_16x16x32_bf16 v[82:85], v[168:171], v[192:195], v[82:85]
	v_mfma_f32_16x16x32_bf16 v[82:85], v[172:175], v[196:199], v[82:85]
	v_mfma_f32_16x16x32_bf16 v[66:69], v[168:171], v[200:203], v[66:69]
	v_mfma_f32_16x16x32_bf16 v[66:69], v[172:175], v[204:207], v[66:69]
	v_mfma_f32_16x16x32_bf16 v[70:73], v[160:163], v[200:203], v[70:73]
	v_mfma_f32_16x16x32_bf16 v[70:73], v[164:167], v[204:207], v[70:73]
	v_mfma_f32_16x16x32_bf16 v[74:77], v[152:155], v[200:203], v[74:77]
	v_mfma_f32_16x16x32_bf16 v[74:77], v[156:159], v[204:207], v[74:77]
	v_mfma_f32_16x16x32_bf16 v[78:81], v[140:143], v[200:203], v[78:81]
	v_mfma_f32_16x16x32_bf16 v[78:81], v[148:151], v[204:207], v[78:81]
	s_setprio 0
	s_barrier
	s_mov_b32 m0, s46
	s_add_i32 s76, s75, 0x80
	ds_read_b128 v[176:179], v136 offset:49152
	ds_read_b128 v[180:183], v136 offset:50176
	ds_read_b128 v[184:187], v136 offset:51200
	ds_read_b128 v[188:191], v136 offset:52224
	ds_read_b128 v[192:195], v136 offset:53248
	ds_read_b128 v[196:199], v136 offset:54272
	ds_read_b128 v[200:203], v136 offset:55296
	ds_read_b128 v[204:207], v136 offset:56320
	buffer_load_dwordx4 v133, s[16:19], s76 offen lds
	s_add_i32 s76, s75, 0x200080
	s_mov_b32 m0, s47
	s_add_i32 s73, s73, 0x18080
	buffer_load_dwordx4 v133, s[16:19], s76 offen lds
	s_add_i32 s76, s75, 0x400080
	s_mov_b32 m0, s50
	s_add_i32 s75, s75, 0x600080
	buffer_load_dwordx4 v133, s[16:19], s76 offen lds
	s_mov_b32 m0, s51
	s_nop 0
	buffer_load_dwordx4 v133, s[16:19], s75 offen lds
	s_mov_b32 m0, s48
	s_nop 0
	buffer_load_dwordx4 v132, s[12:15], s74 offen lds
	s_mov_b32 m0, s49
	s_nop 0
	buffer_load_dwordx4 v132, s[12:15], s73 offen lds
	s_waitcnt vmcnt(8) lgkmcnt(0)
	s_setprio 1
	s_barrier
	v_mfma_f32_16x16x32_bf16 v[62:65], v[140:143], v[176:179], v[62:65]
	v_mfma_f32_16x16x32_bf16 v[62:65], v[148:151], v[180:183], v[62:65]
	v_mfma_f32_16x16x32_bf16 v[58:61], v[152:155], v[176:179], v[58:61]
	v_mfma_f32_16x16x32_bf16 v[58:61], v[156:159], v[180:183], v[58:61]
	v_mfma_f32_16x16x32_bf16 v[54:57], v[160:163], v[176:179], v[54:57]
	v_mfma_f32_16x16x32_bf16 v[54:57], v[164:167], v[180:183], v[54:57]
	v_mfma_f32_16x16x32_bf16 v[50:53], v[168:171], v[176:179], v[50:53]
	v_mfma_f32_16x16x32_bf16 v[50:53], v[172:175], v[180:183], v[50:53]
	v_mfma_f32_16x16x32_bf16 v[34:37], v[168:171], v[184:187], v[34:37]
	v_mfma_f32_16x16x32_bf16 v[34:37], v[172:175], v[188:191], v[34:37]
	v_mfma_f32_16x16x32_bf16 v[38:41], v[160:163], v[184:187], v[38:41]
	v_mfma_f32_16x16x32_bf16 v[38:41], v[164:167], v[188:191], v[38:41]
	v_mfma_f32_16x16x32_bf16 v[42:45], v[152:155], v[184:187], v[42:45]
	v_mfma_f32_16x16x32_bf16 v[42:45], v[156:159], v[188:191], v[42:45]
	v_mfma_f32_16x16x32_bf16 v[46:49], v[140:143], v[184:187], v[46:49]
	v_mfma_f32_16x16x32_bf16 v[46:49], v[148:151], v[188:191], v[46:49]
	v_mfma_f32_16x16x32_bf16 v[30:33], v[140:143], v[192:195], v[30:33]
	v_mfma_f32_16x16x32_bf16 v[30:33], v[148:151], v[196:199], v[30:33]
	v_mfma_f32_16x16x32_bf16 v[26:29], v[152:155], v[192:195], v[26:29]
	v_mfma_f32_16x16x32_bf16 v[26:29], v[156:159], v[196:199], v[26:29]
	v_mfma_f32_16x16x32_bf16 v[22:25], v[160:163], v[192:195], v[22:25]
	v_mfma_f32_16x16x32_bf16 v[22:25], v[164:167], v[196:199], v[22:25]
	v_mfma_f32_16x16x32_bf16 v[18:21], v[168:171], v[192:195], v[18:21]
	v_mfma_f32_16x16x32_bf16 v[18:21], v[172:175], v[196:199], v[18:21]
	v_mfma_f32_16x16x32_bf16 v[2:5], v[168:171], v[200:203], v[2:5]
	v_mfma_f32_16x16x32_bf16 v[2:5], v[172:175], v[204:207], v[2:5]
	v_mfma_f32_16x16x32_bf16 v[6:9], v[160:163], v[200:203], v[6:9]
	v_mfma_f32_16x16x32_bf16 v[6:9], v[164:167], v[204:207], v[6:9]
	v_mfma_f32_16x16x32_bf16 v[10:13], v[152:155], v[200:203], v[10:13]
	v_mfma_f32_16x16x32_bf16 v[10:13], v[156:159], v[204:207], v[10:13]
	v_mfma_f32_16x16x32_bf16 v[14:17], v[140:143], v[200:203], v[14:17]
	v_mfma_f32_16x16x32_bf16 v[14:17], v[148:151], v[204:207], v[14:17]
	s_setprio 0
	s_barrier
	s_add_i32 s72, s72, 2
	s_addk_i32 s70, 0x100
	s_addk_i32 s71, 0x100
	s_cmp_ge_i32 s72, s21
	s_cbranch_scc0 .LBB0_1035

.LBB0_1050:
	ds_read_b128 v[132:135], v142
	ds_read_b128 v[136:139], v142 offset:1024
	ds_read_b128 v[148:151], v142 offset:2048
	ds_read_b128 v[152:155], v142 offset:3072
	ds_read_b128 v[156:159], v143
	ds_read_b128 v[160:163], v143 offset:1024
	ds_read_b128 v[164:167], v143 offset:2048
	ds_read_b128 v[168:171], v143 offset:3072
	s_add_i32 s18, s61, 0xfff40080
	s_cmp_eq_u32 s54, s62
	s_cselect_b32 s64, s35, s18
	s_add_i32 s63, s64, 0x80
	s_add_i32 s18, s61, 0xfffc0000
	s_mov_b32 m0, s55
	ds_read_b128 v[172:175], v144
	ds_read_b128 v[176:179], v144 offset:1024
	ds_read_b128 v[180:183], v144 offset:2048
	ds_read_b128 v[184:187], v144 offset:3072
	ds_read_b128 v[188:191], v144 offset:4096
	ds_read_b128 v[192:195], v144 offset:5120
	ds_read_b128 v[196:199], v144 offset:6144
	ds_read_b128 v[200:203], v144 offset:7168
	buffer_load_dwordx4 v140, s[12:15], s18 offen lds
	s_mov_b32 m0, s56
	s_nop 0
	buffer_load_dwordx4 v140, s[12:15], s61 offen lds
	s_waitcnt vmcnt(8) lgkmcnt(0)
	s_setprio 1
	s_barrier
	v_mfma_f32_16x16x32_bf16 v[126:129], v[132:135], v[172:175], v[126:129]
	v_mfma_f32_16x16x32_bf16 v[126:129], v[136:139], v[176:179], v[126:129]
	v_mfma_f32_16x16x32_bf16 v[122:125], v[148:151], v[172:175], v[122:125]
	v_mfma_f32_16x16x32_bf16 v[122:125], v[152:155], v[176:179], v[122:125]
	v_mfma_f32_16x16x32_bf16 v[118:121], v[156:159], v[172:175], v[118:121]
	v_mfma_f32_16x16x32_bf16 v[118:121], v[160:163], v[176:179], v[118:121]
	v_mfma_f32_16x16x32_bf16 v[114:117], v[164:167], v[172:175], v[114:117]
	v_mfma_f32_16x16x32_bf16 v[114:117], v[168:171], v[176:179], v[114:117]
	v_mfma_f32_16x16x32_bf16 v[98:101], v[164:167], v[180:183], v[98:101]
	v_mfma_f32_16x16x32_bf16 v[98:101], v[168:171], v[184:187], v[98:101]
	v_mfma_f32_16x16x32_bf16 v[102:105], v[156:159], v[180:183], v[102:105]
	v_mfma_f32_16x16x32_bf16 v[102:105], v[160:163], v[184:187], v[102:105]
	v_mfma_f32_16x16x32_bf16 v[106:109], v[148:151], v[180:183], v[106:109]
	v_mfma_f32_16x16x32_bf16 v[106:109], v[152:155], v[184:187], v[106:109]
	v_mfma_f32_16x16x32_bf16 v[110:113], v[132:135], v[180:183], v[110:113]
	v_mfma_f32_16x16x32_bf16 v[110:113], v[136:139], v[184:187], v[110:113]
	v_mfma_f32_16x16x32_bf16 v[94:97], v[132:135], v[188:191], v[94:97]
	v_mfma_f32_16x16x32_bf16 v[94:97], v[136:139], v[192:195], v[94:97]
	v_mfma_f32_16x16x32_bf16 v[90:93], v[148:151], v[188:191], v[90:93]
	v_mfma_f32_16x16x32_bf16 v[90:93], v[152:155], v[192:195], v[90:93]
	v_mfma_f32_16x16x32_bf16 v[86:89], v[156:159], v[188:191], v[86:89]
	v_mfma_f32_16x16x32_bf16 v[86:89], v[160:163], v[192:195], v[86:89]
	v_mfma_f32_16x16x32_bf16 v[82:85], v[164:167], v[188:191], v[82:85]
	v_mfma_f32_16x16x32_bf16 v[82:85], v[168:171], v[192:195], v[82:85]
	v_mfma_f32_16x16x32_bf16 v[66:69], v[164:167], v[196:199], v[66:69]
	v_mfma_f32_16x16x32_bf16 v[66:69], v[168:171], v[200:203], v[66:69]
	v_mfma_f32_16x16x32_bf16 v[70:73], v[156:159], v[196:199], v[70:73]
	v_mfma_f32_16x16x32_bf16 v[70:73], v[160:163], v[200:203], v[70:73]
	v_mfma_f32_16x16x32_bf16 v[74:77], v[148:151], v[196:199], v[74:77]
	v_mfma_f32_16x16x32_bf16 v[74:77], v[152:155], v[200:203], v[74:77]
	v_mfma_f32_16x16x32_bf16 v[78:81], v[132:135], v[196:199], v[78:81]
	v_mfma_f32_16x16x32_bf16 v[78:81], v[136:139], v[200:203], v[78:81]
	s_setprio 0
	s_barrier
	s_mov_b32 m0, s25
	s_mov_b32 s18, s14
	s_mov_b32 s19, s15
	ds_read_b128 v[172:175], v144 offset:16384
	ds_read_b128 v[176:179], v144 offset:17408
	ds_read_b128 v[180:183], v144 offset:18432
	ds_read_b128 v[184:187], v144 offset:19456
	ds_read_b128 v[188:191], v144 offset:20480
	ds_read_b128 v[192:195], v144 offset:21504
	ds_read_b128 v[196:199], v144 offset:22528
	ds_read_b128 v[200:203], v144 offset:23552
	buffer_load_dwordx4 v141, s[16:19], s64 offen lds
	s_add_i32 s65, s64, 0x40000
	s_mov_b32 m0, s27
	s_add_i32 s66, s64, 0x80000
	buffer_load_dwordx4 v141, s[16:19], s65 offen lds
	s_mov_b32 m0, s30
	s_add_i32 s67, s64, 0xc0000
	buffer_load_dwordx4 v141, s[16:19], s66 offen lds
	s_mov_b32 m0, s31
	s_nop 0
	buffer_load_dwordx4 v141, s[16:19], s67 offen lds
	s_mov_b32 m0, s21
	s_nop 0
	buffer_load_dwordx4 v140, s[12:15], s64 offen lds
	s_mov_b32 m0, s38
	s_nop 0
	buffer_load_dwordx4 v140, s[12:15], s65 offen lds
	s_waitcnt vmcnt(8) lgkmcnt(0)
	s_setprio 1
	s_barrier
	v_mfma_f32_16x16x32_bf16 v[62:65], v[132:135], v[172:175], v[62:65]
	v_mfma_f32_16x16x32_bf16 v[62:65], v[136:139], v[176:179], v[62:65]
	v_mfma_f32_16x16x32_bf16 v[58:61], v[148:151], v[172:175], v[58:61]
	v_mfma_f32_16x16x32_bf16 v[58:61], v[152:155], v[176:179], v[58:61]
	v_mfma_f32_16x16x32_bf16 v[54:57], v[156:159], v[172:175], v[54:57]
	v_mfma_f32_16x16x32_bf16 v[54:57], v[160:163], v[176:179], v[54:57]
	v_mfma_f32_16x16x32_bf16 v[50:53], v[164:167], v[172:175], v[50:53]
	v_mfma_f32_16x16x32_bf16 v[50:53], v[168:171], v[176:179], v[50:53]
	v_mfma_f32_16x16x32_bf16 v[34:37], v[164:167], v[180:183], v[34:37]
	v_mfma_f32_16x16x32_bf16 v[34:37], v[168:171], v[184:187], v[34:37]
	v_mfma_f32_16x16x32_bf16 v[38:41], v[156:159], v[180:183], v[38:41]
	v_mfma_f32_16x16x32_bf16 v[38:41], v[160:163], v[184:187], v[38:41]
	v_mfma_f32_16x16x32_bf16 v[42:45], v[148:151], v[180:183], v[42:45]
	v_mfma_f32_16x16x32_bf16 v[42:45], v[152:155], v[184:187], v[42:45]
	v_mfma_f32_16x16x32_bf16 v[46:49], v[132:135], v[180:183], v[46:49]
	v_mfma_f32_16x16x32_bf16 v[46:49], v[136:139], v[184:187], v[46:49]
	v_mfma_f32_16x16x32_bf16 v[30:33], v[132:135], v[188:191], v[30:33]
	v_mfma_f32_16x16x32_bf16 v[30:33], v[136:139], v[192:195], v[30:33]
	v_mfma_f32_16x16x32_bf16 v[26:29], v[148:151], v[188:191], v[26:29]
	v_mfma_f32_16x16x32_bf16 v[26:29], v[152:155], v[192:195], v[26:29]
	v_mfma_f32_16x16x32_bf16 v[22:25], v[156:159], v[188:191], v[22:25]
	v_mfma_f32_16x16x32_bf16 v[22:25], v[160:163], v[192:195], v[22:25]
	v_mfma_f32_16x16x32_bf16 v[18:21], v[164:167], v[188:191], v[18:21]
	v_mfma_f32_16x16x32_bf16 v[18:21], v[168:171], v[192:195], v[18:21]
	v_mfma_f32_16x16x32_bf16 v[2:5], v[164:167], v[196:199], v[2:5]
	v_mfma_f32_16x16x32_bf16 v[2:5], v[168:171], v[200:203], v[2:5]
	v_mfma_f32_16x16x32_bf16 v[6:9], v[156:159], v[196:199], v[6:9]
	v_mfma_f32_16x16x32_bf16 v[6:9], v[160:163], v[200:203], v[6:9]
	v_mfma_f32_16x16x32_bf16 v[10:13], v[148:151], v[196:199], v[10:13]
	v_mfma_f32_16x16x32_bf16 v[10:13], v[152:155], v[200:203], v[10:13]
	v_mfma_f32_16x16x32_bf16 v[14:17], v[132:135], v[196:199], v[14:17]
	v_mfma_f32_16x16x32_bf16 v[14:17], v[136:139], v[200:203], v[14:17]
	s_setprio 0
	s_barrier
	ds_read_b128 v[132:135], v145
	ds_read_b128 v[136:139], v145 offset:1024
	ds_read_b128 v[148:151], v145 offset:2048
	ds_read_b128 v[152:155], v145 offset:3072
	ds_read_b128 v[156:159], v147
	ds_read_b128 v[160:163], v147 offset:1024
	ds_read_b128 v[164:167], v147 offset:2048
	ds_read_b128 v[168:171], v147 offset:3072
	s_mov_b32 m0, s39
	ds_read_b128 v[172:175], v144 offset:32768
	ds_read_b128 v[176:179], v144 offset:33792
	ds_read_b128 v[180:183], v144 offset:34816
	ds_read_b128 v[184:187], v144 offset:35840
	ds_read_b128 v[188:191], v144 offset:36864
	ds_read_b128 v[192:195], v144 offset:37888
	ds_read_b128 v[196:199], v144 offset:38912
	ds_read_b128 v[200:203], v144 offset:39936
	buffer_load_dwordx4 v140, s[12:15], s66 offen lds
	s_mov_b32 m0, s40
	s_nop 0
	buffer_load_dwordx4 v140, s[12:15], s67 offen lds
	s_waitcnt vmcnt(8) lgkmcnt(0)
	s_setprio 1
	s_barrier
	v_mfma_f32_16x16x32_bf16 v[126:129], v[132:135], v[172:175], v[126:129]
	v_mfma_f32_16x16x32_bf16 v[126:129], v[136:139], v[176:179], v[126:129]
	v_mfma_f32_16x16x32_bf16 v[122:125], v[148:151], v[172:175], v[122:125]
	v_mfma_f32_16x16x32_bf16 v[122:125], v[152:155], v[176:179], v[122:125]
	v_mfma_f32_16x16x32_bf16 v[118:121], v[156:159], v[172:175], v[118:121]
	v_mfma_f32_16x16x32_bf16 v[118:121], v[160:163], v[176:179], v[118:121]
	v_mfma_f32_16x16x32_bf16 v[114:117], v[164:167], v[172:175], v[114:117]
	v_mfma_f32_16x16x32_bf16 v[114:117], v[168:171], v[176:179], v[114:117]
	v_mfma_f32_16x16x32_bf16 v[98:101], v[164:167], v[180:183], v[98:101]
	v_mfma_f32_16x16x32_bf16 v[98:101], v[168:171], v[184:187], v[98:101]
	v_mfma_f32_16x16x32_bf16 v[102:105], v[156:159], v[180:183], v[102:105]
	v_mfma_f32_16x16x32_bf16 v[102:105], v[160:163], v[184:187], v[102:105]
	v_mfma_f32_16x16x32_bf16 v[106:109], v[148:151], v[180:183], v[106:109]
	v_mfma_f32_16x16x32_bf16 v[106:109], v[152:155], v[184:187], v[106:109]
	v_mfma_f32_16x16x32_bf16 v[110:113], v[132:135], v[180:183], v[110:113]
	v_mfma_f32_16x16x32_bf16 v[110:113], v[136:139], v[184:187], v[110:113]
	v_mfma_f32_16x16x32_bf16 v[94:97], v[132:135], v[188:191], v[94:97]
	v_mfma_f32_16x16x32_bf16 v[94:97], v[136:139], v[192:195], v[94:97]
	v_mfma_f32_16x16x32_bf16 v[90:93], v[148:151], v[188:191], v[90:93]
	v_mfma_f32_16x16x32_bf16 v[90:93], v[152:155], v[192:195], v[90:93]
	v_mfma_f32_16x16x32_bf16 v[86:89], v[156:159], v[188:191], v[86:89]
	v_mfma_f32_16x16x32_bf16 v[86:89], v[160:163], v[192:195], v[86:89]
	v_mfma_f32_16x16x32_bf16 v[82:85], v[164:167], v[188:191], v[82:85]
	v_mfma_f32_16x16x32_bf16 v[82:85], v[168:171], v[192:195], v[82:85]
	v_mfma_f32_16x16x32_bf16 v[66:69], v[164:167], v[196:199], v[66:69]
	v_mfma_f32_16x16x32_bf16 v[66:69], v[168:171], v[200:203], v[66:69]
	v_mfma_f32_16x16x32_bf16 v[70:73], v[156:159], v[196:199], v[70:73]
	v_mfma_f32_16x16x32_bf16 v[70:73], v[160:163], v[200:203], v[70:73]
	v_mfma_f32_16x16x32_bf16 v[74:77], v[148:151], v[196:199], v[74:77]
	v_mfma_f32_16x16x32_bf16 v[74:77], v[152:155], v[200:203], v[74:77]
	v_mfma_f32_16x16x32_bf16 v[78:81], v[132:135], v[196:199], v[78:81]
	v_mfma_f32_16x16x32_bf16 v[78:81], v[136:139], v[200:203], v[78:81]
	s_setprio 0
	s_barrier
	s_mov_b32 m0, s48
	ds_read_b128 v[172:175], v144 offset:49152
	ds_read_b128 v[176:179], v144 offset:50176
	ds_read_b128 v[180:183], v144 offset:51200
	ds_read_b128 v[184:187], v144 offset:52224
	ds_read_b128 v[188:191], v144 offset:53248
	ds_read_b128 v[192:195], v144 offset:54272
	ds_read_b128 v[196:199], v144 offset:55296
	ds_read_b128 v[200:203], v144 offset:56320
	buffer_load_dwordx4 v141, s[16:19], s63 offen lds
	s_add_i32 s65, s64, 0x40080
	s_mov_b32 m0, s49
	s_add_i32 s66, s64, 0x80080
	buffer_load_dwordx4 v141, s[16:19], s65 offen lds
	s_mov_b32 m0, s52
	s_add_i32 s64, s64, 0xc0080
	buffer_load_dwordx4 v141, s[16:19], s66 offen lds
	s_mov_b32 m0, s53
	s_nop 0
	buffer_load_dwordx4 v141, s[16:19], s64 offen lds
	s_mov_b32 m0, s50
	s_nop 0
	buffer_load_dwordx4 v140, s[12:15], s63 offen lds
	s_mov_b32 m0, s51
	s_nop 0
	buffer_load_dwordx4 v140, s[12:15], s65 offen lds
	s_waitcnt vmcnt(8) lgkmcnt(0)
	s_setprio 1
	s_barrier
	v_mfma_f32_16x16x32_bf16 v[62:65], v[132:135], v[172:175], v[62:65]
	v_mfma_f32_16x16x32_bf16 v[62:65], v[136:139], v[176:179], v[62:65]
	v_mfma_f32_16x16x32_bf16 v[58:61], v[148:151], v[172:175], v[58:61]
	v_mfma_f32_16x16x32_bf16 v[58:61], v[152:155], v[176:179], v[58:61]
	v_mfma_f32_16x16x32_bf16 v[54:57], v[156:159], v[172:175], v[54:57]
	v_mfma_f32_16x16x32_bf16 v[54:57], v[160:163], v[176:179], v[54:57]
	v_mfma_f32_16x16x32_bf16 v[50:53], v[164:167], v[172:175], v[50:53]
	v_mfma_f32_16x16x32_bf16 v[50:53], v[168:171], v[176:179], v[50:53]
	v_mfma_f32_16x16x32_bf16 v[34:37], v[164:167], v[180:183], v[34:37]
	v_mfma_f32_16x16x32_bf16 v[34:37], v[168:171], v[184:187], v[34:37]
	v_mfma_f32_16x16x32_bf16 v[38:41], v[156:159], v[180:183], v[38:41]
	v_mfma_f32_16x16x32_bf16 v[38:41], v[160:163], v[184:187], v[38:41]
	v_mfma_f32_16x16x32_bf16 v[42:45], v[148:151], v[180:183], v[42:45]
	v_mfma_f32_16x16x32_bf16 v[42:45], v[152:155], v[184:187], v[42:45]
	v_mfma_f32_16x16x32_bf16 v[46:49], v[132:135], v[180:183], v[46:49]
	v_mfma_f32_16x16x32_bf16 v[46:49], v[136:139], v[184:187], v[46:49]
	v_mfma_f32_16x16x32_bf16 v[30:33], v[132:135], v[188:191], v[30:33]
	v_mfma_f32_16x16x32_bf16 v[30:33], v[136:139], v[192:195], v[30:33]
	v_mfma_f32_16x16x32_bf16 v[26:29], v[148:151], v[188:191], v[26:29]
	v_mfma_f32_16x16x32_bf16 v[26:29], v[152:155], v[192:195], v[26:29]
	v_mfma_f32_16x16x32_bf16 v[22:25], v[156:159], v[188:191], v[22:25]
	v_mfma_f32_16x16x32_bf16 v[22:25], v[160:163], v[192:195], v[22:25]
	v_mfma_f32_16x16x32_bf16 v[18:21], v[164:167], v[188:191], v[18:21]
	v_mfma_f32_16x16x32_bf16 v[18:21], v[168:171], v[192:195], v[18:21]
	v_mfma_f32_16x16x32_bf16 v[2:5], v[164:167], v[196:199], v[2:5]
	v_mfma_f32_16x16x32_bf16 v[2:5], v[168:171], v[200:203], v[2:5]
	v_mfma_f32_16x16x32_bf16 v[6:9], v[156:159], v[196:199], v[6:9]
	v_mfma_f32_16x16x32_bf16 v[6:9], v[160:163], v[200:203], v[6:9]
	v_mfma_f32_16x16x32_bf16 v[10:13], v[148:151], v[196:199], v[10:13]
	v_mfma_f32_16x16x32_bf16 v[10:13], v[152:155], v[200:203], v[10:13]
	v_mfma_f32_16x16x32_bf16 v[14:17], v[132:135], v[196:199], v[14:17]
	v_mfma_f32_16x16x32_bf16 v[14:17], v[136:139], v[200:203], v[14:17]
	s_setprio 0
	s_barrier
	s_add_i32 s62, s62, 2
	s_addk_i32 s61, 0x100
	s_cmp_ge_i32 s62, s3
	s_cbranch_scc0 .LBB0_1050

.LBB0_1181:
	v_add_u32_e32 v2, 0x10000, v232
	ds_read_b128 v[134:137], v2
	ds_read_b128 v[138:141], v2 offset:1024
	ds_read_b128 v[142:145], v2 offset:2048
	ds_read_b128 v[146:149], v2 offset:3072
	v_add_u32_e32 v2, 0x14000, v232
	ds_read_b128 v[150:153], v2
	ds_read_b128 v[154:157], v2 offset:1024
	ds_read_b128 v[158:161], v2 offset:2048
	ds_read_b128 v[162:165], v2 offset:3072
	s_add_i32 s50, s47, s90
	s_and_b64 s[18:19], exec, s[18:19]
	s_cselect_b32 s51, s88, s50
	s_add_i32 s50, s92, 0x80
	s_or_b32 s52, s51, 0x80
	s_add_i32 s18, s89, s93
	s_add_i32 s94, s94, 0x1bfffc80
	s_cmp_lt_u32 s91, 8
	s_cselect_b32 s18, s18, s94
	s_mov_b32 m0, s74
	s_add_i32 s19, s18, 0x80000
	ds_read_b128 v[166:169], v233
	ds_read_b128 v[170:173], v233 offset:1024
	ds_read_b128 v[174:177], v233 offset:2048
	ds_read_b128 v[178:181], v233 offset:3072
	ds_read_b128 v[182:185], v233 offset:4096
	ds_read_b128 v[186:189], v233 offset:5120
	ds_read_b128 v[190:193], v233 offset:6144
	ds_read_b128 v[194:197], v233 offset:7168
	buffer_load_dwordx4 v230, s[12:15], s19 offen lds
	s_mov_b32 m0, s75
	s_add_i32 s18, s18, 0xc0000
	buffer_load_dwordx4 v230, s[12:15], s18 offen lds
	s_waitcnt vmcnt(8) lgkmcnt(0)
	s_setprio 1
	s_barrier
	v_mfma_f32_16x16x32_bf16 v[130:133], v[134:137], v[166:169], v[130:133]
	v_mfma_f32_16x16x32_bf16 v[130:133], v[138:141], v[170:173], v[130:133]
	v_mfma_f32_16x16x32_bf16 v[126:129], v[142:145], v[166:169], v[126:129]
	v_mfma_f32_16x16x32_bf16 v[126:129], v[146:149], v[170:173], v[126:129]
	v_mfma_f32_16x16x32_bf16 v[122:125], v[150:153], v[166:169], v[122:125]
	v_mfma_f32_16x16x32_bf16 v[122:125], v[154:157], v[170:173], v[122:125]
	v_mfma_f32_16x16x32_bf16 v[118:121], v[158:161], v[166:169], v[118:121]
	v_mfma_f32_16x16x32_bf16 v[118:121], v[162:165], v[170:173], v[118:121]
	v_mfma_f32_16x16x32_bf16 v[102:105], v[158:161], v[174:177], v[102:105]
	v_mfma_f32_16x16x32_bf16 v[102:105], v[162:165], v[178:181], v[102:105]
	v_mfma_f32_16x16x32_bf16 v[106:109], v[150:153], v[174:177], v[106:109]
	v_mfma_f32_16x16x32_bf16 v[106:109], v[154:157], v[178:181], v[106:109]
	v_mfma_f32_16x16x32_bf16 v[110:113], v[142:145], v[174:177], v[110:113]
	v_mfma_f32_16x16x32_bf16 v[110:113], v[146:149], v[178:181], v[110:113]
	v_mfma_f32_16x16x32_bf16 v[114:117], v[134:137], v[174:177], v[114:117]
	v_mfma_f32_16x16x32_bf16 v[114:117], v[138:141], v[178:181], v[114:117]
	v_mfma_f32_16x16x32_bf16 v[98:101], v[134:137], v[182:185], v[98:101]
	v_mfma_f32_16x16x32_bf16 v[98:101], v[138:141], v[186:189], v[98:101]
	v_mfma_f32_16x16x32_bf16 v[94:97], v[142:145], v[182:185], v[94:97]
	v_mfma_f32_16x16x32_bf16 v[94:97], v[146:149], v[186:189], v[94:97]
	v_mfma_f32_16x16x32_bf16 v[90:93], v[150:153], v[182:185], v[90:93]
	v_mfma_f32_16x16x32_bf16 v[90:93], v[154:157], v[186:189], v[90:93]
	v_mfma_f32_16x16x32_bf16 v[86:89], v[158:161], v[182:185], v[86:89]
	v_mfma_f32_16x16x32_bf16 v[86:89], v[162:165], v[186:189], v[86:89]
	v_mfma_f32_16x16x32_bf16 v[70:73], v[158:161], v[190:193], v[70:73]
	v_mfma_f32_16x16x32_bf16 v[70:73], v[162:165], v[194:197], v[70:73]
	v_mfma_f32_16x16x32_bf16 v[74:77], v[150:153], v[190:193], v[74:77]
	v_mfma_f32_16x16x32_bf16 v[74:77], v[154:157], v[194:197], v[74:77]
	v_mfma_f32_16x16x32_bf16 v[78:81], v[142:145], v[190:193], v[78:81]
	v_mfma_f32_16x16x32_bf16 v[78:81], v[146:149], v[194:197], v[78:81]
	v_mfma_f32_16x16x32_bf16 v[82:85], v[134:137], v[190:193], v[82:85]
	v_mfma_f32_16x16x32_bf16 v[82:85], v[138:141], v[194:197], v[82:85]
	s_setprio 0
	s_barrier
	s_mov_b32 m0, s27
	s_mov_b32 s18, s14
	s_mov_b32 s19, s15
	ds_read_b128 v[166:169], v233 offset:16384
	ds_read_b128 v[170:173], v233 offset:17408
	ds_read_b128 v[174:177], v233 offset:18432
	ds_read_b128 v[178:181], v233 offset:19456
	ds_read_b128 v[182:185], v233 offset:20480
	ds_read_b128 v[186:189], v233 offset:21504
	ds_read_b128 v[190:193], v233 offset:22528
	ds_read_b128 v[194:197], v233 offset:23552
	buffer_load_dwordx4 v231, s[16:19], s51 offen lds
	s_mov_b32 m0, s30
	s_add_i32 s53, s51, 0x18000
	buffer_load_dwordx4 v231, s[16:19], s53 offen lds
	s_mov_b32 m0, s31
	s_add_i32 s53, s51, 0x30000
	buffer_load_dwordx4 v231, s[16:19], s53 offen lds
	s_mov_b32 m0, s54
	s_add_i32 s53, s51, 0x48000
	buffer_load_dwordx4 v231, s[16:19], s53 offen lds
	s_mov_b32 m0, s25
	s_add_i32 s53, s92, 0x40000
	buffer_load_dwordx4 v230, s[12:15], s92 offen lds
	s_mov_b32 m0, s55
	s_nop 0
	buffer_load_dwordx4 v230, s[12:15], s53 offen lds
	s_waitcnt vmcnt(8) lgkmcnt(0)
	s_setprio 1
	s_barrier
	v_mfma_f32_16x16x32_bf16 v[66:69], v[134:137], v[166:169], v[66:69]
	v_mfma_f32_16x16x32_bf16 v[62:65], v[142:145], v[166:169], v[62:65]
	v_mfma_f32_16x16x32_bf16 v[50:53], v[134:137], v[174:177], v[50:53]
	v_mfma_f32_16x16x32_bf16 v[46:49], v[142:145], v[174:177], v[46:49]
	v_mfma_f32_16x16x32_bf16 v[34:37], v[134:137], v[182:185], v[34:37]
	v_mfma_f32_16x16x32_bf16 v[30:33], v[142:145], v[182:185], v[30:33]
	v_mfma_f32_16x16x32_bf16 v[18:21], v[134:137], v[190:193], v[18:21]
	v_mfma_f32_16x16x32_bf16 v[14:17], v[142:145], v[190:193], v[14:17]
	v_mfma_f32_16x16x32_bf16 v[58:61], v[150:153], v[166:169], v[58:61]
	v_mfma_f32_16x16x32_bf16 v[54:57], v[158:161], v[166:169], v[54:57]
	v_mfma_f32_16x16x32_bf16 v[42:45], v[150:153], v[174:177], v[42:45]
	v_mfma_f32_16x16x32_bf16 v[38:41], v[158:161], v[174:177], v[38:41]
	v_mfma_f32_16x16x32_bf16 v[26:29], v[150:153], v[182:185], v[26:29]
	v_mfma_f32_16x16x32_bf16 v[22:25], v[158:161], v[182:185], v[22:25]
	v_mfma_f32_16x16x32_bf16 v[10:13], v[150:153], v[190:193], v[10:13]
	v_mfma_f32_16x16x32_bf16 v[4:7], v[158:161], v[190:193], v[6:9]
	v_mfma_f32_16x16x32_bf16 v[66:69], v[138:141], v[170:173], v[66:69]
	v_mfma_f32_16x16x32_bf16 v[62:65], v[146:149], v[170:173], v[62:65]
	v_mfma_f32_16x16x32_bf16 v[50:53], v[138:141], v[178:181], v[50:53]
	v_mfma_f32_16x16x32_bf16 v[46:49], v[146:149], v[178:181], v[46:49]
	v_mfma_f32_16x16x32_bf16 v[34:37], v[138:141], v[186:189], v[34:37]
	v_mfma_f32_16x16x32_bf16 v[30:33], v[146:149], v[186:189], v[30:33]
	v_mfma_f32_16x16x32_bf16 v[18:21], v[138:141], v[194:197], v[18:21]
	v_mfma_f32_16x16x32_bf16 v[14:17], v[146:149], v[194:197], v[14:17]
	v_mfma_f32_16x16x32_bf16 v[58:61], v[154:157], v[170:173], v[58:61]
	v_mfma_f32_16x16x32_bf16 v[54:57], v[162:165], v[170:173], v[54:57]
	v_mfma_f32_16x16x32_bf16 v[42:45], v[154:157], v[178:181], v[42:45]
	v_mfma_f32_16x16x32_bf16 v[38:41], v[162:165], v[178:181], v[38:41]
	v_mfma_f32_16x16x32_bf16 v[26:29], v[154:157], v[186:189], v[26:29]
	v_mfma_f32_16x16x32_bf16 v[22:25], v[162:165], v[186:189], v[22:25]
	v_mfma_f32_16x16x32_bf16 v[10:13], v[154:157], v[194:197], v[10:13]
	v_mfma_f32_16x16x32_bf16 v[4:7], v[162:165], v[194:197], v[4:7]
	s_setprio 0
	s_barrier
	v_add_u32_e32 v2, 0x18000, v232
	ds_read_b128 v[134:137], v2
	ds_read_b128 v[138:141], v2 offset:1024
	ds_read_b128 v[142:145], v2 offset:2048
	ds_read_b128 v[146:149], v2 offset:3072
	v_add_u32_e32 v2, 0x1c000, v232
	ds_read_b128 v[150:153], v2
	ds_read_b128 v[154:157], v2 offset:1024
	ds_read_b128 v[158:161], v2 offset:2048
	ds_read_b128 v[162:165], v2 offset:3072
	s_mov_b32 m0, s56
	s_add_i32 s53, s92, 0x80000
	ds_read_b128 v[166:169], v233 offset:32768
	ds_read_b128 v[170:173], v233 offset:33792
	ds_read_b128 v[174:177], v233 offset:34816
	ds_read_b128 v[178:181], v233 offset:35840
	ds_read_b128 v[182:185], v233 offset:36864
	ds_read_b128 v[186:189], v233 offset:37888
	ds_read_b128 v[190:193], v233 offset:38912
	ds_read_b128 v[194:197], v233 offset:39936
	buffer_load_dwordx4 v230, s[12:15], s53 offen lds
	s_mov_b32 m0, s57
	s_add_i32 s53, s92, 0xc0000
	buffer_load_dwordx4 v230, s[12:15], s53 offen lds
	s_waitcnt vmcnt(8) lgkmcnt(0)
	s_setprio 1
	s_barrier
	v_mfma_f32_16x16x32_bf16 v[130:133], v[134:137], v[166:169], v[130:133]
	v_mfma_f32_16x16x32_bf16 v[130:133], v[138:141], v[170:173], v[130:133]
	v_mfma_f32_16x16x32_bf16 v[126:129], v[142:145], v[166:169], v[126:129]
	v_mfma_f32_16x16x32_bf16 v[126:129], v[146:149], v[170:173], v[126:129]
	v_mfma_f32_16x16x32_bf16 v[122:125], v[150:153], v[166:169], v[122:125]
	v_mfma_f32_16x16x32_bf16 v[122:125], v[154:157], v[170:173], v[122:125]
	v_mfma_f32_16x16x32_bf16 v[118:121], v[158:161], v[166:169], v[118:121]
	v_mfma_f32_16x16x32_bf16 v[118:121], v[162:165], v[170:173], v[118:121]
	v_mfma_f32_16x16x32_bf16 v[102:105], v[158:161], v[174:177], v[102:105]
	v_mfma_f32_16x16x32_bf16 v[102:105], v[162:165], v[178:181], v[102:105]
	v_mfma_f32_16x16x32_bf16 v[106:109], v[150:153], v[174:177], v[106:109]
	v_mfma_f32_16x16x32_bf16 v[106:109], v[154:157], v[178:181], v[106:109]
	v_mfma_f32_16x16x32_bf16 v[110:113], v[142:145], v[174:177], v[110:113]
	v_mfma_f32_16x16x32_bf16 v[110:113], v[146:149], v[178:181], v[110:113]
	v_mfma_f32_16x16x32_bf16 v[114:117], v[134:137], v[174:177], v[114:117]
	v_mfma_f32_16x16x32_bf16 v[114:117], v[138:141], v[178:181], v[114:117]
	v_mfma_f32_16x16x32_bf16 v[98:101], v[134:137], v[182:185], v[98:101]
	v_mfma_f32_16x16x32_bf16 v[98:101], v[138:141], v[186:189], v[98:101]
	v_mfma_f32_16x16x32_bf16 v[94:97], v[142:145], v[182:185], v[94:97]
	v_mfma_f32_16x16x32_bf16 v[94:97], v[146:149], v[186:189], v[94:97]
	v_mfma_f32_16x16x32_bf16 v[90:93], v[150:153], v[182:185], v[90:93]
	v_mfma_f32_16x16x32_bf16 v[90:93], v[154:157], v[186:189], v[90:93]
	v_mfma_f32_16x16x32_bf16 v[86:89], v[158:161], v[182:185], v[86:89]
	v_mfma_f32_16x16x32_bf16 v[86:89], v[162:165], v[186:189], v[86:89]
	v_mfma_f32_16x16x32_bf16 v[70:73], v[158:161], v[190:193], v[70:73]
	v_mfma_f32_16x16x32_bf16 v[70:73], v[162:165], v[194:197], v[70:73]
	v_mfma_f32_16x16x32_bf16 v[74:77], v[150:153], v[190:193], v[74:77]
	v_mfma_f32_16x16x32_bf16 v[74:77], v[154:157], v[194:197], v[74:77]
	v_mfma_f32_16x16x32_bf16 v[78:81], v[142:145], v[190:193], v[78:81]
	v_mfma_f32_16x16x32_bf16 v[78:81], v[146:149], v[194:197], v[78:81]
	v_mfma_f32_16x16x32_bf16 v[82:85], v[134:137], v[190:193], v[82:85]
	v_mfma_f32_16x16x32_bf16 v[82:85], v[138:141], v[194:197], v[82:85]
	s_setprio 0
	s_barrier
	s_mov_b32 m0, s64
	ds_read_b128 v[166:169], v233 offset:49152
	ds_read_b128 v[170:173], v233 offset:50176
	ds_read_b128 v[174:177], v233 offset:51200
	ds_read_b128 v[178:181], v233 offset:52224
	ds_read_b128 v[182:185], v233 offset:53248
	ds_read_b128 v[186:189], v233 offset:54272
	ds_read_b128 v[190:193], v233 offset:55296
	ds_read_b128 v[194:197], v233 offset:56320
	buffer_load_dwordx4 v231, s[16:19], s52 offen lds
	s_mov_b32 m0, s65
	s_add_i32 s52, s51, 0x18080
	buffer_load_dwordx4 v231, s[16:19], s52 offen lds
	s_add_i32 s52, s51, 0x30080
	s_mov_b32 m0, s68
	s_add_i32 s51, s51, 0x48080
	buffer_load_dwordx4 v231, s[16:19], s52 offen lds
	s_mov_b32 m0, s69
	s_nop 0
	buffer_load_dwordx4 v231, s[16:19], s51 offen lds
	s_mov_b32 m0, s66
	s_add_i32 s18, s92, 0x40080
	buffer_load_dwordx4 v230, s[12:15], s50 offen lds
	s_mov_b32 m0, s67
	s_nop 0
	buffer_load_dwordx4 v230, s[12:15], s18 offen lds
	s_waitcnt vmcnt(8) lgkmcnt(0)
	s_setprio 1
	s_barrier
	v_mfma_f32_16x16x32_bf16 v[66:69], v[134:137], v[166:169], v[66:69]
	v_mfma_f32_16x16x32_bf16 v[62:65], v[142:145], v[166:169], v[62:65]
	v_mfma_f32_16x16x32_bf16 v[50:53], v[134:137], v[174:177], v[50:53]
	v_mfma_f32_16x16x32_bf16 v[46:49], v[142:145], v[174:177], v[46:49]
	v_mfma_f32_16x16x32_bf16 v[34:37], v[134:137], v[182:185], v[34:37]
	v_mfma_f32_16x16x32_bf16 v[30:33], v[142:145], v[182:185], v[30:33]
	v_mfma_f32_16x16x32_bf16 v[18:21], v[134:137], v[190:193], v[18:21]
	v_mfma_f32_16x16x32_bf16 v[14:17], v[142:145], v[190:193], v[14:17]
	v_mfma_f32_16x16x32_bf16 v[58:61], v[150:153], v[166:169], v[58:61]
	v_mfma_f32_16x16x32_bf16 v[54:57], v[158:161], v[166:169], v[54:57]
	v_mfma_f32_16x16x32_bf16 v[42:45], v[150:153], v[174:177], v[42:45]
	v_mfma_f32_16x16x32_bf16 v[38:41], v[158:161], v[174:177], v[38:41]
	v_mfma_f32_16x16x32_bf16 v[26:29], v[150:153], v[182:185], v[26:29]
	v_mfma_f32_16x16x32_bf16 v[22:25], v[158:161], v[182:185], v[22:25]
	v_mfma_f32_16x16x32_bf16 v[8:11], v[150:153], v[190:193], v[10:13]
	v_mfma_f32_16x16x32_bf16 v[4:7], v[158:161], v[190:193], v[4:7]
	v_mfma_f32_16x16x32_bf16 v[66:69], v[138:141], v[170:173], v[66:69]
	v_mfma_f32_16x16x32_bf16 v[62:65], v[146:149], v[170:173], v[62:65]
	v_mfma_f32_16x16x32_bf16 v[50:53], v[138:141], v[178:181], v[50:53]
	v_mfma_f32_16x16x32_bf16 v[46:49], v[146:149], v[178:181], v[46:49]
	v_mfma_f32_16x16x32_bf16 v[34:37], v[138:141], v[186:189], v[34:37]
	v_mfma_f32_16x16x32_bf16 v[30:33], v[146:149], v[186:189], v[30:33]
	v_mfma_f32_16x16x32_bf16 v[18:21], v[138:141], v[194:197], v[18:21]
	v_mfma_f32_16x16x32_bf16 v[14:17], v[146:149], v[194:197], v[14:17]
	v_mfma_f32_16x16x32_bf16 v[58:61], v[154:157], v[170:173], v[58:61]
	v_mfma_f32_16x16x32_bf16 v[54:57], v[162:165], v[170:173], v[54:57]
	v_mfma_f32_16x16x32_bf16 v[42:45], v[154:157], v[178:181], v[42:45]
	v_mfma_f32_16x16x32_bf16 v[38:41], v[162:165], v[178:181], v[38:41]
	v_mfma_f32_16x16x32_bf16 v[26:29], v[154:157], v[186:189], v[26:29]
	v_mfma_f32_16x16x32_bf16 v[22:25], v[162:165], v[186:189], v[22:25]
	v_mfma_f32_16x16x32_bf16 v[10:13], v[154:157], v[194:197], v[8:11]
	v_mfma_f32_16x16x32_bf16 v[6:9], v[162:165], v[194:197], v[4:7]
	s_setprio 0
	s_barrier
	s_add_i32 s91, s91, 2
	s_addk_i32 s90, 0x100
	s_cmp_ge_i32 s91, s3
	s_cbranch_scc1 .LBB0_1193

.LBB0_1290:
	ds_read_b128 v[106:109], v224
	ds_read_b128 v[118:121], v224 offset:1024
	ds_read_b128 v[130:133], v224 offset:2048
	ds_read_b128 v[138:141], v224 offset:3072
	ds_read_b128 v[146:149], v225
	ds_read_b128 v[150:153], v225 offset:1024
	ds_read_b128 v[154:157], v225 offset:2048
	ds_read_b128 v[158:161], v225 offset:3072
	s_add_i32 s18, s72, 0xffe80080
	s_cmp_eq_u32 s56, s74
	s_cselect_b32 s75, s6, s18
	s_cselect_b32 s77, s7, s73
	s_or_b32 s76, s75, 0x80
	s_add_i32 s18, s72, 0xfff80000
	s_mov_b32 m0, s57
	ds_read_b128 v[162:165], v226
	ds_read_b128 v[166:169], v226 offset:1024
	ds_read_b128 v[170:173], v226 offset:2048
	ds_read_b128 v[174:177], v226 offset:3072
	ds_read_b128 v[178:181], v226 offset:4096
	ds_read_b128 v[182:185], v226 offset:5120
	ds_read_b128 v[190:193], v226 offset:6144
	ds_read_b128 v[194:197], v226 offset:7168
	buffer_load_dwordx4 v222, s[12:15], s18 offen lds
	s_mov_b32 m0, s60
	s_nop 0
	buffer_load_dwordx4 v222, s[12:15], s72 offen lds
	s_waitcnt vmcnt(8) lgkmcnt(0)
	s_setprio 1
	s_barrier
	v_mfma_f32_16x16x32_bf16 v[142:145], v[106:109], v[162:165], v[142:145]
	v_mfma_f32_16x16x32_bf16 v[142:145], v[118:121], v[166:169], v[142:145]
	v_mfma_f32_16x16x32_bf16 v[134:137], v[130:133], v[162:165], v[134:137]
	v_mfma_f32_16x16x32_bf16 v[134:137], v[138:141], v[166:169], v[134:137]
	v_mfma_f32_16x16x32_bf16 v[126:129], v[146:149], v[162:165], v[126:129]
	v_mfma_f32_16x16x32_bf16 v[126:129], v[150:153], v[166:169], v[126:129]
	v_mfma_f32_16x16x32_bf16 v[122:125], v[154:157], v[162:165], v[122:125]
	v_mfma_f32_16x16x32_bf16 v[122:125], v[158:161], v[166:169], v[122:125]
	v_mfma_f32_16x16x32_bf16 v[98:101], v[154:157], v[170:173], v[98:101]
	v_mfma_f32_16x16x32_bf16 v[98:101], v[158:161], v[174:177], v[98:101]
	v_mfma_f32_16x16x32_bf16 v[102:105], v[146:149], v[170:173], v[102:105]
	v_mfma_f32_16x16x32_bf16 v[102:105], v[150:153], v[174:177], v[102:105]
	v_mfma_f32_16x16x32_bf16 v[110:113], v[130:133], v[170:173], v[110:113]
	v_mfma_f32_16x16x32_bf16 v[110:113], v[138:141], v[174:177], v[110:113]
	v_mfma_f32_16x16x32_bf16 v[114:117], v[106:109], v[170:173], v[114:117]
	v_mfma_f32_16x16x32_bf16 v[114:117], v[118:121], v[174:177], v[114:117]
	v_mfma_f32_16x16x32_bf16 v[94:97], v[106:109], v[178:181], v[94:97]
	v_mfma_f32_16x16x32_bf16 v[94:97], v[118:121], v[182:185], v[94:97]
	v_mfma_f32_16x16x32_bf16 v[90:93], v[130:133], v[178:181], v[90:93]
	v_mfma_f32_16x16x32_bf16 v[90:93], v[138:141], v[182:185], v[90:93]
	v_mfma_f32_16x16x32_bf16 v[86:89], v[146:149], v[178:181], v[86:89]
	v_mfma_f32_16x16x32_bf16 v[86:89], v[150:153], v[182:185], v[86:89]
	v_mfma_f32_16x16x32_bf16 v[82:85], v[154:157], v[178:181], v[82:85]
	v_mfma_f32_16x16x32_bf16 v[82:85], v[158:161], v[182:185], v[82:85]
	v_mfma_f32_16x16x32_bf16 v[66:69], v[154:157], v[190:193], v[66:69]
	v_mfma_f32_16x16x32_bf16 v[66:69], v[158:161], v[194:197], v[66:69]
	v_mfma_f32_16x16x32_bf16 v[70:73], v[146:149], v[190:193], v[70:73]
	v_mfma_f32_16x16x32_bf16 v[70:73], v[150:153], v[194:197], v[70:73]
	v_mfma_f32_16x16x32_bf16 v[74:77], v[130:133], v[190:193], v[74:77]
	v_mfma_f32_16x16x32_bf16 v[74:77], v[138:141], v[194:197], v[74:77]
	v_mfma_f32_16x16x32_bf16 v[78:81], v[106:109], v[190:193], v[78:81]
	v_mfma_f32_16x16x32_bf16 v[78:81], v[118:121], v[194:197], v[78:81]
	s_setprio 0
	s_barrier
	s_mov_b32 m0, s27
	s_mov_b32 s18, s14
	s_mov_b32 s19, s15
	ds_read_b128 v[162:165], v226 offset:16384
	ds_read_b128 v[166:169], v226 offset:17408
	ds_read_b128 v[170:173], v226 offset:18432
	ds_read_b128 v[174:177], v226 offset:19456
	ds_read_b128 v[178:181], v226 offset:20480
	ds_read_b128 v[182:185], v226 offset:21504
	ds_read_b128 v[190:193], v226 offset:22528
	ds_read_b128 v[194:197], v226 offset:23552
	buffer_load_dwordx4 v223, s[16:19], s77 offen lds
	s_mov_b32 m0, s30
	s_add_i32 s78, s77, 0x80000
	buffer_load_dwordx4 v223, s[16:19], s78 offen lds
	s_mov_b32 m0, s31
	s_add_i32 s78, s77, 0x100000
	buffer_load_dwordx4 v223, s[16:19], s78 offen lds
	s_mov_b32 m0, s41
	s_add_i32 s78, s77, 0x180000
	buffer_load_dwordx4 v223, s[16:19], s78 offen lds
	s_mov_b32 m0, s25
	s_add_i32 s78, s75, 0x80000
	buffer_load_dwordx4 v222, s[12:15], s75 offen lds
	s_mov_b32 m0, s42
	s_nop 0
	buffer_load_dwordx4 v222, s[12:15], s78 offen lds
	s_waitcnt vmcnt(8) lgkmcnt(0)
	s_setprio 1
	s_barrier
	v_mfma_f32_16x16x32_bf16 v[62:65], v[106:109], v[162:165], v[62:65]
	v_mfma_f32_16x16x32_bf16 v[62:65], v[118:121], v[166:169], v[62:65]
	v_mfma_f32_16x16x32_bf16 v[58:61], v[130:133], v[162:165], v[58:61]
	v_mfma_f32_16x16x32_bf16 v[58:61], v[138:141], v[166:169], v[58:61]
	v_mfma_f32_16x16x32_bf16 v[54:57], v[146:149], v[162:165], v[54:57]
	v_mfma_f32_16x16x32_bf16 v[54:57], v[150:153], v[166:169], v[54:57]
	v_mfma_f32_16x16x32_bf16 v[50:53], v[154:157], v[162:165], v[50:53]
	v_mfma_f32_16x16x32_bf16 v[50:53], v[158:161], v[166:169], v[50:53]
	v_mfma_f32_16x16x32_bf16 v[34:37], v[154:157], v[170:173], v[34:37]
	v_mfma_f32_16x16x32_bf16 v[34:37], v[158:161], v[174:177], v[34:37]
	v_mfma_f32_16x16x32_bf16 v[38:41], v[146:149], v[170:173], v[38:41]
	v_mfma_f32_16x16x32_bf16 v[38:41], v[150:153], v[174:177], v[38:41]
	v_mfma_f32_16x16x32_bf16 v[42:45], v[130:133], v[170:173], v[42:45]
	v_mfma_f32_16x16x32_bf16 v[42:45], v[138:141], v[174:177], v[42:45]
	v_mfma_f32_16x16x32_bf16 v[46:49], v[106:109], v[170:173], v[46:49]
	v_mfma_f32_16x16x32_bf16 v[46:49], v[118:121], v[174:177], v[46:49]
	v_mfma_f32_16x16x32_bf16 v[30:33], v[106:109], v[178:181], v[30:33]
	v_mfma_f32_16x16x32_bf16 v[30:33], v[118:121], v[182:185], v[30:33]
	v_mfma_f32_16x16x32_bf16 v[26:29], v[130:133], v[178:181], v[26:29]
	v_mfma_f32_16x16x32_bf16 v[26:29], v[138:141], v[182:185], v[26:29]
	v_mfma_f32_16x16x32_bf16 v[22:25], v[146:149], v[178:181], v[22:25]
	v_mfma_f32_16x16x32_bf16 v[22:25], v[150:153], v[182:185], v[22:25]
	v_mfma_f32_16x16x32_bf16 v[18:21], v[154:157], v[178:181], v[18:21]
	v_mfma_f32_16x16x32_bf16 v[18:21], v[158:161], v[182:185], v[18:21]
	v_mfma_f32_16x16x32_bf16 v[2:5], v[154:157], v[190:193], v[2:5]
	v_mfma_f32_16x16x32_bf16 v[2:5], v[158:161], v[194:197], v[2:5]
	v_mfma_f32_16x16x32_bf16 v[6:9], v[146:149], v[190:193], v[6:9]
	v_mfma_f32_16x16x32_bf16 v[6:9], v[150:153], v[194:197], v[6:9]
	v_mfma_f32_16x16x32_bf16 v[10:13], v[130:133], v[190:193], v[10:13]
	v_mfma_f32_16x16x32_bf16 v[10:13], v[138:141], v[194:197], v[10:13]
	v_mfma_f32_16x16x32_bf16 v[14:17], v[106:109], v[190:193], v[14:17]
	v_mfma_f32_16x16x32_bf16 v[14:17], v[118:121], v[194:197], v[14:17]
	s_setprio 0
	s_barrier
	ds_read_b128 v[106:109], v227
	ds_read_b128 v[118:121], v227 offset:1024
	ds_read_b128 v[130:133], v227 offset:2048
	ds_read_b128 v[138:141], v227 offset:3072
	ds_read_b128 v[146:149], v228
	ds_read_b128 v[150:153], v228 offset:1024
	ds_read_b128 v[154:157], v228 offset:2048
	ds_read_b128 v[158:161], v228 offset:3072
	s_mov_b32 m0, s43
	s_add_i32 s78, s75, 0x100000
	ds_read_b128 v[162:165], v226 offset:32768
	ds_read_b128 v[166:169], v226 offset:33792
	ds_read_b128 v[170:173], v226 offset:34816
	ds_read_b128 v[174:177], v226 offset:35840
	ds_read_b128 v[178:181], v226 offset:36864
	ds_read_b128 v[182:185], v226 offset:37888
	ds_read_b128 v[190:193], v226 offset:38912
	ds_read_b128 v[194:197], v226 offset:39936
	buffer_load_dwordx4 v222, s[12:15], s78 offen lds
	s_mov_b32 m0, s44
	s_add_i32 s78, s75, 0x180000
	buffer_load_dwordx4 v222, s[12:15], s78 offen lds
	s_waitcnt vmcnt(8) lgkmcnt(0)
	s_setprio 1
	s_barrier
	v_mfma_f32_16x16x32_bf16 v[142:145], v[106:109], v[162:165], v[142:145]
	v_mfma_f32_16x16x32_bf16 v[142:145], v[118:121], v[166:169], v[142:145]
	v_mfma_f32_16x16x32_bf16 v[134:137], v[130:133], v[162:165], v[134:137]
	v_mfma_f32_16x16x32_bf16 v[134:137], v[138:141], v[166:169], v[134:137]
	v_mfma_f32_16x16x32_bf16 v[126:129], v[146:149], v[162:165], v[126:129]
	v_mfma_f32_16x16x32_bf16 v[126:129], v[150:153], v[166:169], v[126:129]
	v_mfma_f32_16x16x32_bf16 v[122:125], v[154:157], v[162:165], v[122:125]
	v_mfma_f32_16x16x32_bf16 v[122:125], v[158:161], v[166:169], v[122:125]
	v_mfma_f32_16x16x32_bf16 v[98:101], v[154:157], v[170:173], v[98:101]
	v_mfma_f32_16x16x32_bf16 v[98:101], v[158:161], v[174:177], v[98:101]
	v_mfma_f32_16x16x32_bf16 v[102:105], v[146:149], v[170:173], v[102:105]
	v_mfma_f32_16x16x32_bf16 v[102:105], v[150:153], v[174:177], v[102:105]
	v_mfma_f32_16x16x32_bf16 v[110:113], v[130:133], v[170:173], v[110:113]
	v_mfma_f32_16x16x32_bf16 v[110:113], v[138:141], v[174:177], v[110:113]
	v_mfma_f32_16x16x32_bf16 v[114:117], v[106:109], v[170:173], v[114:117]
	v_mfma_f32_16x16x32_bf16 v[114:117], v[118:121], v[174:177], v[114:117]
	v_mfma_f32_16x16x32_bf16 v[94:97], v[106:109], v[178:181], v[94:97]
	v_mfma_f32_16x16x32_bf16 v[94:97], v[118:121], v[182:185], v[94:97]
	v_mfma_f32_16x16x32_bf16 v[90:93], v[130:133], v[178:181], v[90:93]
	v_mfma_f32_16x16x32_bf16 v[90:93], v[138:141], v[182:185], v[90:93]
	v_mfma_f32_16x16x32_bf16 v[86:89], v[146:149], v[178:181], v[86:89]
	v_mfma_f32_16x16x32_bf16 v[86:89], v[150:153], v[182:185], v[86:89]
	v_mfma_f32_16x16x32_bf16 v[82:85], v[154:157], v[178:181], v[82:85]
	v_mfma_f32_16x16x32_bf16 v[82:85], v[158:161], v[182:185], v[82:85]
	v_mfma_f32_16x16x32_bf16 v[66:69], v[154:157], v[190:193], v[66:69]
	v_mfma_f32_16x16x32_bf16 v[66:69], v[158:161], v[194:197], v[66:69]
	v_mfma_f32_16x16x32_bf16 v[70:73], v[146:149], v[190:193], v[70:73]
	v_mfma_f32_16x16x32_bf16 v[70:73], v[150:153], v[194:197], v[70:73]
	v_mfma_f32_16x16x32_bf16 v[74:77], v[130:133], v[190:193], v[74:77]
	v_mfma_f32_16x16x32_bf16 v[74:77], v[138:141], v[194:197], v[74:77]
	v_mfma_f32_16x16x32_bf16 v[78:81], v[106:109], v[190:193], v[78:81]
	v_mfma_f32_16x16x32_bf16 v[78:81], v[118:121], v[194:197], v[78:81]
	s_setprio 0
	s_barrier
	s_mov_b32 m0, s48
	s_or_b32 s78, s77, 0x80
	ds_read_b128 v[162:165], v226 offset:49152
	ds_read_b128 v[166:169], v226 offset:50176
	ds_read_b128 v[170:173], v226 offset:51200
	ds_read_b128 v[174:177], v226 offset:52224
	ds_read_b128 v[178:181], v226 offset:53248
	ds_read_b128 v[182:185], v226 offset:54272
	ds_read_b128 v[190:193], v226 offset:55296
	ds_read_b128 v[194:197], v226 offset:56320
	buffer_load_dwordx4 v223, s[16:19], s78 offen lds
	s_add_i32 s78, s77, 0x80080
	s_mov_b32 m0, s49
	s_add_i32 s75, s75, 0x80080
	buffer_load_dwordx4 v223, s[16:19], s78 offen lds
	s_add_i32 s78, s77, 0x100080
	s_mov_b32 m0, s52
	s_add_i32 s77, s77, 0x180080
	buffer_load_dwordx4 v223, s[16:19], s78 offen lds
	s_mov_b32 m0, s53
	s_nop 0
	buffer_load_dwordx4 v223, s[16:19], s77 offen lds
	s_mov_b32 m0, s50
	s_nop 0
	buffer_load_dwordx4 v222, s[12:15], s76 offen lds
	s_mov_b32 m0, s51
	s_nop 0
	buffer_load_dwordx4 v222, s[12:15], s75 offen lds
	s_waitcnt vmcnt(8) lgkmcnt(0)
	s_setprio 1
	s_barrier
	v_mfma_f32_16x16x32_bf16 v[62:65], v[106:109], v[162:165], v[62:65]
	v_mfma_f32_16x16x32_bf16 v[62:65], v[118:121], v[166:169], v[62:65]
	v_mfma_f32_16x16x32_bf16 v[58:61], v[130:133], v[162:165], v[58:61]
	v_mfma_f32_16x16x32_bf16 v[58:61], v[138:141], v[166:169], v[58:61]
	v_mfma_f32_16x16x32_bf16 v[54:57], v[146:149], v[162:165], v[54:57]
	v_mfma_f32_16x16x32_bf16 v[54:57], v[150:153], v[166:169], v[54:57]
	v_mfma_f32_16x16x32_bf16 v[50:53], v[154:157], v[162:165], v[50:53]
	v_mfma_f32_16x16x32_bf16 v[50:53], v[158:161], v[166:169], v[50:53]
	v_mfma_f32_16x16x32_bf16 v[34:37], v[154:157], v[170:173], v[34:37]
	v_mfma_f32_16x16x32_bf16 v[34:37], v[158:161], v[174:177], v[34:37]
	v_mfma_f32_16x16x32_bf16 v[38:41], v[146:149], v[170:173], v[38:41]
	v_mfma_f32_16x16x32_bf16 v[38:41], v[150:153], v[174:177], v[38:41]
	v_mfma_f32_16x16x32_bf16 v[42:45], v[130:133], v[170:173], v[42:45]
	v_mfma_f32_16x16x32_bf16 v[42:45], v[138:141], v[174:177], v[42:45]
	v_mfma_f32_16x16x32_bf16 v[46:49], v[106:109], v[170:173], v[46:49]
	v_mfma_f32_16x16x32_bf16 v[46:49], v[118:121], v[174:177], v[46:49]
	v_mfma_f32_16x16x32_bf16 v[30:33], v[106:109], v[178:181], v[30:33]
	v_mfma_f32_16x16x32_bf16 v[30:33], v[118:121], v[182:185], v[30:33]
	v_mfma_f32_16x16x32_bf16 v[26:29], v[130:133], v[178:181], v[26:29]
	v_mfma_f32_16x16x32_bf16 v[26:29], v[138:141], v[182:185], v[26:29]
	v_mfma_f32_16x16x32_bf16 v[22:25], v[146:149], v[178:181], v[22:25]
	v_mfma_f32_16x16x32_bf16 v[22:25], v[150:153], v[182:185], v[22:25]
	v_mfma_f32_16x16x32_bf16 v[18:21], v[154:157], v[178:181], v[18:21]
	v_mfma_f32_16x16x32_bf16 v[18:21], v[158:161], v[182:185], v[18:21]
	v_mfma_f32_16x16x32_bf16 v[2:5], v[154:157], v[190:193], v[2:5]
	v_mfma_f32_16x16x32_bf16 v[2:5], v[158:161], v[194:197], v[2:5]
	v_mfma_f32_16x16x32_bf16 v[6:9], v[146:149], v[190:193], v[6:9]
	v_mfma_f32_16x16x32_bf16 v[6:9], v[150:153], v[194:197], v[6:9]
	v_mfma_f32_16x16x32_bf16 v[10:13], v[130:133], v[190:193], v[10:13]
	v_mfma_f32_16x16x32_bf16 v[10:13], v[138:141], v[194:197], v[10:13]
	v_mfma_f32_16x16x32_bf16 v[14:17], v[106:109], v[190:193], v[14:17]
	v_mfma_f32_16x16x32_bf16 v[14:17], v[118:121], v[194:197], v[14:17]
	s_setprio 0
	s_barrier
	s_add_i32 s74, s74, 2
	s_addk_i32 s72, 0x100
	s_addk_i32 s73, 0x100
	s_cmp_ge_i32 s74, s3
	s_cbranch_scc0 .LBB0_1290
	s_and_b64 vcc, exec, s[38:39]
	s_cbranch_vccz .LBB0_1293

.LBB0_1382:
	ds_read_b128 v[144:147], v138
	ds_read_b128 v[148:151], v138 offset:1024
	ds_read_b128 v[152:155], v138 offset:2048
	ds_read_b128 v[156:159], v138 offset:3072
	ds_read_b128 v[160:163], v139
	ds_read_b128 v[164:167], v139 offset:1024
	ds_read_b128 v[168:171], v139 offset:2048
	ds_read_b128 v[172:175], v139 offset:3072
	s_add_i32 s14, s74, 0xffe80080
	s_cmp_eq_u32 s61, s76
	s_cselect_b32 s77, s72, s14
	s_cselect_b32 s79, s73, s75
	s_or_b32 s78, s77, 0x80
	s_add_i32 s14, s74, 0xfff80000
	s_mov_b32 m0, s62
	ds_read_b128 v[176:179], v140
	ds_read_b128 v[180:183], v140 offset:1024
	ds_read_b128 v[184:187], v140 offset:2048
	ds_read_b128 v[188:191], v140 offset:3072
	ds_read_b128 v[192:195], v140 offset:4096
	ds_read_b128 v[196:199], v140 offset:5120
	ds_read_b128 v[200:203], v140 offset:6144
	ds_read_b128 v[204:207], v140 offset:7168
	buffer_load_dwordx4 v136, s[16:19], s14 offen lds
	s_mov_b32 m0, s63
	s_nop 0
	buffer_load_dwordx4 v136, s[16:19], s74 offen lds
	s_waitcnt vmcnt(8) lgkmcnt(0)
	s_setprio 1
	s_barrier
	v_mfma_f32_16x16x32_bf16 v[118:121], v[144:147], v[176:179], v[118:121]
	v_mfma_f32_16x16x32_bf16 v[118:121], v[148:151], v[180:183], v[118:121]
	v_mfma_f32_16x16x32_bf16 v[114:117], v[152:155], v[176:179], v[114:117]
	v_mfma_f32_16x16x32_bf16 v[114:117], v[156:159], v[180:183], v[114:117]
	v_mfma_f32_16x16x32_bf16 v[126:129], v[160:163], v[176:179], v[126:129]
	v_mfma_f32_16x16x32_bf16 v[126:129], v[164:167], v[180:183], v[126:129]
	v_mfma_f32_16x16x32_bf16 v[122:125], v[168:171], v[176:179], v[122:125]
	v_mfma_f32_16x16x32_bf16 v[122:125], v[172:175], v[180:183], v[122:125]
	v_mfma_f32_16x16x32_bf16 v[98:101], v[168:171], v[184:187], v[98:101]
	v_mfma_f32_16x16x32_bf16 v[98:101], v[172:175], v[188:191], v[98:101]
	v_mfma_f32_16x16x32_bf16 v[106:109], v[160:163], v[184:187], v[106:109]
	v_mfma_f32_16x16x32_bf16 v[106:109], v[164:167], v[188:191], v[106:109]
	v_mfma_f32_16x16x32_bf16 v[102:105], v[152:155], v[184:187], v[102:105]
	v_mfma_f32_16x16x32_bf16 v[102:105], v[156:159], v[188:191], v[102:105]
	v_mfma_f32_16x16x32_bf16 v[110:113], v[144:147], v[184:187], v[110:113]
	v_mfma_f32_16x16x32_bf16 v[110:113], v[148:151], v[188:191], v[110:113]
	v_mfma_f32_16x16x32_bf16 v[94:97], v[144:147], v[192:195], v[94:97]
	v_mfma_f32_16x16x32_bf16 v[94:97], v[148:151], v[196:199], v[94:97]
	v_mfma_f32_16x16x32_bf16 v[86:89], v[152:155], v[192:195], v[86:89]
	v_mfma_f32_16x16x32_bf16 v[86:89], v[156:159], v[196:199], v[86:89]
	v_mfma_f32_16x16x32_bf16 v[90:93], v[160:163], v[192:195], v[90:93]
	v_mfma_f32_16x16x32_bf16 v[90:93], v[164:167], v[196:199], v[90:93]
	v_mfma_f32_16x16x32_bf16 v[82:85], v[168:171], v[192:195], v[82:85]
	v_mfma_f32_16x16x32_bf16 v[82:85], v[172:175], v[196:199], v[82:85]
	v_mfma_f32_16x16x32_bf16 v[70:73], v[168:171], v[200:203], v[70:73]
	v_mfma_f32_16x16x32_bf16 v[70:73], v[172:175], v[204:207], v[70:73]
	v_mfma_f32_16x16x32_bf16 v[74:77], v[160:163], v[200:203], v[74:77]
	v_mfma_f32_16x16x32_bf16 v[74:77], v[164:167], v[204:207], v[74:77]
	v_mfma_f32_16x16x32_bf16 v[66:69], v[152:155], v[200:203], v[66:69]
	v_mfma_f32_16x16x32_bf16 v[66:69], v[156:159], v[204:207], v[66:69]
	v_mfma_f32_16x16x32_bf16 v[78:81], v[144:147], v[200:203], v[78:81]
	v_mfma_f32_16x16x32_bf16 v[78:81], v[148:151], v[204:207], v[78:81]
	s_setprio 0
	s_barrier
	s_mov_b32 m0, s45
	s_mov_b32 s14, s18
	s_mov_b32 s15, s19
	ds_read_b128 v[176:179], v140 offset:16384
	ds_read_b128 v[180:183], v140 offset:17408
	ds_read_b128 v[184:187], v140 offset:18432
	ds_read_b128 v[188:191], v140 offset:19456
	ds_read_b128 v[192:195], v140 offset:20480
	ds_read_b128 v[196:199], v140 offset:21504
	ds_read_b128 v[200:203], v140 offset:22528
	ds_read_b128 v[204:207], v140 offset:23552
	buffer_load_dwordx4 v137, s[12:15], s79 offen lds
	s_mov_b32 m0, s46
	s_add_i32 s80, s79, 0x80000
	buffer_load_dwordx4 v137, s[12:15], s80 offen lds
	s_mov_b32 m0, s47
	s_add_i32 s80, s79, 0x100000
	buffer_load_dwordx4 v137, s[12:15], s80 offen lds
	s_mov_b32 m0, s48
	s_add_i32 s80, s79, 0x180000
	buffer_load_dwordx4 v137, s[12:15], s80 offen lds
	s_mov_b32 m0, s44
	s_add_i32 s80, s77, 0x80000
	buffer_load_dwordx4 v136, s[16:19], s77 offen lds
	s_mov_b32 m0, s49
	s_nop 0
	buffer_load_dwordx4 v136, s[16:19], s80 offen lds
	s_waitcnt vmcnt(8) lgkmcnt(0)
	s_setprio 1
	s_barrier
	v_mfma_f32_16x16x32_bf16 v[62:65], v[144:147], v[176:179], v[62:65]
	v_mfma_f32_16x16x32_bf16 v[62:65], v[148:151], v[180:183], v[62:65]
	v_mfma_f32_16x16x32_bf16 v[54:57], v[152:155], v[176:179], v[54:57]
	v_mfma_f32_16x16x32_bf16 v[54:57], v[156:159], v[180:183], v[54:57]
	v_mfma_f32_16x16x32_bf16 v[58:61], v[160:163], v[176:179], v[58:61]
	v_mfma_f32_16x16x32_bf16 v[58:61], v[164:167], v[180:183], v[58:61]
	v_mfma_f32_16x16x32_bf16 v[50:53], v[168:171], v[176:179], v[50:53]
	v_mfma_f32_16x16x32_bf16 v[50:53], v[172:175], v[180:183], v[50:53]
	v_mfma_f32_16x16x32_bf16 v[34:37], v[168:171], v[184:187], v[34:37]
	v_mfma_f32_16x16x32_bf16 v[34:37], v[172:175], v[188:191], v[34:37]
	v_mfma_f32_16x16x32_bf16 v[42:45], v[160:163], v[184:187], v[42:45]
	v_mfma_f32_16x16x32_bf16 v[42:45], v[164:167], v[188:191], v[42:45]
	v_mfma_f32_16x16x32_bf16 v[38:41], v[152:155], v[184:187], v[38:41]
	v_mfma_f32_16x16x32_bf16 v[38:41], v[156:159], v[188:191], v[38:41]
	v_mfma_f32_16x16x32_bf16 v[46:49], v[144:147], v[184:187], v[46:49]
	v_mfma_f32_16x16x32_bf16 v[46:49], v[148:151], v[188:191], v[46:49]
	v_mfma_f32_16x16x32_bf16 v[30:33], v[144:147], v[192:195], v[30:33]
	v_mfma_f32_16x16x32_bf16 v[30:33], v[148:151], v[196:199], v[30:33]
	v_mfma_f32_16x16x32_bf16 v[22:25], v[152:155], v[192:195], v[22:25]
	v_mfma_f32_16x16x32_bf16 v[22:25], v[156:159], v[196:199], v[22:25]
	v_mfma_f32_16x16x32_bf16 v[26:29], v[160:163], v[192:195], v[26:29]
	v_mfma_f32_16x16x32_bf16 v[26:29], v[164:167], v[196:199], v[26:29]
	v_mfma_f32_16x16x32_bf16 v[18:21], v[168:171], v[192:195], v[18:21]
	v_mfma_f32_16x16x32_bf16 v[18:21], v[172:175], v[196:199], v[18:21]
	v_mfma_f32_16x16x32_bf16 v[2:5], v[168:171], v[200:203], v[2:5]
	v_mfma_f32_16x16x32_bf16 v[2:5], v[172:175], v[204:207], v[2:5]
	v_mfma_f32_16x16x32_bf16 v[10:13], v[160:163], v[200:203], v[10:13]
	v_mfma_f32_16x16x32_bf16 v[10:13], v[164:167], v[204:207], v[10:13]
	v_mfma_f32_16x16x32_bf16 v[6:9], v[152:155], v[200:203], v[6:9]
	v_mfma_f32_16x16x32_bf16 v[6:9], v[156:159], v[204:207], v[6:9]
	v_mfma_f32_16x16x32_bf16 v[14:17], v[144:147], v[200:203], v[14:17]
	v_mfma_f32_16x16x32_bf16 v[14:17], v[148:151], v[204:207], v[14:17]
	s_setprio 0
	s_barrier
	ds_read_b128 v[144:147], v141
	ds_read_b128 v[148:151], v141 offset:1024
	ds_read_b128 v[152:155], v141 offset:2048
	ds_read_b128 v[156:159], v141 offset:3072
	ds_read_b128 v[160:163], v142
	ds_read_b128 v[164:167], v142 offset:1024
	ds_read_b128 v[168:171], v142 offset:2048
	ds_read_b128 v[172:175], v142 offset:3072
	s_mov_b32 m0, s50
	s_add_i32 s80, s77, 0x100000
	ds_read_b128 v[176:179], v140 offset:32768
	ds_read_b128 v[180:183], v140 offset:33792
	ds_read_b128 v[184:187], v140 offset:34816
	ds_read_b128 v[188:191], v140 offset:35840
	ds_read_b128 v[192:195], v140 offset:36864
	ds_read_b128 v[196:199], v140 offset:37888
	ds_read_b128 v[200:203], v140 offset:38912
	ds_read_b128 v[204:207], v140 offset:39936
	buffer_load_dwordx4 v136, s[16:19], s80 offen lds
	s_mov_b32 m0, s51
	s_add_i32 s80, s77, 0x180000
	buffer_load_dwordx4 v136, s[16:19], s80 offen lds
	s_waitcnt vmcnt(8) lgkmcnt(0)
	s_setprio 1
	s_barrier
	v_mfma_f32_16x16x32_bf16 v[118:121], v[144:147], v[176:179], v[118:121]
	v_mfma_f32_16x16x32_bf16 v[118:121], v[148:151], v[180:183], v[118:121]
	v_mfma_f32_16x16x32_bf16 v[114:117], v[152:155], v[176:179], v[114:117]
	v_mfma_f32_16x16x32_bf16 v[114:117], v[156:159], v[180:183], v[114:117]
	v_mfma_f32_16x16x32_bf16 v[126:129], v[160:163], v[176:179], v[126:129]
	v_mfma_f32_16x16x32_bf16 v[126:129], v[164:167], v[180:183], v[126:129]
	v_mfma_f32_16x16x32_bf16 v[122:125], v[168:171], v[176:179], v[122:125]
	v_mfma_f32_16x16x32_bf16 v[122:125], v[172:175], v[180:183], v[122:125]
	v_mfma_f32_16x16x32_bf16 v[98:101], v[168:171], v[184:187], v[98:101]
	v_mfma_f32_16x16x32_bf16 v[98:101], v[172:175], v[188:191], v[98:101]
	v_mfma_f32_16x16x32_bf16 v[106:109], v[160:163], v[184:187], v[106:109]
	v_mfma_f32_16x16x32_bf16 v[106:109], v[164:167], v[188:191], v[106:109]
	v_mfma_f32_16x16x32_bf16 v[102:105], v[152:155], v[184:187], v[102:105]
	v_mfma_f32_16x16x32_bf16 v[102:105], v[156:159], v[188:191], v[102:105]
	v_mfma_f32_16x16x32_bf16 v[110:113], v[144:147], v[184:187], v[110:113]
	v_mfma_f32_16x16x32_bf16 v[110:113], v[148:151], v[188:191], v[110:113]
	v_mfma_f32_16x16x32_bf16 v[94:97], v[144:147], v[192:195], v[94:97]
	v_mfma_f32_16x16x32_bf16 v[94:97], v[148:151], v[196:199], v[94:97]
	v_mfma_f32_16x16x32_bf16 v[86:89], v[152:155], v[192:195], v[86:89]
	v_mfma_f32_16x16x32_bf16 v[86:89], v[156:159], v[196:199], v[86:89]
	v_mfma_f32_16x16x32_bf16 v[90:93], v[160:163], v[192:195], v[90:93]
	v_mfma_f32_16x16x32_bf16 v[90:93], v[164:167], v[196:199], v[90:93]
	v_mfma_f32_16x16x32_bf16 v[82:85], v[168:171], v[192:195], v[82:85]
	v_mfma_f32_16x16x32_bf16 v[82:85], v[172:175], v[196:199], v[82:85]
	v_mfma_f32_16x16x32_bf16 v[70:73], v[168:171], v[200:203], v[70:73]
	v_mfma_f32_16x16x32_bf16 v[70:73], v[172:175], v[204:207], v[70:73]
	v_mfma_f32_16x16x32_bf16 v[74:77], v[160:163], v[200:203], v[74:77]
	v_mfma_f32_16x16x32_bf16 v[74:77], v[164:167], v[204:207], v[74:77]
	v_mfma_f32_16x16x32_bf16 v[66:69], v[152:155], v[200:203], v[66:69]
	v_mfma_f32_16x16x32_bf16 v[66:69], v[156:159], v[204:207], v[66:69]
	v_mfma_f32_16x16x32_bf16 v[78:81], v[144:147], v[200:203], v[78:81]
	v_mfma_f32_16x16x32_bf16 v[78:81], v[148:151], v[204:207], v[78:81]
	s_setprio 0
	s_barrier
	s_mov_b32 m0, s53
	s_or_b32 s80, s79, 0x80
	ds_read_b128 v[176:179], v140 offset:49152
	ds_read_b128 v[180:183], v140 offset:50176
	ds_read_b128 v[184:187], v140 offset:51200
	ds_read_b128 v[188:191], v140 offset:52224
	ds_read_b128 v[192:195], v140 offset:53248
	ds_read_b128 v[196:199], v140 offset:54272
	ds_read_b128 v[200:203], v140 offset:55296
	ds_read_b128 v[204:207], v140 offset:56320
	buffer_load_dwordx4 v137, s[12:15], s80 offen lds
	s_add_i32 s80, s79, 0x80080
	s_mov_b32 m0, s54
	s_add_i32 s77, s77, 0x80080
	buffer_load_dwordx4 v137, s[12:15], s80 offen lds
	s_add_i32 s80, s79, 0x100080
	s_mov_b32 m0, s57
	s_add_i32 s79, s79, 0x180080
	buffer_load_dwordx4 v137, s[12:15], s80 offen lds
	s_mov_b32 m0, s58
	s_nop 0
	buffer_load_dwordx4 v137, s[12:15], s79 offen lds
	s_mov_b32 m0, s55
	s_nop 0
	buffer_load_dwordx4 v136, s[16:19], s78 offen lds
	s_mov_b32 m0, s56
	s_nop 0
	buffer_load_dwordx4 v136, s[16:19], s77 offen lds
	s_waitcnt vmcnt(8) lgkmcnt(0)
	s_setprio 1
	s_barrier
	v_mfma_f32_16x16x32_bf16 v[62:65], v[144:147], v[176:179], v[62:65]
	v_mfma_f32_16x16x32_bf16 v[62:65], v[148:151], v[180:183], v[62:65]
	v_mfma_f32_16x16x32_bf16 v[54:57], v[152:155], v[176:179], v[54:57]
	v_mfma_f32_16x16x32_bf16 v[54:57], v[156:159], v[180:183], v[54:57]
	v_mfma_f32_16x16x32_bf16 v[58:61], v[160:163], v[176:179], v[58:61]
	v_mfma_f32_16x16x32_bf16 v[58:61], v[164:167], v[180:183], v[58:61]
	v_mfma_f32_16x16x32_bf16 v[50:53], v[168:171], v[176:179], v[50:53]
	v_mfma_f32_16x16x32_bf16 v[50:53], v[172:175], v[180:183], v[50:53]
	v_mfma_f32_16x16x32_bf16 v[34:37], v[168:171], v[184:187], v[34:37]
	v_mfma_f32_16x16x32_bf16 v[34:37], v[172:175], v[188:191], v[34:37]
	v_mfma_f32_16x16x32_bf16 v[42:45], v[160:163], v[184:187], v[42:45]
	v_mfma_f32_16x16x32_bf16 v[42:45], v[164:167], v[188:191], v[42:45]
	v_mfma_f32_16x16x32_bf16 v[38:41], v[152:155], v[184:187], v[38:41]
	v_mfma_f32_16x16x32_bf16 v[38:41], v[156:159], v[188:191], v[38:41]
	v_mfma_f32_16x16x32_bf16 v[46:49], v[144:147], v[184:187], v[46:49]
	v_mfma_f32_16x16x32_bf16 v[46:49], v[148:151], v[188:191], v[46:49]
	v_mfma_f32_16x16x32_bf16 v[30:33], v[144:147], v[192:195], v[30:33]
	v_mfma_f32_16x16x32_bf16 v[30:33], v[148:151], v[196:199], v[30:33]
	v_mfma_f32_16x16x32_bf16 v[22:25], v[152:155], v[192:195], v[22:25]
	v_mfma_f32_16x16x32_bf16 v[22:25], v[156:159], v[196:199], v[22:25]
	v_mfma_f32_16x16x32_bf16 v[26:29], v[160:163], v[192:195], v[26:29]
	v_mfma_f32_16x16x32_bf16 v[26:29], v[164:167], v[196:199], v[26:29]
	v_mfma_f32_16x16x32_bf16 v[18:21], v[168:171], v[192:195], v[18:21]
	v_mfma_f32_16x16x32_bf16 v[18:21], v[172:175], v[196:199], v[18:21]
	v_mfma_f32_16x16x32_bf16 v[2:5], v[168:171], v[200:203], v[2:5]
	v_mfma_f32_16x16x32_bf16 v[2:5], v[172:175], v[204:207], v[2:5]
	v_mfma_f32_16x16x32_bf16 v[10:13], v[160:163], v[200:203], v[10:13]
	v_mfma_f32_16x16x32_bf16 v[10:13], v[164:167], v[204:207], v[10:13]
	v_mfma_f32_16x16x32_bf16 v[6:9], v[152:155], v[200:203], v[6:9]
	v_mfma_f32_16x16x32_bf16 v[6:9], v[156:159], v[204:207], v[6:9]
	v_mfma_f32_16x16x32_bf16 v[14:17], v[144:147], v[200:203], v[14:17]
	v_mfma_f32_16x16x32_bf16 v[14:17], v[148:151], v[204:207], v[14:17]
	s_setprio 0
	s_barrier
	s_add_i32 s76, s76, 2
	s_addk_i32 s74, 0x100
	s_addk_i32 s75, 0x100
	s_cmp_ge_i32 s76, s27
	s_cbranch_scc0 .LBB0_1382
	s_and_b64 vcc, exec, s[42:43]
	s_cbranch_vccz .LBB0_1385

.LBB0_1402:
	ds_read_b128 v[146:149], v138
	ds_read_b128 v[150:153], v138 offset:1024
	ds_read_b128 v[154:157], v138 offset:2048
	ds_read_b128 v[158:161], v138 offset:3072
	ds_read_b128 v[162:165], v139
	ds_read_b128 v[166:169], v139 offset:1024
	ds_read_b128 v[170:173], v139 offset:2048
	ds_read_b128 v[174:177], v139 offset:3072
	s_add_i32 s22, s75, 0xffe80080
	s_cmp_eq_u32 s62, s77
	s_cselect_b32 s78, s73, s22
	s_cselect_b32 s80, s74, s76
	s_or_b32 s79, s78, 0x80
	s_add_i32 s22, s75, 0xfff80000
	s_mov_b32 m0, s63
	ds_read_b128 v[178:181], v140
	ds_read_b128 v[182:185], v140 offset:1024
	ds_read_b128 v[186:189], v140 offset:2048
	ds_read_b128 v[190:193], v140 offset:3072
	ds_read_b128 v[194:197], v140 offset:4096
	ds_read_b128 v[198:201], v140 offset:5120
	ds_read_b128 v[202:205], v140 offset:6144
	ds_read_b128 v[206:209], v140 offset:7168
	buffer_load_dwordx4 v136, s[16:19], s22 offen lds
	s_mov_b32 m0, s64
	s_nop 0
	buffer_load_dwordx4 v136, s[16:19], s75 offen lds
	s_waitcnt vmcnt(8) lgkmcnt(0)
	s_setprio 1
	s_barrier
	v_mfma_f32_16x16x32_bf16 v[118:121], v[146:149], v[178:181], v[118:121]
	v_mfma_f32_16x16x32_bf16 v[118:121], v[150:153], v[182:185], v[118:121]
	v_mfma_f32_16x16x32_bf16 v[114:117], v[154:157], v[178:181], v[114:117]
	v_mfma_f32_16x16x32_bf16 v[114:117], v[158:161], v[182:185], v[114:117]
	v_mfma_f32_16x16x32_bf16 v[126:129], v[162:165], v[178:181], v[126:129]
	v_mfma_f32_16x16x32_bf16 v[126:129], v[166:169], v[182:185], v[126:129]
	v_mfma_f32_16x16x32_bf16 v[122:125], v[170:173], v[178:181], v[122:125]
	v_mfma_f32_16x16x32_bf16 v[122:125], v[174:177], v[182:185], v[122:125]
	v_mfma_f32_16x16x32_bf16 v[98:101], v[170:173], v[186:189], v[98:101]
	v_mfma_f32_16x16x32_bf16 v[98:101], v[174:177], v[190:193], v[98:101]
	v_mfma_f32_16x16x32_bf16 v[106:109], v[162:165], v[186:189], v[106:109]
	v_mfma_f32_16x16x32_bf16 v[106:109], v[166:169], v[190:193], v[106:109]
	v_mfma_f32_16x16x32_bf16 v[102:105], v[154:157], v[186:189], v[102:105]
	v_mfma_f32_16x16x32_bf16 v[102:105], v[158:161], v[190:193], v[102:105]
	v_mfma_f32_16x16x32_bf16 v[110:113], v[146:149], v[186:189], v[110:113]
	v_mfma_f32_16x16x32_bf16 v[110:113], v[150:153], v[190:193], v[110:113]
	v_mfma_f32_16x16x32_bf16 v[94:97], v[146:149], v[194:197], v[94:97]
	v_mfma_f32_16x16x32_bf16 v[94:97], v[150:153], v[198:201], v[94:97]
	v_mfma_f32_16x16x32_bf16 v[86:89], v[154:157], v[194:197], v[86:89]
	v_mfma_f32_16x16x32_bf16 v[86:89], v[158:161], v[198:201], v[86:89]
	v_mfma_f32_16x16x32_bf16 v[90:93], v[162:165], v[194:197], v[90:93]
	v_mfma_f32_16x16x32_bf16 v[90:93], v[166:169], v[198:201], v[90:93]
	v_mfma_f32_16x16x32_bf16 v[82:85], v[170:173], v[194:197], v[82:85]
	v_mfma_f32_16x16x32_bf16 v[82:85], v[174:177], v[198:201], v[82:85]
	v_mfma_f32_16x16x32_bf16 v[70:73], v[170:173], v[202:205], v[70:73]
	v_mfma_f32_16x16x32_bf16 v[70:73], v[174:177], v[206:209], v[70:73]
	v_mfma_f32_16x16x32_bf16 v[74:77], v[162:165], v[202:205], v[74:77]
	v_mfma_f32_16x16x32_bf16 v[74:77], v[166:169], v[206:209], v[74:77]
	v_mfma_f32_16x16x32_bf16 v[66:69], v[154:157], v[202:205], v[66:69]
	v_mfma_f32_16x16x32_bf16 v[66:69], v[158:161], v[206:209], v[66:69]
	v_mfma_f32_16x16x32_bf16 v[78:81], v[146:149], v[202:205], v[78:81]
	v_mfma_f32_16x16x32_bf16 v[78:81], v[150:153], v[206:209], v[78:81]
	s_setprio 0
	s_barrier
	s_mov_b32 m0, s31
	s_mov_b32 s22, s18
	s_mov_b32 s23, s19
	ds_read_b128 v[178:181], v140 offset:16384
	ds_read_b128 v[182:185], v140 offset:17408
	ds_read_b128 v[186:189], v140 offset:18432
	ds_read_b128 v[190:193], v140 offset:19456
	ds_read_b128 v[194:197], v140 offset:20480
	ds_read_b128 v[198:201], v140 offset:21504
	ds_read_b128 v[202:205], v140 offset:22528
	ds_read_b128 v[206:209], v140 offset:23552
	buffer_load_dwordx4 v137, s[20:23], s80 offen lds
	s_mov_b32 m0, s48
	s_add_i32 s81, s80, 0x80000
	buffer_load_dwordx4 v137, s[20:23], s81 offen lds
	s_mov_b32 m0, s49
	s_add_i32 s81, s80, 0x100000
	buffer_load_dwordx4 v137, s[20:23], s81 offen lds
	s_mov_b32 m0, s50
	s_add_i32 s81, s80, 0x180000
	buffer_load_dwordx4 v137, s[20:23], s81 offen lds
	s_mov_b32 m0, s30
	s_add_i32 s81, s78, 0x80000
	buffer_load_dwordx4 v136, s[16:19], s78 offen lds
	s_mov_b32 m0, s51
	s_nop 0
	buffer_load_dwordx4 v136, s[16:19], s81 offen lds
	s_waitcnt vmcnt(8) lgkmcnt(0)
	s_setprio 1
	s_barrier
	v_mfma_f32_16x16x32_bf16 v[62:65], v[146:149], v[178:181], v[62:65]
	v_mfma_f32_16x16x32_bf16 v[62:65], v[150:153], v[182:185], v[62:65]
	v_mfma_f32_16x16x32_bf16 v[54:57], v[154:157], v[178:181], v[54:57]
	v_mfma_f32_16x16x32_bf16 v[54:57], v[158:161], v[182:185], v[54:57]
	v_mfma_f32_16x16x32_bf16 v[58:61], v[162:165], v[178:181], v[58:61]
	v_mfma_f32_16x16x32_bf16 v[58:61], v[166:169], v[182:185], v[58:61]
	v_mfma_f32_16x16x32_bf16 v[50:53], v[170:173], v[178:181], v[50:53]
	v_mfma_f32_16x16x32_bf16 v[50:53], v[174:177], v[182:185], v[50:53]
	v_mfma_f32_16x16x32_bf16 v[34:37], v[170:173], v[186:189], v[34:37]
	v_mfma_f32_16x16x32_bf16 v[34:37], v[174:177], v[190:193], v[34:37]
	v_mfma_f32_16x16x32_bf16 v[42:45], v[162:165], v[186:189], v[42:45]
	v_mfma_f32_16x16x32_bf16 v[42:45], v[166:169], v[190:193], v[42:45]
	v_mfma_f32_16x16x32_bf16 v[38:41], v[154:157], v[186:189], v[38:41]
	v_mfma_f32_16x16x32_bf16 v[38:41], v[158:161], v[190:193], v[38:41]
	v_mfma_f32_16x16x32_bf16 v[46:49], v[146:149], v[186:189], v[46:49]
	v_mfma_f32_16x16x32_bf16 v[46:49], v[150:153], v[190:193], v[46:49]
	v_mfma_f32_16x16x32_bf16 v[30:33], v[146:149], v[194:197], v[30:33]
	v_mfma_f32_16x16x32_bf16 v[30:33], v[150:153], v[198:201], v[30:33]
	v_mfma_f32_16x16x32_bf16 v[22:25], v[154:157], v[194:197], v[22:25]
	v_mfma_f32_16x16x32_bf16 v[22:25], v[158:161], v[198:201], v[22:25]
	v_mfma_f32_16x16x32_bf16 v[26:29], v[162:165], v[194:197], v[26:29]
	v_mfma_f32_16x16x32_bf16 v[26:29], v[166:169], v[198:201], v[26:29]
	v_mfma_f32_16x16x32_bf16 v[18:21], v[170:173], v[194:197], v[18:21]
	v_mfma_f32_16x16x32_bf16 v[18:21], v[174:177], v[198:201], v[18:21]
	v_mfma_f32_16x16x32_bf16 v[2:5], v[170:173], v[202:205], v[2:5]
	v_mfma_f32_16x16x32_bf16 v[2:5], v[174:177], v[206:209], v[2:5]
	v_mfma_f32_16x16x32_bf16 v[10:13], v[162:165], v[202:205], v[10:13]
	v_mfma_f32_16x16x32_bf16 v[10:13], v[166:169], v[206:209], v[10:13]
	v_mfma_f32_16x16x32_bf16 v[6:9], v[154:157], v[202:205], v[6:9]
	v_mfma_f32_16x16x32_bf16 v[6:9], v[158:161], v[206:209], v[6:9]
	v_mfma_f32_16x16x32_bf16 v[14:17], v[146:149], v[202:205], v[14:17]
	v_mfma_f32_16x16x32_bf16 v[14:17], v[150:153], v[206:209], v[14:17]
	s_setprio 0
	s_barrier
	ds_read_b128 v[146:149], v141
	ds_read_b128 v[150:153], v141 offset:1024
	ds_read_b128 v[154:157], v141 offset:2048
	ds_read_b128 v[158:161], v141 offset:3072
	ds_read_b128 v[162:165], v142
	ds_read_b128 v[166:169], v142 offset:1024
	ds_read_b128 v[170:173], v142 offset:2048
	ds_read_b128 v[174:177], v142 offset:3072
	s_mov_b32 m0, s52
	s_add_i32 s81, s78, 0x100000
	ds_read_b128 v[178:181], v140 offset:32768
	ds_read_b128 v[182:185], v140 offset:33792
	ds_read_b128 v[186:189], v140 offset:34816
	ds_read_b128 v[190:193], v140 offset:35840
	ds_read_b128 v[194:197], v140 offset:36864
	ds_read_b128 v[198:201], v140 offset:37888
	ds_read_b128 v[202:205], v140 offset:38912
	ds_read_b128 v[206:209], v140 offset:39936
	buffer_load_dwordx4 v136, s[16:19], s81 offen lds
	s_mov_b32 m0, s53
	s_add_i32 s81, s78, 0x180000
	buffer_load_dwordx4 v136, s[16:19], s81 offen lds
	s_waitcnt vmcnt(8) lgkmcnt(0)
	s_setprio 1
	s_barrier
	v_mfma_f32_16x16x32_bf16 v[118:121], v[146:149], v[178:181], v[118:121]
	v_mfma_f32_16x16x32_bf16 v[118:121], v[150:153], v[182:185], v[118:121]
	v_mfma_f32_16x16x32_bf16 v[114:117], v[154:157], v[178:181], v[114:117]
	v_mfma_f32_16x16x32_bf16 v[114:117], v[158:161], v[182:185], v[114:117]
	v_mfma_f32_16x16x32_bf16 v[126:129], v[162:165], v[178:181], v[126:129]
	v_mfma_f32_16x16x32_bf16 v[126:129], v[166:169], v[182:185], v[126:129]
	v_mfma_f32_16x16x32_bf16 v[122:125], v[170:173], v[178:181], v[122:125]
	v_mfma_f32_16x16x32_bf16 v[122:125], v[174:177], v[182:185], v[122:125]
	v_mfma_f32_16x16x32_bf16 v[98:101], v[170:173], v[186:189], v[98:101]
	v_mfma_f32_16x16x32_bf16 v[98:101], v[174:177], v[190:193], v[98:101]
	v_mfma_f32_16x16x32_bf16 v[106:109], v[162:165], v[186:189], v[106:109]
	v_mfma_f32_16x16x32_bf16 v[106:109], v[166:169], v[190:193], v[106:109]
	v_mfma_f32_16x16x32_bf16 v[102:105], v[154:157], v[186:189], v[102:105]
	v_mfma_f32_16x16x32_bf16 v[102:105], v[158:161], v[190:193], v[102:105]
	v_mfma_f32_16x16x32_bf16 v[110:113], v[146:149], v[186:189], v[110:113]
	v_mfma_f32_16x16x32_bf16 v[110:113], v[150:153], v[190:193], v[110:113]
	v_mfma_f32_16x16x32_bf16 v[94:97], v[146:149], v[194:197], v[94:97]
	v_mfma_f32_16x16x32_bf16 v[94:97], v[150:153], v[198:201], v[94:97]
	v_mfma_f32_16x16x32_bf16 v[86:89], v[154:157], v[194:197], v[86:89]
	v_mfma_f32_16x16x32_bf16 v[86:89], v[158:161], v[198:201], v[86:89]
	v_mfma_f32_16x16x32_bf16 v[90:93], v[162:165], v[194:197], v[90:93]
	v_mfma_f32_16x16x32_bf16 v[90:93], v[166:169], v[198:201], v[90:93]
	v_mfma_f32_16x16x32_bf16 v[82:85], v[170:173], v[194:197], v[82:85]
	v_mfma_f32_16x16x32_bf16 v[82:85], v[174:177], v[198:201], v[82:85]
	v_mfma_f32_16x16x32_bf16 v[70:73], v[170:173], v[202:205], v[70:73]
	v_mfma_f32_16x16x32_bf16 v[70:73], v[174:177], v[206:209], v[70:73]
	v_mfma_f32_16x16x32_bf16 v[74:77], v[162:165], v[202:205], v[74:77]
	v_mfma_f32_16x16x32_bf16 v[74:77], v[166:169], v[206:209], v[74:77]
	v_mfma_f32_16x16x32_bf16 v[66:69], v[154:157], v[202:205], v[66:69]
	v_mfma_f32_16x16x32_bf16 v[66:69], v[158:161], v[206:209], v[66:69]
	v_mfma_f32_16x16x32_bf16 v[78:81], v[146:149], v[202:205], v[78:81]
	v_mfma_f32_16x16x32_bf16 v[78:81], v[150:153], v[206:209], v[78:81]
	s_setprio 0
	s_barrier
	s_mov_b32 m0, s54
	s_or_b32 s81, s80, 0x80
	ds_read_b128 v[178:181], v140 offset:49152
	ds_read_b128 v[182:185], v140 offset:50176
	ds_read_b128 v[186:189], v140 offset:51200
	ds_read_b128 v[190:193], v140 offset:52224
	ds_read_b128 v[194:197], v140 offset:53248
	ds_read_b128 v[198:201], v140 offset:54272
	ds_read_b128 v[202:205], v140 offset:55296
	ds_read_b128 v[206:209], v140 offset:56320
	buffer_load_dwordx4 v137, s[20:23], s81 offen lds
	s_add_i32 s81, s80, 0x80080
	s_mov_b32 m0, s55
	s_add_i32 s78, s78, 0x80080
	buffer_load_dwordx4 v137, s[20:23], s81 offen lds
	s_add_i32 s81, s80, 0x100080
	s_mov_b32 m0, s58
	s_add_i32 s80, s80, 0x180080
	buffer_load_dwordx4 v137, s[20:23], s81 offen lds
	s_mov_b32 m0, s59
	s_nop 0
	buffer_load_dwordx4 v137, s[20:23], s80 offen lds
	s_mov_b32 m0, s56
	s_nop 0
	buffer_load_dwordx4 v136, s[16:19], s79 offen lds
	s_mov_b32 m0, s57
	s_nop 0
	buffer_load_dwordx4 v136, s[16:19], s78 offen lds
	s_waitcnt vmcnt(8) lgkmcnt(0)
	s_setprio 1
	s_barrier
	v_mfma_f32_16x16x32_bf16 v[62:65], v[146:149], v[178:181], v[62:65]
	v_mfma_f32_16x16x32_bf16 v[62:65], v[150:153], v[182:185], v[62:65]
	v_mfma_f32_16x16x32_bf16 v[54:57], v[154:157], v[178:181], v[54:57]
	v_mfma_f32_16x16x32_bf16 v[54:57], v[158:161], v[182:185], v[54:57]
	v_mfma_f32_16x16x32_bf16 v[58:61], v[162:165], v[178:181], v[58:61]
	v_mfma_f32_16x16x32_bf16 v[58:61], v[166:169], v[182:185], v[58:61]
	v_mfma_f32_16x16x32_bf16 v[50:53], v[170:173], v[178:181], v[50:53]
	v_mfma_f32_16x16x32_bf16 v[50:53], v[174:177], v[182:185], v[50:53]
	v_mfma_f32_16x16x32_bf16 v[34:37], v[170:173], v[186:189], v[34:37]
	v_mfma_f32_16x16x32_bf16 v[34:37], v[174:177], v[190:193], v[34:37]
	v_mfma_f32_16x16x32_bf16 v[42:45], v[162:165], v[186:189], v[42:45]
	v_mfma_f32_16x16x32_bf16 v[42:45], v[166:169], v[190:193], v[42:45]
	v_mfma_f32_16x16x32_bf16 v[38:41], v[154:157], v[186:189], v[38:41]
	v_mfma_f32_16x16x32_bf16 v[38:41], v[158:161], v[190:193], v[38:41]
	v_mfma_f32_16x16x32_bf16 v[46:49], v[146:149], v[186:189], v[46:49]
	v_mfma_f32_16x16x32_bf16 v[46:49], v[150:153], v[190:193], v[46:49]
	v_mfma_f32_16x16x32_bf16 v[30:33], v[146:149], v[194:197], v[30:33]
	v_mfma_f32_16x16x32_bf16 v[30:33], v[150:153], v[198:201], v[30:33]
	v_mfma_f32_16x16x32_bf16 v[22:25], v[154:157], v[194:197], v[22:25]
	v_mfma_f32_16x16x32_bf16 v[22:25], v[158:161], v[198:201], v[22:25]
	v_mfma_f32_16x16x32_bf16 v[26:29], v[162:165], v[194:197], v[26:29]
	v_mfma_f32_16x16x32_bf16 v[26:29], v[166:169], v[198:201], v[26:29]
	v_mfma_f32_16x16x32_bf16 v[18:21], v[170:173], v[194:197], v[18:21]
	v_mfma_f32_16x16x32_bf16 v[18:21], v[174:177], v[198:201], v[18:21]
	v_mfma_f32_16x16x32_bf16 v[2:5], v[170:173], v[202:205], v[2:5]
	v_mfma_f32_16x16x32_bf16 v[2:5], v[174:177], v[206:209], v[2:5]
	v_mfma_f32_16x16x32_bf16 v[10:13], v[162:165], v[202:205], v[10:13]
	v_mfma_f32_16x16x32_bf16 v[10:13], v[166:169], v[206:209], v[10:13]
	v_mfma_f32_16x16x32_bf16 v[6:9], v[154:157], v[202:205], v[6:9]
	v_mfma_f32_16x16x32_bf16 v[6:9], v[158:161], v[206:209], v[6:9]
	v_mfma_f32_16x16x32_bf16 v[14:17], v[146:149], v[202:205], v[14:17]
	v_mfma_f32_16x16x32_bf16 v[14:17], v[150:153], v[206:209], v[14:17]
	s_setprio 0
	s_barrier
	s_add_i32 s77, s77, 2
	s_addk_i32 s75, 0x100
	s_addk_i32 s76, 0x100
	s_cmp_ge_i32 s77, s13
	s_cbranch_scc0 .LBB0_1402
	s_and_b64 vcc, exec, s[46:47]
	s_cbranch_vccz .LBB0_1405

.LBB0_1519:
	ds_read_b128 v[134:137], v208
	ds_read_b128 v[138:141], v208 offset:1024
	ds_read_b128 v[142:145], v208 offset:2048
	ds_read_b128 v[146:149], v208 offset:3072
	ds_read_b128 v[150:153], v209
	ds_read_b128 v[154:157], v209 offset:1024
	ds_read_b128 v[158:161], v209 offset:2048
	ds_read_b128 v[162:165], v209 offset:3072
	s_add_i32 s18, s80, 0xffbf8080
	s_cmp_eq_u32 s65, s82
	s_cselect_b32 s83, s6, s18
	s_cselect_b32 s85, s7, s81
	s_or_b32 s84, s83, 0x80
	s_add_i32 s18, s80, 0xffea8000
	s_mov_b32 m0, s66
	ds_read_b128 v[166:169], v210
	ds_read_b128 v[170:173], v210 offset:1024
	ds_read_b128 v[174:177], v210 offset:2048
	ds_read_b128 v[178:181], v210 offset:3072
	ds_read_b128 v[182:185], v210 offset:4096
	ds_read_b128 v[186:189], v210 offset:5120
	ds_read_b128 v[190:193], v210 offset:6144
	ds_read_b128 v[194:197], v210 offset:7168
	buffer_load_dwordx4 v206, s[12:15], s18 offen lds
	s_mov_b32 m0, s69
	s_nop 0
	buffer_load_dwordx4 v206, s[12:15], s80 offen lds
	s_waitcnt vmcnt(8) lgkmcnt(0)
	s_setprio 1
	s_barrier
	v_mfma_f32_16x16x32_bf16 v[126:129], v[134:137], v[166:169], v[126:129]
	v_mfma_f32_16x16x32_bf16 v[126:129], v[138:141], v[170:173], v[126:129]
	v_mfma_f32_16x16x32_bf16 v[122:125], v[142:145], v[166:169], v[122:125]
	v_mfma_f32_16x16x32_bf16 v[122:125], v[146:149], v[170:173], v[122:125]
	v_mfma_f32_16x16x32_bf16 v[110:113], v[150:153], v[166:169], v[110:113]
	v_mfma_f32_16x16x32_bf16 v[110:113], v[154:157], v[170:173], v[110:113]
	v_mfma_f32_16x16x32_bf16 v[102:105], v[158:161], v[166:169], v[102:105]
	v_mfma_f32_16x16x32_bf16 v[102:105], v[162:165], v[170:173], v[102:105]
	v_mfma_f32_16x16x32_bf16 v[86:89], v[158:161], v[174:177], v[86:89]
	v_mfma_f32_16x16x32_bf16 v[86:89], v[162:165], v[178:181], v[86:89]
	v_mfma_f32_16x16x32_bf16 v[94:97], v[150:153], v[174:177], v[94:97]
	v_mfma_f32_16x16x32_bf16 v[94:97], v[154:157], v[178:181], v[94:97]
	v_mfma_f32_16x16x32_bf16 v[114:117], v[142:145], v[174:177], v[114:117]
	v_mfma_f32_16x16x32_bf16 v[114:117], v[146:149], v[178:181], v[114:117]
	v_mfma_f32_16x16x32_bf16 v[118:121], v[134:137], v[174:177], v[118:121]
	v_mfma_f32_16x16x32_bf16 v[118:121], v[138:141], v[178:181], v[118:121]
	v_mfma_f32_16x16x32_bf16 v[106:109], v[134:137], v[182:185], v[106:109]
	v_mfma_f32_16x16x32_bf16 v[106:109], v[138:141], v[186:189], v[106:109]
	v_mfma_f32_16x16x32_bf16 v[98:101], v[142:145], v[182:185], v[98:101]
	v_mfma_f32_16x16x32_bf16 v[98:101], v[146:149], v[186:189], v[98:101]
	v_mfma_f32_16x16x32_bf16 v[78:81], v[150:153], v[182:185], v[78:81]
	v_mfma_f32_16x16x32_bf16 v[78:81], v[154:157], v[186:189], v[78:81]
	v_mfma_f32_16x16x32_bf16 v[74:77], v[158:161], v[182:185], v[74:77]
	v_mfma_f32_16x16x32_bf16 v[74:77], v[162:165], v[186:189], v[74:77]
	v_mfma_f32_16x16x32_bf16 v[66:69], v[158:161], v[190:193], v[66:69]
	v_mfma_f32_16x16x32_bf16 v[66:69], v[162:165], v[194:197], v[66:69]
	v_mfma_f32_16x16x32_bf16 v[70:73], v[150:153], v[190:193], v[70:73]
	v_mfma_f32_16x16x32_bf16 v[70:73], v[154:157], v[194:197], v[70:73]
	v_mfma_f32_16x16x32_bf16 v[82:85], v[142:145], v[190:193], v[82:85]
	v_mfma_f32_16x16x32_bf16 v[82:85], v[146:149], v[194:197], v[82:85]
	v_mfma_f32_16x16x32_bf16 v[90:93], v[134:137], v[190:193], v[90:93]
	v_mfma_f32_16x16x32_bf16 v[90:93], v[138:141], v[194:197], v[90:93]
	s_setprio 0
	s_barrier
	s_mov_b32 m0, s27
	s_mov_b32 s18, s14
	s_mov_b32 s19, s15
	ds_read_b128 v[166:169], v210 offset:16384
	ds_read_b128 v[170:173], v210 offset:17408
	ds_read_b128 v[174:177], v210 offset:18432
	ds_read_b128 v[178:181], v210 offset:19456
	ds_read_b128 v[182:185], v210 offset:20480
	ds_read_b128 v[186:189], v210 offset:21504
	ds_read_b128 v[190:193], v210 offset:22528
	ds_read_b128 v[194:197], v210 offset:23552
	buffer_load_dwordx4 v207, s[16:19], s85 offen lds
	s_mov_b32 m0, s30
	s_add_i32 s86, s85, 0x158000
	buffer_load_dwordx4 v207, s[16:19], s86 offen lds
	s_mov_b32 m0, s31
	s_add_i32 s86, s85, 0x2b0000
	buffer_load_dwordx4 v207, s[16:19], s86 offen lds
	s_mov_b32 m0, s50
	s_add_i32 s86, s85, 0x408000
	buffer_load_dwordx4 v207, s[16:19], s86 offen lds
	s_mov_b32 m0, s25
	s_add_i32 s86, s83, 0x158000
	buffer_load_dwordx4 v206, s[12:15], s83 offen lds
	s_mov_b32 m0, s51
	s_nop 0
	buffer_load_dwordx4 v206, s[12:15], s86 offen lds
	s_waitcnt vmcnt(8) lgkmcnt(0)
	s_setprio 1
	s_barrier
	v_mfma_f32_16x16x32_bf16 v[62:65], v[134:137], v[166:169], v[62:65]
	v_mfma_f32_16x16x32_bf16 v[62:65], v[138:141], v[170:173], v[62:65]
	v_mfma_f32_16x16x32_bf16 v[58:61], v[142:145], v[166:169], v[58:61]
	v_mfma_f32_16x16x32_bf16 v[58:61], v[146:149], v[170:173], v[58:61]
	v_mfma_f32_16x16x32_bf16 v[46:49], v[150:153], v[166:169], v[46:49]
	v_mfma_f32_16x16x32_bf16 v[46:49], v[154:157], v[170:173], v[46:49]
	v_mfma_f32_16x16x32_bf16 v[38:41], v[158:161], v[166:169], v[38:41]
	v_mfma_f32_16x16x32_bf16 v[38:41], v[162:165], v[170:173], v[38:41]
	v_mfma_f32_16x16x32_bf16 v[22:25], v[158:161], v[174:177], v[22:25]
	v_mfma_f32_16x16x32_bf16 v[22:25], v[162:165], v[178:181], v[22:25]
	v_mfma_f32_16x16x32_bf16 v[30:33], v[150:153], v[174:177], v[30:33]
	v_mfma_f32_16x16x32_bf16 v[30:33], v[154:157], v[178:181], v[30:33]
	v_mfma_f32_16x16x32_bf16 v[50:53], v[142:145], v[174:177], v[50:53]
	v_mfma_f32_16x16x32_bf16 v[50:53], v[146:149], v[178:181], v[50:53]
	v_mfma_f32_16x16x32_bf16 v[54:57], v[134:137], v[174:177], v[54:57]
	v_mfma_f32_16x16x32_bf16 v[54:57], v[138:141], v[178:181], v[54:57]
	v_mfma_f32_16x16x32_bf16 v[42:45], v[134:137], v[182:185], v[42:45]
	v_mfma_f32_16x16x32_bf16 v[42:45], v[138:141], v[186:189], v[42:45]
	v_mfma_f32_16x16x32_bf16 v[34:37], v[142:145], v[182:185], v[34:37]
	v_mfma_f32_16x16x32_bf16 v[34:37], v[146:149], v[186:189], v[34:37]
	v_mfma_f32_16x16x32_bf16 v[14:17], v[150:153], v[182:185], v[14:17]
	v_mfma_f32_16x16x32_bf16 v[14:17], v[154:157], v[186:189], v[14:17]
	v_mfma_f32_16x16x32_bf16 v[10:13], v[158:161], v[182:185], v[10:13]
	v_mfma_f32_16x16x32_bf16 v[10:13], v[162:165], v[186:189], v[10:13]
	v_mfma_f32_16x16x32_bf16 v[2:5], v[158:161], v[190:193], v[2:5]
	v_mfma_f32_16x16x32_bf16 v[2:5], v[162:165], v[194:197], v[2:5]
	v_mfma_f32_16x16x32_bf16 v[6:9], v[150:153], v[190:193], v[6:9]
	v_mfma_f32_16x16x32_bf16 v[6:9], v[154:157], v[194:197], v[6:9]
	v_mfma_f32_16x16x32_bf16 v[18:21], v[142:145], v[190:193], v[18:21]
	v_mfma_f32_16x16x32_bf16 v[18:21], v[146:149], v[194:197], v[18:21]
	v_mfma_f32_16x16x32_bf16 v[26:29], v[134:137], v[190:193], v[26:29]
	v_mfma_f32_16x16x32_bf16 v[26:29], v[138:141], v[194:197], v[26:29]
	s_setprio 0
	s_barrier
	ds_read_b128 v[134:137], v211
	ds_read_b128 v[138:141], v211 offset:1024
	ds_read_b128 v[142:145], v211 offset:2048
	ds_read_b128 v[146:149], v211 offset:3072
	ds_read_b128 v[150:153], v212
	ds_read_b128 v[154:157], v212 offset:1024
	ds_read_b128 v[158:161], v212 offset:2048
	ds_read_b128 v[162:165], v212 offset:3072
	s_mov_b32 m0, s52
	s_add_i32 s86, s83, 0x2b0000
	ds_read_b128 v[166:169], v210 offset:32768
	ds_read_b128 v[170:173], v210 offset:33792
	ds_read_b128 v[174:177], v210 offset:34816
	ds_read_b128 v[178:181], v210 offset:35840
	ds_read_b128 v[182:185], v210 offset:36864
	ds_read_b128 v[186:189], v210 offset:37888
	ds_read_b128 v[190:193], v210 offset:38912
	ds_read_b128 v[194:197], v210 offset:39936
	buffer_load_dwordx4 v206, s[12:15], s86 offen lds
	s_mov_b32 m0, s53
	s_add_i32 s86, s83, 0x408000
	buffer_load_dwordx4 v206, s[12:15], s86 offen lds
	s_waitcnt vmcnt(8) lgkmcnt(0)
	s_setprio 1
	s_barrier
	v_mfma_f32_16x16x32_bf16 v[126:129], v[134:137], v[166:169], v[126:129]
	v_mfma_f32_16x16x32_bf16 v[126:129], v[138:141], v[170:173], v[126:129]
	v_mfma_f32_16x16x32_bf16 v[122:125], v[142:145], v[166:169], v[122:125]
	v_mfma_f32_16x16x32_bf16 v[122:125], v[146:149], v[170:173], v[122:125]
	v_mfma_f32_16x16x32_bf16 v[110:113], v[150:153], v[166:169], v[110:113]
	v_mfma_f32_16x16x32_bf16 v[110:113], v[154:157], v[170:173], v[110:113]
	v_mfma_f32_16x16x32_bf16 v[102:105], v[158:161], v[166:169], v[102:105]
	v_mfma_f32_16x16x32_bf16 v[102:105], v[162:165], v[170:173], v[102:105]
	v_mfma_f32_16x16x32_bf16 v[86:89], v[158:161], v[174:177], v[86:89]
	v_mfma_f32_16x16x32_bf16 v[86:89], v[162:165], v[178:181], v[86:89]
	v_mfma_f32_16x16x32_bf16 v[94:97], v[150:153], v[174:177], v[94:97]
	v_mfma_f32_16x16x32_bf16 v[94:97], v[154:157], v[178:181], v[94:97]
	v_mfma_f32_16x16x32_bf16 v[114:117], v[142:145], v[174:177], v[114:117]
	v_mfma_f32_16x16x32_bf16 v[114:117], v[146:149], v[178:181], v[114:117]
	v_mfma_f32_16x16x32_bf16 v[118:121], v[134:137], v[174:177], v[118:121]
	v_mfma_f32_16x16x32_bf16 v[118:121], v[138:141], v[178:181], v[118:121]
	v_mfma_f32_16x16x32_bf16 v[106:109], v[134:137], v[182:185], v[106:109]
	v_mfma_f32_16x16x32_bf16 v[106:109], v[138:141], v[186:189], v[106:109]
	v_mfma_f32_16x16x32_bf16 v[98:101], v[142:145], v[182:185], v[98:101]
	v_mfma_f32_16x16x32_bf16 v[98:101], v[146:149], v[186:189], v[98:101]
	v_mfma_f32_16x16x32_bf16 v[78:81], v[150:153], v[182:185], v[78:81]
	v_mfma_f32_16x16x32_bf16 v[78:81], v[154:157], v[186:189], v[78:81]
	v_mfma_f32_16x16x32_bf16 v[74:77], v[158:161], v[182:185], v[74:77]
	v_mfma_f32_16x16x32_bf16 v[74:77], v[162:165], v[186:189], v[74:77]
	v_mfma_f32_16x16x32_bf16 v[66:69], v[158:161], v[190:193], v[66:69]
	v_mfma_f32_16x16x32_bf16 v[66:69], v[162:165], v[194:197], v[66:69]
	v_mfma_f32_16x16x32_bf16 v[70:73], v[150:153], v[190:193], v[70:73]
	v_mfma_f32_16x16x32_bf16 v[70:73], v[154:157], v[194:197], v[70:73]
	v_mfma_f32_16x16x32_bf16 v[82:85], v[142:145], v[190:193], v[82:85]
	v_mfma_f32_16x16x32_bf16 v[82:85], v[146:149], v[194:197], v[82:85]
	v_mfma_f32_16x16x32_bf16 v[90:93], v[134:137], v[190:193], v[90:93]
	v_mfma_f32_16x16x32_bf16 v[90:93], v[138:141], v[194:197], v[90:93]
	s_setprio 0
	s_barrier
	s_mov_b32 m0, s57
	s_or_b32 s86, s85, 0x80
	ds_read_b128 v[166:169], v210 offset:49152
	ds_read_b128 v[170:173], v210 offset:50176
	ds_read_b128 v[174:177], v210 offset:51200
	ds_read_b128 v[178:181], v210 offset:52224
	ds_read_b128 v[182:185], v210 offset:53248
	ds_read_b128 v[186:189], v210 offset:54272
	ds_read_b128 v[190:193], v210 offset:55296
	ds_read_b128 v[194:197], v210 offset:56320
	buffer_load_dwordx4 v207, s[16:19], s86 offen lds
	s_add_i32 s86, s85, 0x158080
	s_mov_b32 m0, s58
	s_add_i32 s83, s83, 0x158080
	buffer_load_dwordx4 v207, s[16:19], s86 offen lds
	s_add_i32 s86, s85, 0x2b0080
	s_mov_b32 m0, s61
	s_add_i32 s85, s85, 0x408080
	buffer_load_dwordx4 v207, s[16:19], s86 offen lds
	s_mov_b32 m0, s62
	s_nop 0
	buffer_load_dwordx4 v207, s[16:19], s85 offen lds
	s_mov_b32 m0, s59
	s_nop 0
	buffer_load_dwordx4 v206, s[12:15], s84 offen lds
	s_mov_b32 m0, s60
	s_nop 0
	buffer_load_dwordx4 v206, s[12:15], s83 offen lds
	s_waitcnt vmcnt(8) lgkmcnt(0)
	s_setprio 1
	s_barrier
	v_mfma_f32_16x16x32_bf16 v[62:65], v[134:137], v[166:169], v[62:65]
	v_mfma_f32_16x16x32_bf16 v[62:65], v[138:141], v[170:173], v[62:65]
	v_mfma_f32_16x16x32_bf16 v[58:61], v[142:145], v[166:169], v[58:61]
	v_mfma_f32_16x16x32_bf16 v[58:61], v[146:149], v[170:173], v[58:61]
	v_mfma_f32_16x16x32_bf16 v[46:49], v[150:153], v[166:169], v[46:49]
	v_mfma_f32_16x16x32_bf16 v[46:49], v[154:157], v[170:173], v[46:49]
	v_mfma_f32_16x16x32_bf16 v[38:41], v[158:161], v[166:169], v[38:41]
	v_mfma_f32_16x16x32_bf16 v[38:41], v[162:165], v[170:173], v[38:41]
	v_mfma_f32_16x16x32_bf16 v[22:25], v[158:161], v[174:177], v[22:25]
	v_mfma_f32_16x16x32_bf16 v[22:25], v[162:165], v[178:181], v[22:25]
	v_mfma_f32_16x16x32_bf16 v[30:33], v[150:153], v[174:177], v[30:33]
	v_mfma_f32_16x16x32_bf16 v[30:33], v[154:157], v[178:181], v[30:33]
	v_mfma_f32_16x16x32_bf16 v[50:53], v[142:145], v[174:177], v[50:53]
	v_mfma_f32_16x16x32_bf16 v[50:53], v[146:149], v[178:181], v[50:53]
	v_mfma_f32_16x16x32_bf16 v[54:57], v[134:137], v[174:177], v[54:57]
	v_mfma_f32_16x16x32_bf16 v[54:57], v[138:141], v[178:181], v[54:57]
	v_mfma_f32_16x16x32_bf16 v[42:45], v[134:137], v[182:185], v[42:45]
	v_mfma_f32_16x16x32_bf16 v[42:45], v[138:141], v[186:189], v[42:45]
	v_mfma_f32_16x16x32_bf16 v[34:37], v[142:145], v[182:185], v[34:37]
	v_mfma_f32_16x16x32_bf16 v[34:37], v[146:149], v[186:189], v[34:37]
	v_mfma_f32_16x16x32_bf16 v[14:17], v[150:153], v[182:185], v[14:17]
	v_mfma_f32_16x16x32_bf16 v[14:17], v[154:157], v[186:189], v[14:17]
	v_mfma_f32_16x16x32_bf16 v[10:13], v[158:161], v[182:185], v[10:13]
	v_mfma_f32_16x16x32_bf16 v[10:13], v[162:165], v[186:189], v[10:13]
	v_mfma_f32_16x16x32_bf16 v[2:5], v[158:161], v[190:193], v[2:5]
	v_mfma_f32_16x16x32_bf16 v[2:5], v[162:165], v[194:197], v[2:5]
	v_mfma_f32_16x16x32_bf16 v[6:9], v[150:153], v[190:193], v[6:9]
	v_mfma_f32_16x16x32_bf16 v[6:9], v[154:157], v[194:197], v[6:9]
	v_mfma_f32_16x16x32_bf16 v[18:21], v[142:145], v[190:193], v[18:21]
	v_mfma_f32_16x16x32_bf16 v[18:21], v[146:149], v[194:197], v[18:21]
	v_mfma_f32_16x16x32_bf16 v[26:29], v[134:137], v[190:193], v[26:29]
	v_mfma_f32_16x16x32_bf16 v[26:29], v[138:141], v[194:197], v[26:29]
	s_setprio 0
	s_barrier
	s_add_i32 s82, s82, 2
	s_addk_i32 s80, 0x100
	s_addk_i32 s81, 0x100
	s_cmp_ge_i32 s82, s3
	s_cbranch_scc0 .LBB0_1519
	v_pk_mul_f32 v[182:183], v[128:129], 0.5 op_sel_hi:[1,0]
	v_pk_mul_f32 v[184:185], v[126:127], 0.5 op_sel_hi:[1,0]
	v_pk_mul_f32 v[186:187], v[124:125], 0.5 op_sel_hi:[1,0]
	v_pk_mul_f32 v[188:189], v[122:123], 0.5 op_sel_hi:[1,0]
	v_pk_mul_f32 v[196:197], v[112:113], 0.5 op_sel_hi:[1,0]
	v_pk_mul_f32 v[194:195], v[110:111], 0.5 op_sel_hi:[1,0]
	v_pk_mul_f32 v[192:193], v[104:105], 0.5 op_sel_hi:[1,0]
	v_pk_mul_f32 v[190:191], v[102:103], 0.5 op_sel_hi:[1,0]
	v_pk_mul_f32 v[180:181], v[120:121], 0.5 op_sel_hi:[1,0]
	v_pk_mul_f32 v[178:179], v[118:119], 0.5 op_sel_hi:[1,0]
	v_pk_mul_f32 v[176:177], v[116:117], 0.5 op_sel_hi:[1,0]
	v_pk_mul_f32 v[174:175], v[114:115], 0.5 op_sel_hi:[1,0]
	v_pk_mul_f32 v[170:171], v[96:97], 0.5 op_sel_hi:[1,0]
	v_pk_mul_f32 v[168:169], v[94:95], 0.5 op_sel_hi:[1,0]
	v_pk_mul_f32 v[166:167], v[88:89], 0.5 op_sel_hi:[1,0]
	v_pk_mul_f32 v[164:165], v[86:87], 0.5 op_sel_hi:[1,0]
	v_pk_mul_f32 v[162:163], v[108:109], 0.5 op_sel_hi:[1,0]
	v_pk_mul_f32 v[160:161], v[106:107], 0.5 op_sel_hi:[1,0]
	v_pk_mul_f32 v[158:159], v[100:101], 0.5 op_sel_hi:[1,0]
	v_pk_mul_f32 v[156:157], v[98:99], 0.5 op_sel_hi:[1,0]
	v_pk_mul_f32 v[154:155], v[80:81], 0.5 op_sel_hi:[1,0]
	v_pk_mul_f32 v[152:153], v[78:79], 0.5 op_sel_hi:[1,0]
	v_pk_mul_f32 v[150:151], v[76:77], 0.5 op_sel_hi:[1,0]
	v_pk_mul_f32 v[148:149], v[74:75], 0.5 op_sel_hi:[1,0]
	v_pk_mul_f32 v[144:145], v[92:93], 0.5 op_sel_hi:[1,0]
	v_pk_mul_f32 v[142:143], v[90:91], 0.5 op_sel_hi:[1,0]
	v_pk_mul_f32 v[140:141], v[84:85], 0.5 op_sel_hi:[1,0]
	v_pk_mul_f32 v[138:139], v[82:83], 0.5 op_sel_hi:[1,0]
	v_pk_mul_f32 v[136:137], v[72:73], 0.5 op_sel_hi:[1,0]
	v_pk_mul_f32 v[134:135], v[70:71], 0.5 op_sel_hi:[1,0]
	v_pk_mul_f32 v[128:129], v[68:69], 0.5 op_sel_hi:[1,0]
	v_pk_mul_f32 v[126:127], v[66:67], 0.5 op_sel_hi:[1,0]
	v_pk_mul_f32 v[122:123], v[64:65], 0.5 op_sel_hi:[1,0]
	v_pk_mul_f32 v[120:121], v[62:63], 0.5 op_sel_hi:[1,0]
	v_pk_mul_f32 v[118:119], v[60:61], 0.5 op_sel_hi:[1,0]
	v_pk_mul_f32 v[116:117], v[58:59], 0.5 op_sel_hi:[1,0]
	v_pk_mul_f32 v[112:113], v[48:49], 0.5 op_sel_hi:[1,0]
	v_pk_mul_f32 v[110:111], v[46:47], 0.5 op_sel_hi:[1,0]
	v_pk_mul_f32 v[108:109], v[40:41], 0.5 op_sel_hi:[1,0]
	v_pk_mul_f32 v[106:107], v[38:39], 0.5 op_sel_hi:[1,0]
	v_pk_mul_f32 v[104:105], v[56:57], 0.5 op_sel_hi:[1,0]
	v_pk_mul_f32 v[102:103], v[54:55], 0.5 op_sel_hi:[1,0]
	v_pk_mul_f32 v[100:101], v[52:53], 0.5 op_sel_hi:[1,0]
	v_pk_mul_f32 v[98:99], v[50:51], 0.5 op_sel_hi:[1,0]
	v_pk_mul_f32 v[96:97], v[32:33], 0.5 op_sel_hi:[1,0]
	v_pk_mul_f32 v[94:95], v[30:31], 0.5 op_sel_hi:[1,0]
	v_pk_mul_f32 v[92:93], v[24:25], 0.5 op_sel_hi:[1,0]
	v_pk_mul_f32 v[90:91], v[22:23], 0.5 op_sel_hi:[1,0]
	v_pk_mul_f32 v[88:89], v[44:45], 0.5 op_sel_hi:[1,0]
	v_pk_mul_f32 v[86:87], v[42:43], 0.5 op_sel_hi:[1,0]
	v_pk_mul_f32 v[84:85], v[36:37], 0.5 op_sel_hi:[1,0]
	v_pk_mul_f32 v[82:83], v[34:35], 0.5 op_sel_hi:[1,0]
	v_pk_mul_f32 v[80:81], v[16:17], 0.5 op_sel_hi:[1,0]
	v_pk_mul_f32 v[78:79], v[14:15], 0.5 op_sel_hi:[1,0]
	v_pk_mul_f32 v[76:77], v[12:13], 0.5 op_sel_hi:[1,0]
	v_pk_mul_f32 v[74:75], v[10:11], 0.5 op_sel_hi:[1,0]
	v_pk_mul_f32 v[72:73], v[28:29], 0.5 op_sel_hi:[1,0]
	v_pk_mul_f32 v[70:71], v[26:27], 0.5 op_sel_hi:[1,0]
	v_pk_mul_f32 v[68:69], v[20:21], 0.5 op_sel_hi:[1,0]
	v_pk_mul_f32 v[66:67], v[18:19], 0.5 op_sel_hi:[1,0]
	v_pk_mul_f32 v[64:65], v[8:9], 0.5 op_sel_hi:[1,0]
	v_pk_mul_f32 v[62:63], v[6:7], 0.5 op_sel_hi:[1,0]
	v_pk_mul_f32 v[60:61], v[4:5], 0.5 op_sel_hi:[1,0]
	v_pk_mul_f32 v[58:59], v[2:3], 0.5 op_sel_hi:[1,0]
	s_and_b64 vcc, exec, s[40:41]
	s_cbranch_vccz .LBB0_1522
